# SSD table loads hoisted; NA P@V operand via ds_read_b64_tr_b16 (V tile rows 136 B)
# speedup vs baseline: 1.0253x; 1.0104x over previous
.LBB0_550:
	s_ashr_i32 s0, s24, 7
	v_mov_b32_e32 v6, v190
	s_ashr_i32 s1, s0, 31
	s_and_b32 s20, s2, 0x1fc0
	v_lshlrev_b32_e32 v0, 3, v6
	s_lshl_b64 s[58:59], s[0:1], 13
	v_and_b32_e32 v98, 56, v0
	v_ashrrev_i32_e32 v80, 3, v6
	s_or_b32 s58, s58, s20
	v_lshlrev_b32_e32 v168, 1, v98
	v_ashrrev_i32_e32 v81, 31, v80
	v_lshl_add_u64 v[0:1], v[194:195], 0, v[168:169]
	v_lshl_add_u64 v[2:3], s[58:59], 0, v[80:81]
	s_movk_i32 s20, 0x600
	v_mad_u64_u32 v[4:5], s[0:1], v2, s20, v[0:1]
	v_add_u32_e32 v2, 64, v6
	v_ashrrev_i32_e32 v82, 3, v2
	v_ashrrev_i32_e32 v83, 31, v82
	v_mad_i32_i24 v5, v3, s20, v5
	v_lshl_add_u64 v[2:3], s[58:59], 0, v[82:83]
	global_load_dwordx4 v[32:35], v[4:5], off
	v_mad_u64_u32 v[4:5], s[0:1], v2, s20, v[0:1]
	v_add_u32_e32 v2, 0x80, v6
	v_ashrrev_i32_e32 v84, 3, v2
	v_ashrrev_i32_e32 v85, 31, v84
	v_mad_i32_i24 v5, v3, s20, v5
	v_lshl_add_u64 v[2:3], s[58:59], 0, v[84:85]
	global_load_dwordx4 v[40:43], v[4:5], off
	v_mad_u64_u32 v[4:5], s[0:1], v2, s20, v[0:1]
	v_add_u32_e32 v2, 0xc0, v6
	v_ashrrev_i32_e32 v86, 3, v2
	v_ashrrev_i32_e32 v87, 31, v86
	v_mad_i32_i24 v5, v3, s20, v5
	v_lshl_add_u64 v[2:3], s[58:59], 0, v[86:87]
	global_load_dwordx4 v[48:51], v[4:5], off
	v_mad_u64_u32 v[4:5], s[0:1], v2, s20, v[0:1]
	v_add_u32_e32 v2, 0x100, v6
	v_ashrrev_i32_e32 v88, 3, v2
	v_ashrrev_i32_e32 v89, 31, v88
	v_mad_i32_i24 v5, v3, s20, v5
	v_lshl_add_u64 v[2:3], s[58:59], 0, v[88:89]
	global_load_dwordx4 v[52:55], v[4:5], off
	v_mad_u64_u32 v[4:5], s[0:1], v2, s20, v[0:1]
	v_add_u32_e32 v2, 0x140, v6
	v_ashrrev_i32_e32 v90, 3, v2
	v_ashrrev_i32_e32 v91, 31, v90
	v_mad_i32_i24 v5, v3, s20, v5
	v_lshl_add_u64 v[2:3], s[58:59], 0, v[90:91]
	global_load_dwordx4 v[64:67], v[4:5], off
	v_mad_u64_u32 v[4:5], s[0:1], v2, s20, v[0:1]
	v_add_u32_e32 v2, 0x180, v6
	v_ashrrev_i32_e32 v92, 3, v2
	v_ashrrev_i32_e32 v93, 31, v92
	v_mad_i32_i24 v5, v3, s20, v5
	v_lshl_add_u64 v[2:3], s[58:59], 0, v[92:93]
	global_load_dwordx4 v[68:71], v[4:5], off
	v_mad_u64_u32 v[4:5], s[0:1], v2, s20, v[0:1]
	v_add_u32_e32 v2, 0x1c0, v6
	v_ashrrev_i32_e32 v94, 3, v2
	v_ashrrev_i32_e32 v95, 31, v94
	v_mad_i32_i24 v5, v3, s20, v5
	v_lshl_add_u64 v[2:3], s[58:59], 0, v[94:95]
	v_mad_u64_u32 v[0:1], s[0:1], v2, s20, v[0:1]
	v_mad_i32_i24 v1, v3, s20, v1
	global_load_dwordx4 v[72:75], v[4:5], off
	global_load_dwordx4 v[76:79], v[0:1], off
	v_ashrrev_i32_e32 v0, 1, v6
	v_and_b32_e32 v0, -8, v0
	v_and_b32_e32 v81, 15, v6
	v_ashrrev_i32_e32 v1, 31, v0
	v_or_b32_e32 v83, s58, v81
	v_lshlrev_b64 v[20:21], 1, v[0:1]
	v_lshlrev_b32_e32 v168, 7, v81
	v_mad_u64_u32 v[2:3], s[0:1], v83, s20, v[202:203]
	v_lshl_add_u64 v[8:9], v[168:169], 0, v[20:21]
	v_lshl_add_u64 v[22:23], v[206:207], 0, v[8:9]
	s_movk_i32 s0, 0x2000
	v_add_co_u32_e32 v12, vcc, s0, v22
	s_movk_i32 s0, 0x3000
	s_nop 0
	v_addc_co_u32_e32 v13, vcc, 0, v23, vcc
	v_or_b32_e32 v8, 16, v83
	v_add_co_u32_e32 v96, vcc, s0, v22
	v_mad_u64_u32 v[8:9], s[0:1], v8, s20, v[202:203]
	v_mad_i32_i24 v3, s59, v229, v3
	v_mad_i32_i24 v9, s59, v229, v9
	v_lshl_add_u64 v[0:1], v[2:3], 0, v[20:21]
	v_addc_co_u32_e32 v97, vcc, 0, v23, vcc
	v_lshl_add_u64 v[14:15], v[8:9], 0, v[20:21]
	global_load_dwordx4 v[4:7], v[0:1], off offset:1280
	s_nop 0
	global_load_dwordx4 v[0:3], v[0:1], off offset:1344
	s_nop 0
	global_load_dwordx4 v[24:27], v[22:23], off
	global_load_dwordx4 v[28:31], v[22:23], off offset:64
	global_load_dwordx4 v[36:39], v[96:97], off offset:-4096
	global_load_dwordx4 v[44:47], v[12:13], off offset:64
	global_load_dwordx4 v[8:11], v[14:15], off offset:1280
	global_load_dwordx4 v[16:19], v[14:15], off offset:1344
	global_load_dwordx4 v[56:59], v[22:23], off offset:2048
	global_load_dwordx4 v[60:63], v[22:23], off offset:2112
	global_load_dwordx4 v[100:103], v[12:13], off offset:2048
	global_load_dwordx4 v[104:107], v[12:13], off offset:2112
	v_or_b32_e32 v12, 32, v83
	v_mad_u64_u32 v[12:13], s[0:1], v12, s20, v[202:203]
	s_movk_i32 s0, 0x1000
	s_nop 0
	v_add_co_u32_e32 v136, vcc, s0, v22
	v_or_b32_e32 v22, 48, v83
	s_nop 0
	v_addc_co_u32_e32 v137, vcc, 0, v23, vcc
	v_mad_u64_u32 v[22:23], s[0:1], v22, s20, v[202:203]
	v_mad_i32_i24 v13, s59, v229, v13
	v_mad_i32_i24 v23, s59, v229, v23
	v_lshl_add_u64 v[108:109], v[12:13], 0, v[20:21]
	v_lshl_add_u64 v[124:125], v[22:23], 0, v[20:21]
	global_load_dwordx4 v[12:15], v[108:109], off offset:1280
	global_load_dwordx4 v[128:131], v[108:109], off offset:1344
	s_nop 0
	global_load_dwordx4 v[108:111], v[136:137], off
	global_load_dwordx4 v[112:115], v[136:137], off offset:64
	global_load_dwordx4 v[116:119], v[96:97], off
	global_load_dwordx4 v[120:123], v[96:97], off offset:64
	global_load_dwordx4 v[20:23], v[124:125], off offset:1280
	global_load_dwordx4 v[132:135], v[124:125], off offset:1344
	s_nop 0
	global_load_dwordx4 v[124:127], v[136:137], off offset:2048
	s_nop 0
	global_load_dwordx4 v[136:139], v[136:137], off offset:2112
	s_nop 0
	global_load_dwordx4 v[140:143], v[96:97], off offset:2048
	global_load_dwordx4 v[144:147], v[96:97], off offset:2112
	v_or_b32_e32 v83, s58, v190
	v_mov_b64_e32 v[96:97], s[52:53]
	s_movk_i32 s0, 0x1220
	v_mad_u64_u32 v[96:97], s[0:1], v83, s0, v[96:97]
	v_mov_b32_e32 v83, 0x1220
	v_mad_i32_i24 v97, s59, v83, v97
	v_lshl_add_u64 v[96:97], v[186:187], 1, v[96:97]
	v_add_co_u32_e32 v148, vcc, 0x1000, v96
	s_mov_b64 s[0:1], 0
	s_nop 0
	v_addc_co_u32_e32 v149, vcc, 0, v97, vcc
	global_load_ushort v83, v[148:149], off
	global_load_ushort v211, v[148:149], off offset:16
	global_load_dword v209, v[196:197], off
	global_load_dword v212, v[196:197], off offset:32
	global_load_dword v210, v[198:199], off
	global_load_dword v213, v[198:199], off offset:32
	s_waitcnt vmcnt(0)
	v_lshlrev_b32_e32 v83, 16, v83
	v_lshl_add_u64 v[148:149], v[196:197], 0, s[0:1]
	v_mov_b32_e32 v85, v209
	s_mov_b32 s0, 0x41a00000
	s_waitcnt vmcnt(0)
	v_add_f32_e32 v93, v85, v83
	v_cmp_nlt_f32_e32 vcc, s0, v93
	s_and_saveexec_b64 s[0:1], vcc
	s_cbranch_execz .LBB0_552
	v_mul_f32_e32 v83, 0x3fb8aa3b, v93
	v_rndne_f32_e32 v85, v83
	s_mov_b32 s20, 0x3fb8aa3b
	v_sub_f32_e32 v87, v83, v85
	v_fma_f32 v83, v93, s20, -v83
	v_fmac_f32_e32 v83, 0x32a5705f, v93
	v_add_f32_e32 v83, v87, v83
	v_cvt_i32_f32_e32 v85, v85
	v_exp_f32_e32 v83, v83
	v_cmp_ngt_f32_e32 vcc, s37, v93
	s_mov_b32 s20, 0x3f2aaaab
	v_ldexp_f32 v83, v83, v85
	v_cndmask_b32_e32 v83, 0, v83, vcc
	v_cmp_nlt_f32_e32 vcc, s30, v93
	s_nop 1
	v_cndmask_b32_e32 v83, v231, v83, vcc
	v_add_f32_e32 v85, 1.0, v83
	v_add_f32_e32 v87, -1.0, v85
	v_sub_f32_e32 v89, v87, v85
	v_add_f32_e32 v89, 1.0, v89
	v_sub_f32_e32 v87, v83, v87
	v_add_f32_e32 v87, v87, v89
	v_frexp_mant_f32_e32 v89, v85
	v_cvt_f64_f32_e32 v[148:149], v85
	v_frexp_exp_i32_f64_e32 v91, v[148:149]
	v_cmp_gt_f32_e32 vcc, s20, v89
	s_mov_b32 s20, 0x3f317218
	s_nop 0
	v_subbrev_co_u32_e32 v89, vcc, 0, v91, vcc
	v_sub_u32_e32 v91, 0, v89
	v_ldexp_f32 v85, v85, v91
	v_ldexp_f32 v87, v87, v91
	v_add_f32_e32 v91, -1.0, v85
	v_add_f32_e32 v95, 1.0, v85
	v_add_f32_e32 v93, 1.0, v91
	v_add_f32_e32 v99, -1.0, v95
	v_sub_f32_e32 v93, v85, v93
	v_sub_f32_e32 v85, v85, v99
	v_add_f32_e32 v85, v87, v85
	v_add_f32_e32 v93, v87, v93
	v_add_f32_e32 v87, v95, v85
	v_sub_f32_e32 v95, v95, v87
	v_add_f32_e32 v85, v85, v95
	v_rcp_f32_e32 v95, v87
	v_add_f32_e32 v149, v91, v93
	v_sub_f32_e32 v91, v91, v149
	v_add_f32_e32 v91, v93, v91
	v_mul_f32_e32 v93, v149, v95
	v_mul_f32_e32 v150, v87, v93
	v_fma_f32 v152, v93, v87, -v150
	v_fmac_f32_e32 v152, v93, v85
	v_add_f32_e32 v148, v150, v152
	v_sub_f32_e32 v151, v149, v148
	v_pk_add_f32 v[154:155], v[148:149], v[150:151] neg_lo:[0,1] neg_hi:[0,1]
	v_mov_b32_e32 v153, v148
	v_pk_add_f32 v[148:149], v[154:155], v[152:153] neg_lo:[0,1] neg_hi:[0,1]
	s_nop 0
	v_add_f32_e32 v91, v91, v149
	v_add_f32_e32 v91, v148, v91
	v_add_f32_e32 v149, v151, v91
	v_mul_f32_e32 v99, v95, v149
	v_mul_f32_e32 v150, v87, v99
	v_fma_f32 v152, v99, v87, -v150
	v_fmac_f32_e32 v152, v99, v85
	v_add_f32_e32 v148, v150, v152
	v_sub_f32_e32 v85, v151, v149
	v_sub_f32_e32 v151, v149, v148
	v_pk_add_f32 v[154:155], v[148:149], v[150:151] neg_lo:[0,1] neg_hi:[0,1]
	v_mov_b32_e32 v153, v148
	v_add_f32_e32 v85, v91, v85
	v_pk_add_f32 v[148:149], v[154:155], v[152:153] neg_lo:[0,1] neg_hi:[0,1]
	v_add_f32_e32 v87, v93, v99
	v_add_f32_e32 v85, v85, v149
	v_add_f32_e32 v85, v148, v85
	v_add_f32_e32 v85, v151, v85
	v_sub_f32_e32 v91, v87, v93
	v_mul_f32_e32 v85, v95, v85
	v_sub_f32_e32 v91, v99, v91
	v_add_f32_e32 v85, v91, v85
	v_add_f32_e32 v91, v87, v85
	v_cvt_f32_i32_e32 v148, v89
	v_mul_f32_e32 v93, v91, v91
	v_mov_b32_e32 v95, 0x3ecc95a3
	v_fmamk_f32 v95, v93, 0x3e9b6dac, v95
	v_fmaak_f32 v179, v93, v95, 0x3f2aaada
	v_mul_f32_e32 v149, v91, v93
	v_pk_mul_f32 v[152:153], v[148:149], v[178:179]
	v_ldexp_f32 v151, v91, 1
	v_fma_f32 v150, v148, s20, -v152
	v_fmac_f32_e32 v150, 0xb102e308, v148
	v_sub_f32_e32 v87, v91, v87
	v_pk_add_f32 v[148:149], v[152:153], v[150:151]
	v_sub_f32_e32 v85, v85, v87
	v_sub_f32_e32 v87, v149, v151
	v_ldexp_f32 v85, v85, 1
	v_sub_f32_e32 v87, v153, v87
	v_add_f32_e32 v155, v85, v87
	v_mov_b32_e32 v154, v152
	v_pk_add_f32 v[152:153], v[148:149], v[152:153] neg_lo:[0,1] neg_hi:[0,1]
	v_pk_add_f32 v[156:157], v[148:149], v[154:155]
	v_mov_b32_e32 v151, v148
	v_mov_b32_e32 v153, v157
	v_pk_add_f32 v[158:159], v[150:151], v[152:153] neg_lo:[0,1] neg_hi:[0,1]
	v_pk_add_f32 v[150:151], v[150:151], v[152:153]
	v_mov_b32_e32 v154, v155
	v_pk_add_f32 v[152:153], v[150:151], v[148:149] op_sel:[1,0] op_sel_hi:[0,1] neg_lo:[0,1] neg_hi:[0,1]
	v_pk_add_f32 v[160:161], v[156:157], v[152:153] op_sel_hi:[1,0] neg_lo:[0,1] neg_hi:[0,1]
	v_mov_b32_e32 v156, v157
	v_mov_b32_e32 v157, v151
	v_pk_mov_b32 v[152:153], v[148:149], v[152:153] op_sel:[1,0]
	v_mov_b32_e32 v155, v148
	v_pk_add_f32 v[152:153], v[156:157], v[152:153] neg_lo:[0,1] neg_hi:[0,1]
	v_mov_b32_e32 v160, v158
	v_pk_add_f32 v[148:149], v[154:155], v[152:153] neg_lo:[0,1] neg_hi:[0,1]
	v_mov_b32_e32 v159, v151
	v_pk_add_f32 v[152:153], v[160:161], v[148:149]
	s_mov_b32 s20, 0x7f800000
	v_pk_add_f32 v[154:155], v[152:153], v[152:153] op_sel:[0,1] op_sel_hi:[1,0]
	v_cmp_neq_f32_e32 vcc, s20, v83
	v_pk_add_f32 v[150:151], v[150:151], v[154:155] op_sel:[1,0] op_sel_hi:[0,1]
	v_mov_b32_e32 v153, v150
	v_pk_add_f32 v[156:157], v[152:153], v[158:159] neg_lo:[0,1] neg_hi:[0,1]
	v_mov_b32_e32 v149, v154
	v_sub_f32_e32 v85, v152, v156
	v_pk_add_f32 v[148:149], v[148:149], v[156:157] neg_lo:[0,1] neg_hi:[0,1]
	v_sub_f32_e32 v85, v158, v85
	v_add_f32_e32 v85, v148, v85
	v_add_f32_e32 v85, v85, v149
	v_add_f32_e32 v85, v150, v85
	s_mov_b32 s20, 0x33800000
	v_cndmask_b32_e32 v85, v231, v85, vcc
	v_cmp_lt_f32_e64 vcc, |v83|, s20
	s_nop 1
	v_cndmask_b32_e32 v93, v85, v83, vcc
.LBB0_552:
	s_or_b64 exec, exec, s[0:1]
	s_mov_b64 s[0:1], 0
	s_mov_b32 s22, 0x3fb8aa3b
	v_lshl_add_u64 v[148:149], v[198:199], 0, s[0:1]
	v_mov_b32_e32 v83, v210
	v_and_b32_e32 v168, 64, v224
	s_mov_b64 s[0:1], 0
	s_waitcnt vmcnt(0)
	v_mul_f32_e32 v85, 0x3fb8aa3b, v83
	v_fma_f32 v87, v83, s22, -v85
	v_rndne_f32_e32 v89, v85
	v_fmac_f32_e32 v87, 0x32a5705f, v83
	v_sub_f32_e32 v85, v85, v89
	v_add_f32_e32 v85, v85, v87
	v_exp_f32_e32 v85, v85
	v_cvt_i32_f32_e32 v87, v89
	v_cmp_ngt_f32_e32 vcc, s37, v83
	v_ldexp_f32 v85, v85, v87
	s_nop 0
	v_cndmask_b32_e32 v85, 0, v85, vcc
	v_cmp_nlt_f32_e32 vcc, s30, v83
	v_add_u32_e32 v83, -1, v224
	s_nop 0
	v_cndmask_b32_e32 v85, v231, v85, vcc
	v_cmp_lt_i32_e32 vcc, v83, v168
	v_mul_f32_e64 v87, v93, -v85
	s_nop 0
	v_cndmask_b32_e32 v83, v83, v224, vcc
	v_lshlrev_b32_e32 v83, 2, v83
	ds_bpermute_b32 v89, v83, v87
	s_waitcnt lgkmcnt(0)
	v_fma_f32 v85, v93, -v85, v89
	v_cndmask_b32_e64 v87, v85, v87, s[38:39]
	v_add_u32_e32 v85, -2, v224
	v_cmp_lt_i32_e32 vcc, v85, v168
	s_nop 1
	v_cndmask_b32_e32 v85, v85, v224, vcc
	v_lshlrev_b32_e32 v85, 2, v85
	ds_bpermute_b32 v89, v85, v87
	s_waitcnt lgkmcnt(0)
	v_add_f32_e32 v89, v87, v89
	v_cndmask_b32_e64 v89, v89, v87, s[40:41]
	v_add_u32_e32 v87, -4, v224
	v_cmp_lt_i32_e32 vcc, v87, v168
	s_nop 1
	v_cndmask_b32_e32 v87, v87, v224, vcc
	v_lshlrev_b32_e32 v87, 2, v87
	ds_bpermute_b32 v91, v87, v89
	s_waitcnt lgkmcnt(0)
	v_add_f32_e32 v91, v89, v91
	v_cndmask_b32_e64 v91, v91, v89, s[42:43]
	v_add_u32_e32 v89, -8, v224
	v_cmp_lt_i32_e32 vcc, v89, v168
	s_nop 1
	v_cndmask_b32_e32 v89, v89, v224, vcc
	v_lshlrev_b32_e32 v89, 2, v89
	ds_bpermute_b32 v95, v89, v91
	s_waitcnt lgkmcnt(0)
	v_add_f32_e32 v95, v91, v95
	v_cndmask_b32_e64 v95, v95, v91, s[44:45]
	v_add_u32_e32 v91, -16, v224
	v_cmp_lt_i32_e32 vcc, v91, v168
	s_nop 1
	v_cndmask_b32_e32 v91, v91, v224, vcc
	v_lshlrev_b32_e32 v91, 2, v91
	ds_bpermute_b32 v99, v91, v95
	s_waitcnt lgkmcnt(0)
	v_add_f32_e32 v99, v95, v99
	v_cndmask_b32_e64 v99, v99, v95, s[46:47]
	v_subrev_u32_e32 v95, 32, v224
	v_cmp_lt_i32_e32 vcc, v95, v168
	s_nop 1
	v_cndmask_b32_e32 v95, v95, v224, vcc
	v_lshlrev_b32_e32 v95, 2, v95
	ds_bpermute_b32 v148, v95, v99
	v_add_co_u32_e32 v96, vcc, 0x1000, v96
	s_waitcnt lgkmcnt(0)
	v_add_f32_e32 v148, v99, v148
	v_cndmask_b32_e64 v99, v148, v99, s[48:49]
	v_addc_co_u32_e32 v97, vcc, 0, v97, vcc
	ds_write2st64_b32 v241, v93, v99 offset0:69 offset1:70
	v_mov_b32_e32 v93, v211
	s_waitcnt vmcnt(0)
	v_lshlrev_b32_e32 v93, 16, v93
	v_lshl_add_u64 v[96:97], v[196:197], 0, s[0:1]
	v_mov_b32_e32 v96, v212
	s_mov_b32 s0, 0x41a00000
	s_waitcnt vmcnt(0)
	v_add_f32_e32 v93, v96, v93
	v_cmp_nlt_f32_e32 vcc, s0, v93
	s_and_saveexec_b64 s[0:1], vcc
	s_cbranch_execz .LBB0_554
	v_mul_f32_e32 v96, 0x3fb8aa3b, v93
	v_rndne_f32_e32 v97, v96
	v_sub_f32_e32 v99, v96, v97
	v_fma_f32 v96, v93, s22, -v96
	v_fmac_f32_e32 v96, 0x32a5705f, v93
	v_add_f32_e32 v96, v99, v96
	v_cvt_i32_f32_e32 v97, v97
	v_exp_f32_e32 v96, v96
	v_cmp_ngt_f32_e32 vcc, s37, v93
	s_mov_b32 s20, 0x3f2aaaab
	v_ldexp_f32 v96, v96, v97
	v_cndmask_b32_e32 v96, 0, v96, vcc
	v_cmp_nlt_f32_e32 vcc, s30, v93
	s_nop 1
	v_cndmask_b32_e32 v93, v231, v96, vcc
	v_add_f32_e32 v99, 1.0, v93
	v_add_f32_e32 v96, -1.0, v99
	v_sub_f32_e32 v97, v96, v99
	v_add_f32_e32 v97, 1.0, v97
	v_sub_f32_e32 v96, v93, v96
	v_add_f32_e32 v148, v96, v97
	v_frexp_mant_f32_e32 v149, v99
	v_cvt_f64_f32_e32 v[96:97], v99
	v_frexp_exp_i32_f64_e32 v96, v[96:97]
	v_cmp_gt_f32_e32 vcc, s20, v149
	s_mov_b32 s20, 0x3f317218
	s_nop 0
	v_subbrev_co_u32_e32 v154, vcc, 0, v96, vcc
	v_sub_u32_e32 v96, 0, v154
	v_ldexp_f32 v97, v99, v96
	v_add_f32_e32 v99, -1.0, v97
	v_add_f32_e32 v149, 1.0, v97
	v_ldexp_f32 v96, v148, v96
	v_add_f32_e32 v148, 1.0, v99
	v_add_f32_e32 v150, -1.0, v149
	v_sub_f32_e32 v148, v97, v148
	v_sub_f32_e32 v97, v97, v150
	v_add_f32_e32 v148, v96, v148
	v_add_f32_e32 v96, v96, v97
	v_add_f32_e32 v155, v149, v96
	v_rcp_f32_e32 v157, v155
	v_sub_f32_e32 v97, v149, v155
	v_add_f32_e32 v156, v96, v97
	v_add_f32_e32 v97, v99, v148
	v_sub_f32_e32 v96, v99, v97
	v_mul_f32_e32 v158, v97, v157
	v_add_f32_e32 v99, v148, v96
	v_mul_f32_e32 v148, v155, v158
	v_fma_f32 v150, v158, v155, -v148
	v_fmac_f32_e32 v150, v158, v156
	v_add_f32_e32 v96, v148, v150
	v_sub_f32_e32 v149, v97, v96
	v_pk_add_f32 v[152:153], v[96:97], v[148:149] neg_lo:[0,1] neg_hi:[0,1]
	v_mov_b32_e32 v151, v96
	v_pk_add_f32 v[96:97], v[152:153], v[150:151] neg_lo:[0,1] neg_hi:[0,1]
	s_nop 0
	v_add_f32_e32 v97, v99, v97
	v_add_f32_e32 v96, v96, v97
	v_add_f32_e32 v97, v149, v96
	v_mul_f32_e32 v99, v157, v97
	v_mul_f32_e32 v148, v155, v99
	v_fma_f32 v150, v99, v155, -v148
	v_fmac_f32_e32 v150, v99, v156
	v_sub_f32_e32 v149, v149, v97
	v_add_f32_e32 v155, v96, v149
	v_add_f32_e32 v96, v148, v150
	v_sub_f32_e32 v149, v97, v96
	v_pk_add_f32 v[152:153], v[96:97], v[148:149] neg_lo:[0,1] neg_hi:[0,1]
	v_mov_b32_e32 v151, v96
	v_pk_add_f32 v[96:97], v[152:153], v[150:151] neg_lo:[0,1] neg_hi:[0,1]
	s_nop 0
	v_add_f32_e32 v97, v155, v97
	v_add_f32_e32 v96, v96, v97
	v_add_f32_e32 v97, v158, v99
	v_add_f32_e32 v96, v149, v96
	v_sub_f32_e32 v148, v97, v158
	v_mul_f32_e32 v96, v157, v96
	v_sub_f32_e32 v99, v99, v148
	v_add_f32_e32 v99, v99, v96
	v_add_f32_e32 v148, v97, v99
	v_mul_f32_e32 v150, v148, v148
	v_mov_b32_e32 v96, 0x3ecc95a3
	v_fmamk_f32 v96, v150, 0x3e9b6dac, v96
	v_fmaak_f32 v179, v150, v96, 0x3f2aaada
	v_cvt_f32_i32_e32 v96, v154
	v_sub_f32_e32 v97, v148, v97
	v_sub_f32_e32 v97, v99, v97
	v_ldexp_f32 v99, v97, 1
	v_mul_f32_e32 v97, v148, v150
	v_pk_mul_f32 v[150:151], v[96:97], v[178:179]
	v_ldexp_f32 v149, v148, 1
	v_fma_f32 v148, v96, s20, -v150
	v_fmac_f32_e32 v148, 0xb102e308, v96
	v_pk_add_f32 v[96:97], v[150:151], v[148:149]
	v_mov_b32_e32 v152, v150
	v_sub_f32_e32 v149, v97, v149
	v_sub_f32_e32 v149, v151, v149
	v_add_f32_e32 v153, v99, v149
	v_pk_add_f32 v[150:151], v[96:97], v[150:151] neg_lo:[0,1] neg_hi:[0,1]
	v_pk_add_f32 v[154:155], v[96:97], v[152:153]
	v_mov_b32_e32 v149, v96
	v_mov_b32_e32 v151, v155
	v_pk_add_f32 v[156:157], v[148:149], v[150:151] neg_lo:[0,1] neg_hi:[0,1]
	v_pk_add_f32 v[148:149], v[148:149], v[150:151]
	v_mov_b32_e32 v152, v153
	v_pk_add_f32 v[150:151], v[148:149], v[96:97] op_sel:[1,0] op_sel_hi:[0,1] neg_lo:[0,1] neg_hi:[0,1]
	v_pk_add_f32 v[158:159], v[154:155], v[150:151] op_sel_hi:[1,0] neg_lo:[0,1] neg_hi:[0,1]
	v_mov_b32_e32 v154, v155
	v_mov_b32_e32 v155, v149
	v_pk_mov_b32 v[150:151], v[96:97], v[150:151] op_sel:[1,0]
	v_mov_b32_e32 v153, v96
	v_pk_add_f32 v[150:151], v[154:155], v[150:151] neg_lo:[0,1] neg_hi:[0,1]
	v_mov_b32_e32 v158, v156
	v_pk_add_f32 v[96:97], v[152:153], v[150:151] neg_lo:[0,1] neg_hi:[0,1]
	v_mov_b32_e32 v157, v149
	v_pk_add_f32 v[150:151], v[158:159], v[96:97]
	s_mov_b32 s20, 0x7f800000
	v_pk_add_f32 v[152:153], v[150:151], v[150:151] op_sel:[0,1] op_sel_hi:[1,0]
	v_cmp_neq_f32_e32 vcc, s20, v93
	v_pk_add_f32 v[148:149], v[148:149], v[152:153] op_sel:[1,0] op_sel_hi:[0,1]
	v_mov_b32_e32 v151, v148
	v_pk_add_f32 v[154:155], v[150:151], v[156:157] neg_lo:[0,1] neg_hi:[0,1]
	v_mov_b32_e32 v97, v152
	v_sub_f32_e32 v99, v150, v154
	v_pk_add_f32 v[96:97], v[96:97], v[154:155] neg_lo:[0,1] neg_hi:[0,1]
	v_sub_f32_e32 v99, v156, v99
	v_add_f32_e32 v96, v96, v99
	v_add_f32_e32 v96, v96, v97
	v_add_f32_e32 v96, v148, v96
	s_mov_b32 s20, 0x33800000
	v_cndmask_b32_e32 v96, v231, v96, vcc
	v_cmp_lt_f32_e64 vcc, |v93|, s20
	s_nop 1
	v_cndmask_b32_e32 v93, v96, v93, vcc
.LBB0_554:
	s_or_b64 exec, exec, s[0:1]
	s_mov_b64 s[0:1], 0
	s_movk_i32 s20, 0x84
	v_lshl_add_u64 v[96:97], v[198:199], 0, s[0:1]
	v_mov_b32_e32 v96, v213
	v_mov_b32_e32 v170, v230
	v_mov_b32_e32 v232, 0x1b00
	s_movk_i32 s23, 0x420
	s_mov_b32 s25, 0x5040100
	s_waitcnt vmcnt(0)
	v_mul_f32_e32 v97, 0x3fb8aa3b, v96
	v_fma_f32 v99, v96, s22, -v97
	v_rndne_f32_e32 v148, v97
	v_fmac_f32_e32 v99, 0x32a5705f, v96
	v_sub_f32_e32 v97, v97, v148
	v_add_f32_e32 v97, v97, v99
	v_exp_f32_e32 v97, v97
	v_cvt_i32_f32_e32 v99, v148
	v_cmp_ngt_f32_e32 vcc, s37, v96
	s_movk_i32 s22, 0x600
	v_ldexp_f32 v97, v97, v99
	v_cndmask_b32_e32 v97, 0, v97, vcc
	v_cmp_nlt_f32_e32 vcc, s30, v96
	s_nop 1
	v_cndmask_b32_e32 v96, v231, v97, vcc
	v_mul_f32_e64 v97, v93, -v96
	ds_bpermute_b32 v83, v83, v97
	s_waitcnt lgkmcnt(0)
	v_fma_f32 v83, v93, -v96, v83
	v_cndmask_b32_e64 v83, v83, v97, s[38:39]
	ds_bpermute_b32 v85, v85, v83
	s_waitcnt lgkmcnt(0)
	v_add_f32_e32 v85, v83, v85
	v_cndmask_b32_e64 v83, v85, v83, s[40:41]
	ds_bpermute_b32 v85, v87, v83
	s_waitcnt lgkmcnt(0)
	v_add_f32_e32 v85, v83, v85
	v_cndmask_b32_e64 v83, v85, v83, s[42:43]
	ds_bpermute_b32 v85, v89, v83
	s_waitcnt lgkmcnt(0)
	v_add_f32_e32 v85, v83, v85
	v_cndmask_b32_e64 v83, v85, v83, s[44:45]
	ds_bpermute_b32 v85, v91, v83
	s_waitcnt lgkmcnt(0)
	v_add_f32_e32 v85, v83, v85
	v_cndmask_b32_e64 v83, v85, v83, s[46:47]
	ds_bpermute_b32 v85, v95, v83
	s_waitcnt lgkmcnt(0)
	v_add_f32_e32 v85, v83, v85
	v_cndmask_b32_e64 v83, v85, v83, s[48:49]
	ds_bpermute_b32 v85, v230, v83
	v_mov_b32_e32 v230, 0x1200
	s_waitcnt lgkmcnt(0)
	v_sub_f32_e32 v83, v85, v83
	v_fma_f32 v83, v93, -v96, v83
	v_lshl_add_u32 v96, v98, 1, v191
	v_mad_u64_u32 v[98:99], s[0:1], v80, s20, v[96:97]
	ds_write2st64_b32 v241, v93, v83 offset0:71 offset1:72
	ds_write2_b32 v98, v32, v33 offset1:1
	ds_write2_b32 v98, v34, v35 offset0:2 offset1:3
	v_mad_u64_u32 v[32:33], s[0:1], v82, s20, v[96:97]
	ds_write2_b32 v32, v40, v41 offset1:1
	ds_write2_b32 v32, v42, v43 offset0:2 offset1:3
	v_mad_u64_u32 v[32:33], s[0:1], v84, s20, v[96:97]
	ds_write2_b32 v32, v48, v49 offset1:1
	ds_write2_b32 v32, v50, v51 offset0:2 offset1:3
	v_mad_u64_u32 v[32:33], s[0:1], v86, s20, v[96:97]
	ds_write2_b32 v32, v52, v53 offset1:1
	ds_write2_b32 v32, v54, v55 offset0:2 offset1:3
	v_mad_u64_u32 v[32:33], s[0:1], v88, s20, v[96:97]
	ds_write2_b32 v32, v64, v65 offset1:1
	ds_write2_b32 v32, v66, v67 offset0:2 offset1:3
	v_mad_u64_u32 v[32:33], s[0:1], v90, s20, v[96:97]
	ds_write2_b32 v32, v68, v69 offset1:1
	ds_write2_b32 v32, v70, v71 offset0:2 offset1:3
	v_mad_u64_u32 v[32:33], s[0:1], v92, s20, v[96:97]
	ds_write2_b32 v32, v72, v73 offset1:1
	ds_write2_b32 v32, v74, v75 offset0:2 offset1:3
	v_mad_u64_u32 v[32:33], s[0:1], v94, s20, v[96:97]
	ds_write2_b32 v32, v76, v77 offset1:1
	ds_write2_b32 v32, v78, v79 offset0:2 offset1:3
	v_lshl_add_u32 v32, v81, 2, v191
	s_waitcnt lgkmcnt(0)
	v_add_u32_e32 v80, 0x4400, v32
	v_add_u32_e32 v81, 0x4800, v32
	ds_read2_b32 v[64:65], v80 offset0:128 offset1:144
	ds_read2_b32 v[66:67], v81 offset1:16
	v_mfma_f32_16x16x32_bf16 v[40:43], v[36:39], v[4:7], 0
	ds_read2_b32 v[148:149], v80 offset0:160 offset1:176
	ds_read2_b32 v[150:151], v81 offset0:32 offset1:48
	s_waitcnt lgkmcnt(3)
	v_mul_f32_e32 v33, 0x3fb8aa3b, v64
	s_waitcnt lgkmcnt(2)
	v_mul_f32_e32 v32, 0x3fb8aa3b, v66
	v_exp_f32_e32 v52, v33
	v_exp_f32_e32 v54, v32
	v_mfma_f32_16x16x32_bf16 v[32:35], v[24:27], v[4:7], 0
	v_mul_f32_e32 v64, 0x3fb8aa3b, v65
	v_exp_f32_e32 v86, v64
	v_mul_f32_e32 v64, 0x3fb8aa3b, v67
	v_mfma_f32_16x16x32_bf16 v[40:43], v[44:47], v[0:3], v[40:43]
	v_exp_f32_e32 v88, v64
	s_waitcnt lgkmcnt(1)
	v_mul_f32_e32 v80, 0x3fb8aa3b, v148
	v_exp_f32_e32 v148, v80
	v_mfma_f32_16x16x32_bf16 v[32:35], v[28:31], v[0:3], v[32:35]
	s_waitcnt lgkmcnt(0)
	v_mul_f32_e32 v80, 0x3fb8aa3b, v150
	s_nop 0
	v_pk_mul_f32 v[40:41], v[54:55], v[40:41] op_sel_hi:[0,1]
	v_pk_mul_f32 v[42:43], v[54:55], v[42:43] op_sel_hi:[0,1]
	v_mfma_f32_16x16x32_bf16 v[48:51], v[100:103], v[4:7], 0
	v_exp_f32_e32 v150, v80
	s_nop 0
	v_pk_fma_f32 v[34:35], v[34:35], v[52:53], v[42:43] op_sel_hi:[1,0,1]
	v_pk_fma_f32 v[32:33], v[32:33], v[52:53], v[40:41] op_sel_hi:[1,0,1]
	v_mfma_f32_16x16x32_bf16 v[40:43], v[56:59], v[4:7], 0
	v_add_f32_e64 v34, v34, 0
	v_add_f32_e64 v35, v35, 0
	v_pk_add_f32 v[32:33], v[32:33], 0 op_sel_hi:[1,0]
	v_mfma_f32_16x16x32_bf16 v[48:51], v[104:107], v[0:3], v[48:51]
	v_mfma_f32_16x16x32_bf16 v[40:43], v[60:63], v[0:3], v[40:43]
	v_mfma_f32_16x16x32_bf16 v[68:71], v[116:119], v[4:7], 0
	s_nop 5
	v_mul_f32_e64 v48, v54, v48
	v_mul_f32_e64 v49, v54, v49
	v_pk_mul_f32 v[50:51], v[54:55], v[50:51] op_sel_hi:[0,1]
	v_pk_fma_f32 v[42:43], v[52:53], v[42:43], v[50:51] op_sel_hi:[0,1,1]
	v_pk_fma_f32 v[40:41], v[52:53], v[40:41], v[48:49] op_sel_hi:[0,1,1]
	v_mfma_f32_16x16x32_bf16 v[48:51], v[108:111], v[4:7], 0
	v_add_f32_e64 v42, v42, 0
	v_add_f32_e64 v43, v43, 0
	v_pk_add_f32 v[40:41], v[40:41], 0 op_sel_hi:[1,0]
	v_mfma_f32_16x16x32_bf16 v[68:71], v[120:123], v[0:3], v[68:71]
	v_mfma_f32_16x16x32_bf16 v[48:51], v[112:115], v[0:3], v[48:51]
	v_mfma_f32_16x16x32_bf16 v[72:75], v[140:143], v[4:7], 0
	s_nop 5
	v_mul_f32_e64 v68, v54, v68
	v_mul_f32_e64 v69, v54, v69
	v_pk_mul_f32 v[70:71], v[54:55], v[70:71] op_sel_hi:[0,1]
	v_pk_fma_f32 v[50:51], v[52:53], v[50:51], v[70:71] op_sel_hi:[0,1,1]
	v_pk_fma_f32 v[48:49], v[52:53], v[48:49], v[68:69] op_sel_hi:[0,1,1]
	v_mfma_f32_16x16x32_bf16 v[68:71], v[124:127], v[4:7], 0
	v_add_f32_e64 v50, v50, 0
	v_add_f32_e64 v51, v51, 0
	v_pk_add_f32 v[48:49], v[48:49], 0 op_sel_hi:[1,0]
	v_mfma_f32_16x16x32_bf16 v[72:75], v[144:147], v[0:3], v[72:75]
	v_mfma_f32_16x16x32_bf16 v[68:71], v[136:139], v[0:3], v[68:71]
	v_mfma_f32_16x16x32_bf16 v[64:67], v[24:27], v[8:11], 0
	s_nop 5
	v_mul_f32_e64 v72, v54, v72
	v_mul_f32_e64 v73, v54, v73
	v_pk_mul_f32 v[54:55], v[54:55], v[74:75] op_sel_hi:[0,1]
	v_pk_fma_f32 v[54:55], v[52:53], v[70:71], v[54:55] op_sel_hi:[0,1,1]
	v_pk_fma_f32 v[52:53], v[52:53], v[68:69], v[72:73] op_sel_hi:[0,1,1]
	v_mfma_f32_16x16x32_bf16 v[68:71], v[36:39], v[8:11], 0
	v_add_f32_e64 v54, v54, 0
	v_add_f32_e64 v55, v55, 0
	v_pk_add_f32 v[52:53], v[52:53], 0 op_sel_hi:[1,0]
	v_mfma_f32_16x16x32_bf16 v[68:71], v[44:47], v[16:19], v[68:71]
	v_mfma_f32_16x16x32_bf16 v[64:67], v[28:31], v[16:19], v[64:67]
	v_mfma_f32_16x16x32_bf16 v[72:75], v[100:103], v[8:11], 0
	s_nop 5
	v_mul_f32_e64 v68, v88, v68
	v_mul_f32_e64 v69, v88, v69
	v_pk_mul_f32 v[70:71], v[88:89], v[70:71] op_sel_hi:[0,1]
	v_pk_fma_f32 v[66:67], v[66:67], v[86:87], v[70:71] op_sel_hi:[1,0,1]
	v_pk_fma_f32 v[64:65], v[64:65], v[86:87], v[68:69] op_sel_hi:[1,0,1]
	v_mfma_f32_16x16x32_bf16 v[68:71], v[56:59], v[8:11], 0
	v_add_f32_e64 v66, v66, 0
	v_add_f32_e64 v67, v67, 0
	v_pk_add_f32 v[64:65], v[64:65], 0 op_sel_hi:[1,0]
	v_mfma_f32_16x16x32_bf16 v[72:75], v[104:107], v[16:19], v[72:75]
	v_mfma_f32_16x16x32_bf16 v[68:71], v[60:63], v[16:19], v[68:71]
	v_mfma_f32_16x16x32_bf16 v[76:79], v[116:119], v[8:11], 0
	s_nop 5
	v_mul_f32_e64 v72, v88, v72
	v_mul_f32_e64 v73, v88, v73
	v_pk_mul_f32 v[74:75], v[88:89], v[74:75] op_sel_hi:[0,1]
	v_pk_fma_f32 v[70:71], v[86:87], v[70:71], v[74:75] op_sel_hi:[0,1,1]
	v_pk_fma_f32 v[68:69], v[86:87], v[68:69], v[72:73] op_sel_hi:[0,1,1]
	v_mfma_f32_16x16x32_bf16 v[72:75], v[108:111], v[8:11], 0
	v_add_f32_e64 v70, v70, 0
	v_add_f32_e64 v71, v71, 0
	v_pk_add_f32 v[68:69], v[68:69], 0 op_sel_hi:[1,0]
	v_mfma_f32_16x16x32_bf16 v[76:79], v[120:123], v[16:19], v[76:79]
	v_mfma_f32_16x16x32_bf16 v[72:75], v[112:115], v[16:19], v[72:75]
	v_mfma_f32_16x16x32_bf16 v[82:85], v[140:143], v[8:11], 0
	s_nop 5
	v_mul_f32_e64 v76, v88, v76
	v_mul_f32_e64 v77, v88, v77
	v_pk_mul_f32 v[78:79], v[88:89], v[78:79] op_sel_hi:[0,1]
	v_pk_fma_f32 v[74:75], v[86:87], v[74:75], v[78:79] op_sel_hi:[0,1,1]
	v_pk_fma_f32 v[72:73], v[86:87], v[72:73], v[76:77] op_sel_hi:[0,1,1]
	v_mfma_f32_16x16x32_bf16 v[76:79], v[124:127], v[8:11], 0
	v_add_f32_e64 v74, v74, 0
	v_add_f32_e64 v75, v75, 0
	v_pk_add_f32 v[72:73], v[72:73], 0 op_sel_hi:[1,0]
	v_mfma_f32_16x16x32_bf16 v[82:85], v[144:147], v[16:19], v[82:85]
	v_mfma_f32_16x16x32_bf16 v[76:79], v[136:139], v[16:19], v[76:79]
	v_mfma_f32_16x16x32_bf16 v[92:95], v[116:119], v[12:15], 0
	s_nop 5
	v_mul_f32_e64 v82, v88, v82
	v_mul_f32_e64 v83, v88, v83
	v_pk_mul_f32 v[84:85], v[88:89], v[84:85] op_sel_hi:[0,1]
	v_pk_fma_f32 v[78:79], v[86:87], v[78:79], v[84:85] op_sel_hi:[0,1,1]
	v_pk_fma_f32 v[76:77], v[86:87], v[76:77], v[82:83] op_sel_hi:[0,1,1]
	v_mfma_f32_16x16x32_bf16 v[84:87], v[36:39], v[12:15], 0
	v_add_f32_e64 v78, v78, 0
	v_add_f32_e64 v79, v79, 0
	v_pk_add_f32 v[76:77], v[76:77], 0 op_sel_hi:[1,0]
	v_mfma_f32_16x16x32_bf16 v[80:83], v[24:27], v[12:15], 0
	v_mfma_f32_16x16x32_bf16 v[84:87], v[44:47], v[128:131], v[84:87]
	v_mfma_f32_16x16x32_bf16 v[80:83], v[28:31], v[128:131], v[80:83]
	v_mfma_f32_16x16x32_bf16 v[88:91], v[100:103], v[12:15], 0
	s_nop 5
	v_mul_f32_e64 v84, v150, v84
	v_mul_f32_e64 v85, v150, v85
	v_pk_mul_f32 v[86:87], v[150:151], v[86:87] op_sel_hi:[0,1]
	v_pk_fma_f32 v[82:83], v[82:83], v[148:149], v[86:87] op_sel_hi:[1,0,1]
	v_pk_fma_f32 v[80:81], v[80:81], v[148:149], v[84:85] op_sel_hi:[1,0,1]
	v_mfma_f32_16x16x32_bf16 v[84:87], v[56:59], v[12:15], 0
	v_add_f32_e64 v82, v82, 0
	v_add_f32_e64 v83, v83, 0
	v_pk_add_f32 v[80:81], v[80:81], 0 op_sel_hi:[1,0]
	v_mfma_f32_16x16x32_bf16 v[88:91], v[104:107], v[128:131], v[88:91]
	v_mfma_f32_16x16x32_bf16 v[84:87], v[60:63], v[128:131], v[84:87]
	v_mfma_f32_16x16x32_bf16 v[92:95], v[120:123], v[128:131], v[92:95]
	s_nop 5
	v_mul_f32_e64 v88, v150, v88
	v_mul_f32_e64 v89, v150, v89
	v_pk_mul_f32 v[90:91], v[150:151], v[90:91] op_sel_hi:[0,1]
	v_pk_fma_f32 v[86:87], v[148:149], v[86:87], v[90:91] op_sel_hi:[0,1,1]
	v_pk_fma_f32 v[84:85], v[148:149], v[84:85], v[88:89] op_sel_hi:[0,1,1]
	v_mfma_f32_16x16x32_bf16 v[88:91], v[108:111], v[12:15], 0
	v_mul_f32_e64 v92, v150, v92
	v_mul_f32_e64 v93, v150, v93
	v_pk_mul_f32 v[94:95], v[150:151], v[94:95] op_sel_hi:[0,1]
	v_pk_add_f32 v[86:87], v[86:87], 0 op_sel_hi:[1,0]
	v_mfma_f32_16x16x32_bf16 v[88:91], v[112:115], v[128:131], v[88:91]
	v_add_f32_e64 v84, v84, 0
	v_add_f32_e64 v85, v85, 0
	v_mfma_f32_16x16x32_bf16 v[96:99], v[140:143], v[12:15], 0
	v_mfma_f32_16x16x32_bf16 v[24:27], v[24:27], v[20:23], 0
	s_nop 3
	v_fma_f32 v90, v148, v90, v94
	v_fma_f32 v91, v148, v91, v95
	v_pk_fma_f32 v[88:89], v[148:149], v[88:89], v[92:93] op_sel_hi:[0,1,1]
	v_pk_add_f32 v[90:91], v[90:91], 0 op_sel_hi:[1,0]
	v_mfma_f32_16x16x32_bf16 v[92:95], v[124:127], v[12:15], 0
	v_add_f32_e64 v88, v88, 0
	v_add_f32_e64 v89, v89, 0
	v_mfma_f32_16x16x32_bf16 v[96:99], v[144:147], v[128:131], v[96:99]
	v_mfma_f32_16x16x32_bf16 v[92:95], v[136:139], v[128:131], v[92:95]
	v_mfma_f32_16x16x32_bf16 v[24:27], v[28:31], v[132:135], v[24:27]
	s_nop 5
	v_mul_f32_e64 v96, v150, v96
	v_mul_f32_e64 v97, v150, v97
	v_pk_mul_f32 v[98:99], v[150:151], v[98:99] op_sel_hi:[0,1]
	v_pk_fma_f32 v[92:93], v[148:149], v[92:93], v[96:97] op_sel_hi:[0,1,1]
	v_mfma_f32_16x16x32_bf16 v[28:31], v[36:39], v[20:23], 0
	v_mul_f32_e32 v96, 0x3fb8aa3b, v149
	v_pk_fma_f32 v[94:95], v[148:149], v[94:95], v[98:99] op_sel_hi:[0,1,1]
	v_exp_f32_e32 v148, v96
	v_mul_f32_e32 v96, 0x3fb8aa3b, v151
	v_exp_f32_e32 v150, v96
	v_mfma_f32_16x16x32_bf16 v[28:31], v[44:47], v[132:135], v[28:31]
	v_add_f32_e64 v94, v94, 0
	v_add_f32_e64 v95, v95, 0
	v_pk_add_f32 v[92:93], v[92:93], 0 op_sel_hi:[1,0]
	s_nop 4
	v_pk_mul_f32 v[28:29], v[150:151], v[28:29] op_sel_hi:[0,1]
	v_pk_mul_f32 v[30:31], v[150:151], v[30:31] op_sel_hi:[0,1]
	v_pk_fma_f32 v[26:27], v[26:27], v[148:149], v[30:31] op_sel_hi:[1,0,1]
	v_pk_fma_f32 v[24:25], v[24:25], v[148:149], v[28:29] op_sel_hi:[1,0,1]
	v_mfma_f32_16x16x32_bf16 v[28:31], v[100:103], v[20:23], 0
	v_add_f32_e64 v98, v26, 0
	v_add_f32_e64 v99, v27, 0
	v_pk_add_f32 v[96:97], v[24:25], 0 op_sel_hi:[1,0]
	v_mfma_f32_16x16x32_bf16 v[24:27], v[56:59], v[20:23], 0
	v_mfma_f32_16x16x32_bf16 v[28:31], v[104:107], v[132:135], v[28:31]
	v_mfma_f32_16x16x32_bf16 v[24:27], v[60:63], v[132:135], v[24:27]
	s_nop 6
	v_mul_f32_e64 v28, v150, v28
	v_mul_f32_e64 v29, v150, v29
	v_pk_mul_f32 v[30:31], v[150:151], v[30:31] op_sel_hi:[0,1]
	v_pk_fma_f32 v[26:27], v[148:149], v[26:27], v[30:31] op_sel_hi:[0,1,1]
	v_pk_fma_f32 v[24:25], v[148:149], v[24:25], v[28:29] op_sel_hi:[0,1,1]
	v_mfma_f32_16x16x32_bf16 v[28:31], v[116:119], v[20:23], 0
	v_add_f32_e64 v102, v26, 0
	v_add_f32_e64 v103, v27, 0
	v_pk_add_f32 v[100:101], v[24:25], 0 op_sel_hi:[1,0]
	v_mfma_f32_16x16x32_bf16 v[24:27], v[108:111], v[20:23], 0
	v_mfma_f32_16x16x32_bf16 v[28:31], v[120:123], v[132:135], v[28:31]
	v_mfma_f32_16x16x32_bf16 v[24:27], v[112:115], v[132:135], v[24:27]
	s_nop 6
	v_mul_f32_e64 v28, v150, v28
	v_mul_f32_e64 v29, v150, v29
	v_pk_mul_f32 v[30:31], v[150:151], v[30:31] op_sel_hi:[0,1]
	v_pk_fma_f32 v[26:27], v[148:149], v[26:27], v[30:31] op_sel_hi:[0,1,1]
	v_pk_fma_f32 v[24:25], v[148:149], v[24:25], v[28:29] op_sel_hi:[0,1,1]
	v_mfma_f32_16x16x32_bf16 v[28:31], v[140:143], v[20:23], 0
	v_add_f32_e64 v106, v26, 0
	v_add_f32_e64 v107, v27, 0
	v_pk_add_f32 v[104:105], v[24:25], 0 op_sel_hi:[1,0]
	v_mfma_f32_16x16x32_bf16 v[24:27], v[124:127], v[20:23], 0
	v_mfma_f32_16x16x32_bf16 v[28:31], v[144:147], v[132:135], v[28:31]
	v_mfma_f32_16x16x32_bf16 v[24:27], v[136:139], v[132:135], v[24:27]
	s_nop 6
	v_mul_f32_e64 v28, v150, v28
	v_mul_f32_e64 v29, v150, v29
	v_pk_fma_f32 v[24:25], v[148:149], v[24:25], v[28:29] op_sel_hi:[0,1,1]
	v_pk_mul_f32 v[30:31], v[150:151], v[30:31] op_sel_hi:[0,1]
	v_pk_add_f32 v[108:109], v[24:25], 0 op_sel_hi:[1,0]
	v_mov_b32_e32 v24, v190
	v_pk_fma_f32 v[26:27], v[148:149], v[26:27], v[30:31] op_sel_hi:[0,1,1]
	v_pk_add_f32 v[110:111], v[26:27], 0 op_sel_hi:[1,0]
	v_ashrrev_i32_e32 v25, 1, v24
	v_and_or_b32 v28, v24, 15, s58
	v_and_b32_e32 v26, -8, v25
	v_mad_u64_u32 v[24:25], s[0:1], v28, s22, v[202:203]
	v_or_b32_e32 v29, 16, v28
	v_ashrrev_i32_e32 v27, 31, v26
	s_mul_i32 s0, s59, 0x600
	v_mad_u64_u32 v[44:45], s[20:21], v29, s22, v[202:203]
	v_add_u32_e32 v25, s0, v25
	v_lshlrev_b64 v[30:31], 1, v[26:27]
	v_add_u32_e32 v45, s0, v45
	v_lshl_add_u64 v[36:37], v[24:25], 0, v[30:31]
	v_lshl_add_u64 v[56:57], v[44:45], 0, v[30:31]
	v_or_b32_e32 v29, 32, v28
	global_load_dwordx4 v[24:27], v[36:37], off offset:1024
	s_nop 0
	global_load_dwordx4 v[36:39], v[36:37], off offset:1088
	s_nop 0
	global_load_dwordx4 v[44:47], v[56:57], off offset:1024
	global_load_dwordx4 v[112:115], v[56:57], off offset:1088
	v_mad_u64_u32 v[56:57], s[20:21], v29, s22, v[202:203]
	v_or_b32_e32 v28, 48, v28
	v_add_u32_e32 v57, s0, v57
	v_mad_u64_u32 v[28:29], s[20:21], v28, s22, v[202:203]
	v_lshl_add_u64 v[60:61], v[56:57], 0, v[30:31]
	v_add_u32_e32 v29, s0, v29
	global_load_dwordx4 v[56:59], v[60:61], off offset:1024
	global_load_dwordx4 v[136:139], v[60:61], off offset:1088
	v_lshl_add_u64 v[60:61], v[28:29], 0, v[30:31]
	global_load_dwordx4 v[28:31], v[60:61], off offset:1024
	global_load_dwordx4 v[140:143], v[60:61], off offset:1088
	s_waitcnt vmcnt(7)
	v_mfma_f32_16x16x32_bf16 v[60:63], v[24:27], v[4:7], 0
	s_movk_i32 s21, 0x90
	s_movk_i32 s22, 0x1220
	s_mul_i32 s20, s59, 0x1220
	v_mfma_f32_16x16x32_bf16 v[116:119], v[24:27], v[8:11], 0
	v_mfma_f32_16x16x32_bf16 v[120:123], v[24:27], v[12:15], 0
	v_mfma_f32_16x16x32_bf16 v[24:27], v[24:27], v[20:23], 0
	s_waitcnt vmcnt(5)
	v_mfma_f32_16x16x32_bf16 v[144:147], v[44:47], v[4:7], 0
	v_mfma_f32_16x16x32_bf16 v[148:151], v[44:47], v[8:11], 0
	v_mfma_f32_16x16x32_bf16 v[152:155], v[44:47], v[12:15], 0
	v_mfma_f32_16x16x32_bf16 v[44:47], v[44:47], v[20:23], 0
	s_waitcnt vmcnt(3)
	v_mfma_f32_16x16x32_bf16 v[160:163], v[56:59], v[8:11], 0
	v_mfma_f32_16x16x32_bf16 v[164:167], v[56:59], v[12:15], 0
	s_waitcnt vmcnt(1)
	v_mfma_f32_16x16x32_bf16 v[216:219], v[28:31], v[8:11], 0
	v_mfma_f32_16x16x32_bf16 v[220:223], v[28:31], v[12:15], 0
	v_mfma_f32_16x16x32_bf16 v[156:159], v[56:59], v[4:7], 0
	v_mfma_f32_16x16x32_bf16 v[208:211], v[56:59], v[20:23], 0
	v_mfma_f32_16x16x32_bf16 v[212:215], v[28:31], v[4:7], 0
	v_mfma_f32_16x16x32_bf16 v[244:247], v[28:31], v[20:23], 0
	v_mfma_f32_16x16x32_bf16 v[124:127], v[36:39], v[0:3], v[60:63]
	v_mfma_f32_16x16x32_bf16 v[60:63], v[36:39], v[16:19], v[116:119]
	v_mfma_f32_16x16x32_bf16 v[28:31], v[36:39], v[128:131], v[120:123]
	v_mfma_f32_16x16x32_bf16 v[12:15], v[36:39], v[132:135], v[24:27]
	v_mfma_f32_16x16x32_bf16 v[56:59], v[112:115], v[16:19], v[148:151]
	v_mfma_f32_16x16x32_bf16 v[24:27], v[112:115], v[128:131], v[152:155]
	v_mfma_f32_16x16x32_bf16 v[8:11], v[112:115], v[132:135], v[44:47]
	v_mfma_f32_16x16x32_bf16 v[44:47], v[136:139], v[16:19], v[160:163]
	v_mfma_f32_16x16x32_bf16 v[20:23], v[136:139], v[128:131], v[164:167]
	s_waitcnt vmcnt(0)
	v_mfma_f32_16x16x32_bf16 v[36:39], v[140:143], v[16:19], v[216:219]
	v_mfma_f32_16x16x32_bf16 v[16:19], v[140:143], v[128:131], v[220:223]
	v_mov_b32_e32 v129, v190
	s_nop 0
	v_mov_b32_e32 v216, v60
	v_ashrrev_i32_e32 v130, 4, v129
	v_and_b32_e32 v128, 15, v129
	v_and_b32_e32 v129, -16, v129
	v_lshlrev_b32_e32 v131, 3, v130
	v_add_u32_e32 v129, v191, v129
	v_mfma_f32_16x16x32_bf16 v[116:119], v[136:139], v[0:3], v[156:159]
	v_mov_b32_e32 v217, v62
	v_mov_b32_e32 v218, v56
	v_mov_b32_e32 v219, v58
	v_mfma_f32_16x16x32_bf16 v[4:7], v[136:139], v[132:135], v[208:211]
	v_sub_u32_e32 v139, v129, v131
	v_lshl_add_u32 v131, v128, 2, v191
	v_mov_b32_e32 v58, v57
	v_mfma_f32_16x16x32_bf16 v[120:123], v[112:115], v[0:3], v[144:147]
	v_mov_b32_e32 v210, v116
	v_mov_b32_e32 v211, v118
	v_mov_b32_e32 v118, v117
	v_mfma_f32_16x16x32_bf16 v[112:115], v[140:143], v[0:3], v[212:215]
	v_mov_b32_e32 v220, v24
	v_mov_b32_e32 v221, v26
	v_mov_b32_e32 v26, v25
	v_mfma_f32_16x16x32_bf16 v[0:3], v[140:143], v[132:135], v[244:247]
	ds_read_b32 v142, v131 offset:17920
	ds_read_b128 v[134:137], v129 offset:17920
	ds_read_b128 v[144:147], v129 offset:17664
	v_lshlrev_b32_e32 v132, 2, v130
	v_mov_b32_e32 v214, v124
	v_mov_b32_e32 v215, v126
	s_waitcnt lgkmcnt(1)
	v_sub_f32_e32 v133, v142, v134
	v_mul_f32_e32 v133, 0x3fb8aa3b, v133
	v_exp_f32_e32 v148, v133
	v_sub_f32_e32 v133, v142, v135
	v_mul_f32_e32 v133, 0x3fb8aa3b, v133
	v_exp_f32_e32 v133, v133
	v_or_b32_e32 v134, 2, v132
	v_cmp_le_i32_e32 vcc, v132, v128
	v_cmp_le_i32_e64 s[0:1], v134, v128
	v_mul_f32_e32 v133, v125, v133
	s_waitcnt lgkmcnt(0)
	v_mul_f32_e32 v143, v145, v133
	v_sub_f32_e32 v133, v142, v136
	v_mul_f32_e32 v133, 0x3fb8aa3b, v133
	v_exp_f32_e32 v149, v133
	v_sub_f32_e32 v133, v142, v137
	v_mul_f32_e32 v133, 0x3fb8aa3b, v133
	v_exp_f32_e32 v133, v133
	v_pk_mul_f32 v[148:149], v[214:215], v[148:149]
	v_mov_b32_e32 v145, v146
	v_pk_mul_f32 v[144:145], v[144:145], v[148:149]
	v_mul_f32_e32 v133, v127, v133
	v_mov_b32_e32 v209, v114
	v_mov_b32_e32 v114, v113
	v_or_b32_e32 v113, 3, v132
	v_cndmask_b32_e32 v124, 0, v144, vcc
	v_cndmask_b32_e64 v126, 0, v145, s[0:1]
	v_mul_f32_e32 v144, v147, v133
	v_cmp_lt_i32_e64 s[0:1], v132, v128
	v_cmp_ge_i32_e64 s[50:51], v128, v113
	s_nop 0
	v_cndmask_b32_e64 v143, 0, v143, s[0:1]
	v_cndmask_b32_e64 v144, 0, v144, s[50:51]
	v_mad_u32_u24 v141, v128, s21, v139
	v_cvt_pk_bf16_f32 v145, v126, v144
	v_cvt_pk_bf16_f32 v144, v124, v143
	ds_write_b64 v141, v[144:145] offset:8448
	ds_read_b128 v[144:147], v129 offset:17984
	ds_read_b128 v[148:151], v129 offset:17728
	v_mov_b32_e32 v212, v120
	v_mov_b32_e32 v213, v122
	v_add_u32_e32 v138, 16, v132
	s_waitcnt lgkmcnt(1)
	v_sub_f32_e32 v143, v142, v144
	v_mul_f32_e32 v143, 0x3fb8aa3b, v143
	v_exp_f32_e32 v144, v143
	v_sub_f32_e32 v143, v142, v145
	v_mul_f32_e32 v143, 0x3fb8aa3b, v143
	v_exp_f32_e32 v152, v143
	v_sub_f32_e32 v143, v142, v146
	v_mul_f32_e32 v143, 0x3fb8aa3b, v143
	v_exp_f32_e32 v145, v143
	v_sub_f32_e32 v143, v142, v147
	v_mul_f32_e32 v143, 0x3fb8aa3b, v143
	v_exp_f32_e32 v153, v143
	v_pk_mul_f32 v[144:145], v[212:213], v[144:145]
	s_waitcnt lgkmcnt(0)
	v_mov_b32_e32 v146, v148
	v_mov_b32_e32 v147, v150
	v_add_u32_e32 v137, 18, v132
	v_pk_mul_f32 v[144:145], v[146:147], v[144:145]
	v_cmp_le_i32_e64 s[0:1], v138, v128
	v_mov_b32_e32 v122, v121
	v_add_u32_e32 v136, 17, v132
	v_cndmask_b32_e64 v143, 0, v144, s[0:1]
	v_cmp_le_i32_e64 s[0:1], v137, v128
	v_mov_b32_e32 v150, v149
	v_add_u32_e32 v135, 19, v132
	v_cndmask_b32_e64 v146, 0, v145, s[0:1]
	v_pk_mul_f32 v[144:145], v[122:123], v[152:153]
	v_cmp_le_i32_e64 s[0:1], v136, v128
	v_pk_mul_f32 v[144:145], v[150:151], v[144:145]
	s_nop 0
	v_cndmask_b32_e64 v144, 0, v144, s[0:1]
	v_cmp_le_i32_e64 s[0:1], v135, v128
	s_nop 1
	v_cndmask_b32_e64 v145, 0, v145, s[0:1]
	v_cvt_pk_bf16_f32 v145, v146, v145
	v_cvt_pk_bf16_f32 v144, v143, v144
	ds_write_b64 v141, v[144:145] offset:8480
	ds_read_b128 v[144:147], v129 offset:18048
	ds_read_b128 v[148:151], v129 offset:17792
	v_add_u32_e32 v133, 32, v132
	v_add_u32_e32 v126, 34, v132
	v_cmp_le_i32_e64 s[0:1], v133, v128
	s_waitcnt lgkmcnt(1)
	v_sub_f32_e32 v143, v142, v144
	v_mul_f32_e32 v143, 0x3fb8aa3b, v143
	v_exp_f32_e32 v144, v143
	v_sub_f32_e32 v143, v142, v145
	v_mul_f32_e32 v143, 0x3fb8aa3b, v143
	v_exp_f32_e32 v152, v143
	v_sub_f32_e32 v143, v142, v146
	v_mul_f32_e32 v143, 0x3fb8aa3b, v143
	v_exp_f32_e32 v145, v143
	v_sub_f32_e32 v143, v142, v147
	v_mul_f32_e32 v143, 0x3fb8aa3b, v143
	v_exp_f32_e32 v153, v143
	v_pk_mul_f32 v[144:145], v[210:211], v[144:145]
	s_waitcnt lgkmcnt(0)
	v_mov_b32_e32 v146, v148
	v_mov_b32_e32 v147, v150
	v_pk_mul_f32 v[144:145], v[146:147], v[144:145]
	v_add_u32_e32 v124, 33, v132
	v_cndmask_b32_e64 v143, 0, v144, s[0:1]
	v_cmp_le_i32_e64 s[0:1], v126, v128
	v_mov_b32_e32 v150, v149
	v_add_u32_e32 v121, 35, v132
	v_cndmask_b32_e64 v146, 0, v145, s[0:1]
	v_pk_mul_f32 v[144:145], v[118:119], v[152:153]
	v_cmp_le_i32_e64 s[0:1], v124, v128
	v_pk_mul_f32 v[144:145], v[150:151], v[144:145]
	s_nop 0
	v_cndmask_b32_e64 v144, 0, v144, s[0:1]
	v_cmp_le_i32_e64 s[0:1], v121, v128
	s_nop 1
	v_cndmask_b32_e64 v145, 0, v145, s[0:1]
	v_cvt_pk_bf16_f32 v145, v146, v145
	v_cvt_pk_bf16_f32 v144, v143, v144
	ds_write_b64 v141, v[144:145] offset:8512
	ds_read_b128 v[144:147], v129 offset:18112
	ds_read_b128 v[148:151], v129 offset:17856
	v_mov_b32_e32 v208, v112
	v_add_u32_e32 v140, 48, v132
	v_add_u32_e32 v120, 50, v132
	s_waitcnt lgkmcnt(1)
	v_sub_f32_e32 v143, v142, v144
	v_mul_f32_e32 v143, 0x3fb8aa3b, v143
	v_exp_f32_e32 v144, v143
	v_sub_f32_e32 v143, v142, v145
	v_mul_f32_e32 v143, 0x3fb8aa3b, v143
	v_exp_f32_e32 v152, v143
	v_sub_f32_e32 v143, v142, v146
	v_mul_f32_e32 v143, 0x3fb8aa3b, v143
	v_exp_f32_e32 v145, v143
	v_sub_f32_e32 v142, v142, v147
	v_mul_f32_e32 v142, 0x3fb8aa3b, v142
	v_exp_f32_e32 v153, v142
	v_pk_mul_f32 v[142:143], v[208:209], v[144:145]
	s_waitcnt lgkmcnt(0)
	v_mov_b32_e32 v144, v148
	v_mov_b32_e32 v145, v150
	v_pk_mul_f32 v[142:143], v[144:145], v[142:143]
	v_cmp_le_i32_e64 s[0:1], v140, v128
	v_add_u32_e32 v117, 49, v132
	v_mov_b32_e32 v150, v149
	v_cndmask_b32_e64 v144, 0, v142, s[0:1]
	v_cmp_le_i32_e64 s[0:1], v120, v128
	v_add_u32_e32 v116, 51, v132
	s_nop 0
	v_cndmask_b32_e64 v145, 0, v143, s[0:1]
	v_pk_mul_f32 v[142:143], v[114:115], v[152:153]
	v_cmp_le_i32_e64 s[0:1], v117, v128
	v_pk_mul_f32 v[142:143], v[150:151], v[142:143]
	s_nop 0
	v_cndmask_b32_e64 v142, 0, v142, s[0:1]
	v_cmp_le_i32_e64 s[0:1], v116, v128
	s_nop 1
	v_cndmask_b32_e64 v143, 0, v143, s[0:1]
	v_or_b32_e32 v112, 16, v128
	v_cvt_pk_bf16_f32 v143, v145, v143
	v_cvt_pk_bf16_f32 v142, v144, v142
	ds_write_b64 v141, v[142:143] offset:8544
	v_lshl_add_u32 v141, v112, 2, v191
	ds_read_b32 v142, v141 offset:17920
	ds_read_b128 v[144:147], v129 offset:17920
	ds_read_b128 v[148:151], v129 offset:17664
	v_cmp_le_i32_e64 s[0:1], v132, v112
	v_cmp_ge_i32_e64 s[50:51], v112, v113
	v_mad_u32_u24 v141, v112, s21, v139
	s_waitcnt lgkmcnt(1)
	v_sub_f32_e32 v143, v142, v144
	v_mul_f32_e32 v143, 0x3fb8aa3b, v143
	v_exp_f32_e32 v144, v143
	v_sub_f32_e32 v143, v142, v145
	v_mul_f32_e32 v143, 0x3fb8aa3b, v143
	v_sub_f32_e32 v145, v142, v146
	v_exp_f32_e32 v143, v143
	v_mul_f32_e32 v145, 0x3fb8aa3b, v145
	v_exp_f32_e32 v145, v145
	v_mov_b32_e32 v222, v12
	v_mul_f32_e32 v143, v61, v143
	s_waitcnt lgkmcnt(0)
	v_mul_f32_e32 v143, v149, v143
	v_pk_mul_f32 v[144:145], v[216:217], v[144:145]
	v_mov_b32_e32 v149, v150
	v_pk_mul_f32 v[144:145], v[148:149], v[144:145]
	v_mov_b32_e32 v223, v14
	v_cndmask_b32_e64 v60, 0, v144, s[0:1]
	v_sub_f32_e32 v144, v142, v147
	v_mul_f32_e32 v144, 0x3fb8aa3b, v144
	v_exp_f32_e32 v144, v144
	v_cmp_le_i32_e64 s[0:1], v134, v112
	v_mul_f32_e32 v144, v63, v144
	s_nop 0
	v_cndmask_b32_e64 v62, 0, v145, s[0:1]
	v_cmp_lt_i32_e64 s[0:1], v132, v112
	v_mul_f32_e32 v144, v151, v144
	v_cndmask_b32_e64 v144, 0, v144, s[50:51]
	v_cndmask_b32_e64 v143, 0, v143, s[0:1]
	v_cvt_pk_bf16_f32 v145, v62, v144
	v_cvt_pk_bf16_f32 v144, v60, v143
	ds_write_b64 v141, v[144:145] offset:8448
	ds_read_b128 v[144:147], v129 offset:17984
	ds_read_b128 v[148:151], v129 offset:17728
	v_cmp_le_i32_e64 s[0:1], v137, v112
	v_mad_u32_u24 v174, v128, s21, v129
	v_mad_u32_u24 v175, v112, s21, v129
	s_waitcnt lgkmcnt(1)
	v_sub_f32_e32 v60, v142, v144
	v_mul_f32_e32 v60, 0x3fb8aa3b, v60
	v_exp_f32_e32 v144, v60
	v_sub_f32_e32 v60, v142, v145
	v_mul_f32_e32 v60, 0x3fb8aa3b, v60
	v_exp_f32_e32 v152, v60
	v_sub_f32_e32 v60, v142, v146
	v_mul_f32_e32 v60, 0x3fb8aa3b, v60
	v_exp_f32_e32 v145, v60
	v_sub_f32_e32 v60, v142, v147
	v_mul_f32_e32 v60, 0x3fb8aa3b, v60
	v_exp_f32_e32 v153, v60
	v_pk_mul_f32 v[144:145], v[218:219], v[144:145]
	s_waitcnt lgkmcnt(0)
	v_mov_b32_e32 v146, v148
	v_mov_b32_e32 v147, v150
	v_pk_mul_f32 v[144:145], v[146:147], v[144:145]
	v_pk_mul_f32 v[56:57], v[58:59], v[152:153]
	v_mov_b32_e32 v150, v149
	v_cndmask_b32_e64 v62, 0, v145, s[0:1]
	v_pk_mul_f32 v[56:57], v[150:151], v[56:57]
	v_cmp_le_i32_e64 s[0:1], v136, v112
	v_cndmask_b32_e32 v60, 0, v144, vcc
	s_nop 0
	v_cndmask_b32_e64 v56, 0, v56, s[0:1]
	v_cmp_le_i32_e64 s[0:1], v135, v112
	s_nop 1
	v_cndmask_b32_e64 v57, 0, v57, s[0:1]
	v_cvt_pk_bf16_f32 v57, v62, v57
	v_cvt_pk_bf16_f32 v56, v60, v56
	ds_write_b64 v141, v[56:57] offset:8480
	ds_read_b128 v[144:147], v129 offset:18048
	ds_read_b128 v[148:151], v129 offset:17792
	v_mov_b32_e32 v57, v46
	v_cmp_le_i32_e64 s[0:1], v133, v112
	v_mov_b32_e32 v46, v45
	s_waitcnt lgkmcnt(1)
	v_sub_f32_e32 v56, v142, v144
	v_mul_f32_e32 v56, 0x3fb8aa3b, v56
	v_exp_f32_e32 v144, v56
	v_sub_f32_e32 v56, v142, v145
	v_mul_f32_e32 v56, 0x3fb8aa3b, v56
	v_exp_f32_e32 v152, v56
	v_sub_f32_e32 v56, v142, v146
	v_mul_f32_e32 v56, 0x3fb8aa3b, v56
	v_exp_f32_e32 v145, v56
	v_sub_f32_e32 v56, v142, v147
	v_mul_f32_e32 v56, 0x3fb8aa3b, v56
	v_exp_f32_e32 v153, v56
	v_mov_b32_e32 v56, v44
	v_pk_mul_f32 v[144:145], v[56:57], v[144:145]
	s_waitcnt lgkmcnt(0)
	v_mov_b32_e32 v146, v148
	v_mov_b32_e32 v147, v150
	v_pk_mul_f32 v[144:145], v[146:147], v[144:145]
	v_pk_mul_f32 v[44:45], v[46:47], v[152:153]
	v_cndmask_b32_e64 v60, 0, v144, s[0:1]
	v_cmp_le_i32_e64 s[0:1], v126, v112
	v_mov_b32_e32 v150, v149
	v_pk_mul_f32 v[44:45], v[150:151], v[44:45]
	v_cndmask_b32_e64 v62, 0, v145, s[0:1]
	v_cmp_le_i32_e64 s[0:1], v124, v112
	s_nop 1
	v_cndmask_b32_e64 v44, 0, v44, s[0:1]
	v_cmp_le_i32_e64 s[0:1], v121, v112
	s_nop 1
	v_cndmask_b32_e64 v45, 0, v45, s[0:1]
	v_cvt_pk_bf16_f32 v45, v62, v45
	v_cvt_pk_bf16_f32 v44, v60, v44
	ds_write_b64 v141, v[44:45] offset:8512
	ds_read_b128 v[144:147], v129 offset:18112
	ds_read_b128 v[148:151], v129 offset:17856
	v_mov_b32_e32 v45, v38
	v_cmp_le_i32_e64 s[0:1], v140, v112
	v_mov_b32_e32 v38, v37
	s_waitcnt lgkmcnt(1)
	v_sub_f32_e32 v44, v142, v144
	v_mul_f32_e32 v44, 0x3fb8aa3b, v44
	v_exp_f32_e32 v144, v44
	v_sub_f32_e32 v44, v142, v145
	v_mul_f32_e32 v44, 0x3fb8aa3b, v44
	v_exp_f32_e32 v152, v44
	v_sub_f32_e32 v44, v142, v146
	v_mul_f32_e32 v44, 0x3fb8aa3b, v44
	v_exp_f32_e32 v145, v44
	v_sub_f32_e32 v44, v142, v147
	v_mul_f32_e32 v44, 0x3fb8aa3b, v44
	v_exp_f32_e32 v153, v44
	v_mov_b32_e32 v44, v36
	v_pk_mul_f32 v[142:143], v[44:45], v[144:145]
	s_waitcnt lgkmcnt(0)
	v_mov_b32_e32 v144, v148
	v_mov_b32_e32 v145, v150
	v_pk_mul_f32 v[142:143], v[144:145], v[142:143]
	v_pk_mul_f32 v[36:37], v[38:39], v[152:153]
	v_cndmask_b32_e64 v60, 0, v142, s[0:1]
	v_cmp_le_i32_e64 s[0:1], v120, v112
	v_mov_b32_e32 v150, v149
	v_pk_mul_f32 v[36:37], v[150:151], v[36:37]
	v_cndmask_b32_e64 v62, 0, v143, s[0:1]
	v_cmp_le_i32_e64 s[0:1], v117, v112
	s_nop 1
	v_cndmask_b32_e64 v36, 0, v36, s[0:1]
	v_cmp_le_i32_e64 s[0:1], v116, v112
	s_nop 1
	v_cndmask_b32_e64 v37, 0, v37, s[0:1]
	v_cvt_pk_bf16_f32 v37, v62, v37
	v_cvt_pk_bf16_f32 v36, v60, v36
	ds_write_b64 v141, v[36:37] offset:8544
	ds_read_b32 v142, v131 offset:18048
	ds_read_b128 v[144:147], v129 offset:17920
	ds_read_b128 v[148:151], v129 offset:17664
	v_mov_b32_e32 v37, v30
	v_or_b32_e32 v141, 32, v128
	v_cmp_le_i32_e64 s[0:1], v132, v141
	s_waitcnt lgkmcnt(1)
	v_sub_f32_e32 v36, v142, v144
	v_mul_f32_e32 v36, 0x3fb8aa3b, v36
	v_exp_f32_e32 v144, v36
	v_sub_f32_e32 v36, v142, v145
	v_mul_f32_e32 v36, 0x3fb8aa3b, v36
	v_exp_f32_e32 v36, v36
	v_cmp_ge_i32_e64 s[50:51], v141, v113
	v_mad_u32_u24 v60, v128, s21, v230
	v_add_u32_e32 v62, v139, v60
	v_mul_f32_e32 v36, v29, v36
	s_waitcnt lgkmcnt(0)
	v_mul_f32_e32 v143, v149, v36
	v_sub_f32_e32 v36, v142, v146
	v_mul_f32_e32 v36, 0x3fb8aa3b, v36
	v_exp_f32_e32 v145, v36
	v_sub_f32_e32 v36, v142, v147
	v_mul_f32_e32 v36, 0x3fb8aa3b, v36
	v_exp_f32_e32 v36, v36
	v_mov_b32_e32 v149, v150
	v_add_u32_e32 v176, v129, v60
	v_mul_f32_e32 v36, v31, v36
	v_mul_f32_e32 v146, v151, v36
	v_mov_b32_e32 v36, v28
	v_pk_mul_f32 v[144:145], v[36:37], v[144:145]
	s_nop 0
	v_pk_mul_f32 v[144:145], v[148:149], v[144:145]
	s_nop 0
	v_cndmask_b32_e64 v28, 0, v144, s[0:1]
	v_cmp_le_i32_e64 s[0:1], v134, v141
	v_cndmask_b32_e64 v144, 0, v146, s[50:51]
	s_nop 0
	v_cndmask_b32_e64 v30, 0, v145, s[0:1]
	v_cmp_lt_i32_e64 s[0:1], v132, v141
	s_nop 1
	v_cndmask_b32_e64 v143, 0, v143, s[0:1]
	v_cvt_pk_bf16_f32 v145, v30, v144
	v_cvt_pk_bf16_f32 v144, v28, v143
	ds_write_b64 v62, v[144:145] offset:8448
	ds_read_b128 v[144:147], v129 offset:17984
	ds_read_b128 v[148:151], v129 offset:17728
	v_cmp_le_i32_e64 s[0:1], v138, v141
	s_waitcnt lgkmcnt(1)
	v_sub_f32_e32 v28, v142, v144
	v_mul_f32_e32 v28, 0x3fb8aa3b, v28
	v_exp_f32_e32 v144, v28
	v_sub_f32_e32 v28, v142, v145
	v_mul_f32_e32 v28, 0x3fb8aa3b, v28
	v_exp_f32_e32 v152, v28
	v_sub_f32_e32 v28, v142, v146
	v_mul_f32_e32 v28, 0x3fb8aa3b, v28
	v_exp_f32_e32 v145, v28
	v_sub_f32_e32 v28, v142, v147
	v_mul_f32_e32 v28, 0x3fb8aa3b, v28
	v_exp_f32_e32 v153, v28
	v_pk_mul_f32 v[144:145], v[220:221], v[144:145]
	s_waitcnt lgkmcnt(0)
	v_mov_b32_e32 v146, v148
	v_mov_b32_e32 v147, v150
	v_pk_mul_f32 v[144:145], v[146:147], v[144:145]
	v_pk_mul_f32 v[24:25], v[26:27], v[152:153]
	v_cndmask_b32_e64 v28, 0, v144, s[0:1]
	v_cmp_le_i32_e64 s[0:1], v137, v141
	v_mov_b32_e32 v150, v149
	v_pk_mul_f32 v[24:25], v[150:151], v[24:25]
	v_cndmask_b32_e64 v30, 0, v145, s[0:1]
	v_cmp_le_i32_e64 s[0:1], v136, v141
	s_nop 1
	v_cndmask_b32_e64 v24, 0, v24, s[0:1]
	v_cmp_le_i32_e64 s[0:1], v135, v141
	s_nop 1
	v_cndmask_b32_e64 v25, 0, v25, s[0:1]
	v_cvt_pk_bf16_f32 v25, v30, v25
	v_cvt_pk_bf16_f32 v24, v28, v24
	ds_write_b64 v62, v[24:25] offset:8480
	ds_read_b128 v[144:147], v129 offset:18048
	ds_read_b128 v[148:151], v129 offset:17792
	v_mov_b32_e32 v25, v22
	v_mov_b32_e32 v22, v21
	v_cmp_le_i32_e64 s[0:1], v126, v141
	s_waitcnt lgkmcnt(1)
	v_sub_f32_e32 v24, v142, v144
	v_mul_f32_e32 v24, 0x3fb8aa3b, v24
	v_exp_f32_e32 v144, v24
	v_sub_f32_e32 v24, v142, v145
	v_mul_f32_e32 v24, 0x3fb8aa3b, v24
	v_exp_f32_e32 v152, v24
	v_sub_f32_e32 v24, v142, v146
	v_mul_f32_e32 v24, 0x3fb8aa3b, v24
	v_exp_f32_e32 v145, v24
	v_sub_f32_e32 v24, v142, v147
	v_mul_f32_e32 v24, 0x3fb8aa3b, v24
	v_exp_f32_e32 v153, v24
	v_mov_b32_e32 v24, v20
	v_pk_mul_f32 v[144:145], v[24:25], v[144:145]
	s_waitcnt lgkmcnt(0)
	v_mov_b32_e32 v146, v148
	v_mov_b32_e32 v147, v150
	v_pk_mul_f32 v[144:145], v[146:147], v[144:145]
	v_pk_mul_f32 v[20:21], v[22:23], v[152:153]
	v_mov_b32_e32 v150, v149
	v_cndmask_b32_e64 v30, 0, v145, s[0:1]
	v_pk_mul_f32 v[20:21], v[150:151], v[20:21]
	v_cmp_le_i32_e64 s[0:1], v124, v141
	v_cndmask_b32_e32 v28, 0, v144, vcc
	s_nop 0
	v_cndmask_b32_e64 v20, 0, v20, s[0:1]
	v_cmp_le_i32_e64 s[0:1], v121, v141
	s_nop 1
	v_cndmask_b32_e64 v21, 0, v21, s[0:1]
	v_cvt_pk_bf16_f32 v21, v30, v21
	v_cvt_pk_bf16_f32 v20, v28, v20
	ds_write_b64 v62, v[20:21] offset:8512
	ds_read_b128 v[144:147], v129 offset:18112
	ds_read_b128 v[148:151], v129 offset:17856
	v_mov_b32_e32 v21, v18
	v_cmp_le_i32_e64 s[0:1], v140, v141
	v_mov_b32_e32 v18, v17
	s_waitcnt lgkmcnt(1)
	v_sub_f32_e32 v20, v142, v144
	v_mul_f32_e32 v20, 0x3fb8aa3b, v20
	v_exp_f32_e32 v144, v20
	v_sub_f32_e32 v20, v142, v145
	v_mul_f32_e32 v20, 0x3fb8aa3b, v20
	v_exp_f32_e32 v152, v20
	v_sub_f32_e32 v20, v142, v146
	v_mul_f32_e32 v20, 0x3fb8aa3b, v20
	v_exp_f32_e32 v145, v20
	v_sub_f32_e32 v20, v142, v147
	v_mul_f32_e32 v20, 0x3fb8aa3b, v20
	v_exp_f32_e32 v153, v20
	v_mov_b32_e32 v20, v16
	v_pk_mul_f32 v[142:143], v[20:21], v[144:145]
	s_waitcnt lgkmcnt(0)
	v_mov_b32_e32 v144, v148
	v_mov_b32_e32 v145, v150
	v_pk_mul_f32 v[142:143], v[144:145], v[142:143]
	v_pk_mul_f32 v[16:17], v[18:19], v[152:153]
	v_cndmask_b32_e64 v28, 0, v142, s[0:1]
	v_cmp_le_i32_e64 s[0:1], v120, v141
	v_mov_b32_e32 v150, v149
	v_pk_mul_f32 v[16:17], v[150:151], v[16:17]
	v_cndmask_b32_e64 v30, 0, v143, s[0:1]
	v_cmp_le_i32_e64 s[0:1], v117, v141
	s_nop 1
	v_cndmask_b32_e64 v16, 0, v16, s[0:1]
	v_cmp_le_i32_e64 s[0:1], v116, v141
	s_nop 1
	v_cndmask_b32_e64 v17, 0, v17, s[0:1]
	v_cvt_pk_bf16_f32 v17, v30, v17
	v_cvt_pk_bf16_f32 v16, v28, v16
	ds_write_b64 v62, v[16:17] offset:8544
	ds_read_b32 v62, v131 offset:18112
	ds_read_b128 v[140:143], v129 offset:17920
	ds_read_b128 v[144:147], v129 offset:17664
	v_mad_u32_u24 v28, v128, s21, v232
	v_add_u32_e32 v150, v139, v28
	v_or_b32_e32 v30, 48, v128
	s_waitcnt lgkmcnt(1)
	v_sub_f32_e32 v17, v62, v141
	v_mul_f32_e32 v17, 0x3fb8aa3b, v17
	v_exp_f32_e32 v17, v17
	v_sub_f32_e32 v16, v62, v140
	v_mul_f32_e32 v16, 0x3fb8aa3b, v16
	v_exp_f32_e32 v16, v16
	v_mul_f32_e32 v17, v13, v17
	s_waitcnt lgkmcnt(0)
	v_mul_f32_e32 v139, v145, v17
	v_sub_f32_e32 v17, v62, v142
	v_mul_f32_e32 v17, 0x3fb8aa3b, v17
	v_exp_f32_e32 v17, v17
	v_sub_f32_e32 v140, v62, v143
	v_mul_f32_e32 v140, 0x3fb8aa3b, v140
	v_exp_f32_e32 v140, v140
	v_pk_mul_f32 v[16:17], v[222:223], v[16:17]
	v_mov_b32_e32 v145, v146
	v_pk_mul_f32 v[16:17], v[144:145], v[16:17]
	v_cmp_le_i32_e64 s[0:1], v132, v30
	v_mul_f32_e32 v140, v15, v140
	v_mul_f32_e32 v140, v147, v140
	v_cndmask_b32_e64 v12, 0, v16, s[0:1]
	v_cmp_le_i32_e64 s[0:1], v134, v30
	v_cmp_ge_i32_e64 s[50:51], v30, v113
	v_add_u32_e32 v177, v129, v28
	v_cndmask_b32_e64 v14, 0, v17, s[0:1]
	v_cmp_lt_i32_e64 s[0:1], v132, v30
	v_cndmask_b32_e64 v16, 0, v140, s[50:51]
	s_nop 0
	v_cndmask_b32_e64 v17, 0, v139, s[0:1]
	v_and_b32_sdwa v132, v12, v228 dst_sel:DWORD dst_unused:UNUSED_PAD src0_sel:WORD_1 src1_sel:DWORD
	v_add3_u32 v12, v12, v132, s96
	v_and_b32_sdwa v132, v17, v228 dst_sel:DWORD dst_unused:UNUSED_PAD src0_sel:WORD_1 src1_sel:DWORD
	s_nop 0
	v_add3_u32 v17, v17, v132, s96
	v_and_b32_e32 v113, 0xffff0000, v17
	v_cvt_pk_bf16_f32 v17, v14, v16
	v_or_b32_sdwa v16, v113, v12 dst_sel:DWORD dst_unused:UNUSED_PAD src0_sel:DWORD src1_sel:WORD_1
	ds_write_b64 v150, v[16:17] offset:8448
	ds_read_b128 v[140:143], v129 offset:17984
	ds_read_b128 v[144:147], v129 offset:17728
	v_mov_b32_e32 v16, v8
	v_mov_b32_e32 v17, v10
	v_cmp_le_i32_e64 s[0:1], v138, v30
	s_waitcnt lgkmcnt(1)
	v_sub_f32_e32 v12, v62, v140
	v_mul_f32_e32 v12, 0x3fb8aa3b, v12
	v_exp_f32_e32 v140, v12
	v_sub_f32_e32 v12, v62, v141
	v_mul_f32_e32 v12, 0x3fb8aa3b, v12
	v_exp_f32_e32 v148, v12
	v_sub_f32_e32 v12, v62, v142
	v_mul_f32_e32 v12, 0x3fb8aa3b, v12
	v_exp_f32_e32 v141, v12
	v_sub_f32_e32 v12, v62, v143
	v_mul_f32_e32 v12, 0x3fb8aa3b, v12
	v_exp_f32_e32 v149, v12
	v_pk_mul_f32 v[140:141], v[16:17], v[140:141]
	s_waitcnt lgkmcnt(0)
	v_mov_b32_e32 v142, v144
	v_mov_b32_e32 v143, v146
	v_pk_mul_f32 v[140:141], v[142:143], v[140:141]
	v_mov_b32_e32 v10, v9
	v_cndmask_b32_e64 v12, 0, v140, s[0:1]
	v_cmp_le_i32_e64 s[0:1], v137, v30
	v_pk_mul_f32 v[8:9], v[10:11], v[148:149]
	v_mov_b32_e32 v146, v145
	v_cndmask_b32_e64 v14, 0, v141, s[0:1]
	v_pk_mul_f32 v[8:9], v[146:147], v[8:9]
	v_cmp_le_i32_e64 s[0:1], v136, v30
	s_nop 1
	v_cndmask_b32_e64 v8, 0, v8, s[0:1]
	v_cmp_le_i32_e64 s[0:1], v135, v30
	s_nop 1
	v_cndmask_b32_e64 v9, 0, v9, s[0:1]
	v_cvt_pk_bf16_f32 v9, v14, v9
	v_cvt_pk_bf16_f32 v8, v12, v8
	ds_write_b64 v150, v[8:9] offset:8480
	ds_read_b128 v[134:137], v129 offset:18048
	ds_read_b128 v[138:141], v129 offset:17792
	v_mov_b32_e32 v9, v6
	v_cmp_le_i32_e64 s[0:1], v133, v30
	v_mov_b32_e32 v6, v5
	s_waitcnt lgkmcnt(1)
	v_sub_f32_e32 v8, v62, v134
	v_mul_f32_e32 v8, 0x3fb8aa3b, v8
	v_exp_f32_e32 v134, v8
	v_sub_f32_e32 v8, v62, v135
	v_mul_f32_e32 v8, 0x3fb8aa3b, v8
	v_exp_f32_e32 v142, v8
	v_sub_f32_e32 v8, v62, v136
	v_mul_f32_e32 v8, 0x3fb8aa3b, v8
	v_exp_f32_e32 v135, v8
	v_sub_f32_e32 v8, v62, v137
	v_mul_f32_e32 v8, 0x3fb8aa3b, v8
	v_exp_f32_e32 v143, v8
	v_mov_b32_e32 v8, v4
	v_pk_mul_f32 v[134:135], v[8:9], v[134:135]
	s_waitcnt lgkmcnt(0)
	v_mov_b32_e32 v136, v138
	v_mov_b32_e32 v137, v140
	v_pk_mul_f32 v[134:135], v[136:137], v[134:135]
	v_pk_mul_f32 v[4:5], v[6:7], v[142:143]
	v_cndmask_b32_e64 v12, 0, v134, s[0:1]
	v_cmp_le_i32_e64 s[0:1], v126, v30
	v_mov_b32_e32 v140, v139
	v_pk_mul_f32 v[4:5], v[140:141], v[4:5]
	v_cndmask_b32_e64 v14, 0, v135, s[0:1]
	v_cmp_le_i32_e64 s[0:1], v124, v30
	s_nop 1
	v_cndmask_b32_e64 v4, 0, v4, s[0:1]
	v_cmp_le_i32_e64 s[0:1], v121, v30
	s_nop 1
	v_cndmask_b32_e64 v5, 0, v5, s[0:1]
	v_cvt_pk_bf16_f32 v5, v14, v5
	v_cvt_pk_bf16_f32 v4, v12, v4
	ds_write_b64 v150, v[4:5] offset:8512
	ds_read_b128 v[132:135], v129 offset:18112
	ds_read_b128 v[136:139], v129 offset:17856
	v_mov_b32_e32 v5, v2
	v_mov_b32_e32 v2, v1
	s_waitcnt lgkmcnt(1)
	v_sub_f32_e32 v4, v62, v132
	v_mul_f32_e32 v4, 0x3fb8aa3b, v4
	v_exp_f32_e32 v132, v4
	v_sub_f32_e32 v4, v62, v133
	v_mul_f32_e32 v4, 0x3fb8aa3b, v4
	v_exp_f32_e32 v140, v4
	v_sub_f32_e32 v4, v62, v134
	v_mul_f32_e32 v4, 0x3fb8aa3b, v4
	v_exp_f32_e32 v133, v4
	v_sub_f32_e32 v4, v62, v135
	v_mul_f32_e32 v4, 0x3fb8aa3b, v4
	v_exp_f32_e32 v141, v4
	v_mov_b32_e32 v4, v0
	v_pk_mul_f32 v[132:133], v[4:5], v[132:133]
	s_waitcnt lgkmcnt(0)
	v_mov_b32_e32 v134, v136
	v_mov_b32_e32 v135, v138
	v_pk_mul_f32 v[132:133], v[134:135], v[132:133]
	v_pk_mul_f32 v[0:1], v[2:3], v[140:141]
	v_cndmask_b32_e32 v12, 0, v132, vcc
	v_cmp_le_i32_e32 vcc, v120, v30
	v_mov_b32_e32 v138, v137
	v_pk_mul_f32 v[0:1], v[138:139], v[0:1]
	v_cndmask_b32_e32 v14, 0, v133, vcc
	v_cmp_le_i32_e32 vcc, v117, v30
	s_nop 1
	v_cndmask_b32_e32 v0, 0, v0, vcc
	v_cmp_le_i32_e32 vcc, v116, v30
	s_nop 1
	v_cndmask_b32_e32 v1, 0, v1, vcc
	v_cvt_pk_bf16_f32 v1, v14, v1
	v_cvt_pk_bf16_f32 v0, v12, v0
	ds_write_b64 v150, v[0:1] offset:8544
	v_lshlrev_b32_e32 v0, 1, v128
	v_sub_u32_e32 v0, v131, v0
	v_mad_u64_u32 v[0:1], s[0:1], v130, s23, v[0:1]
	s_waitcnt lgkmcnt(0)
	ds_read_u16 v1, v0 offset:132
	ds_read_u16 v12, v0 offset:264
	ds_read_u16 v14, v0 offset:396
	ds_read_u16 v30, v0 offset:528
	ds_read_u16 v62, v0 offset:660
	ds_read_u16 v113, v0 offset:792
	ds_read_u16 v116, v0 offset:924
	ds_read_u16 v117, v0
	ds_read_u16 v120, v0 offset:32
	ds_read_u16 v121, v0 offset:164
	ds_read_u16 v124, v0 offset:296
	ds_read_u16 v126, v0 offset:428
	ds_read_u16 v132, v0 offset:560
	ds_read_u16 v133, v0 offset:692
	ds_read_u16 v134, v0 offset:824
	ds_read_u16 v135, v0 offset:956
	ds_read_u16 v179, v0 offset:64
	ds_read_u16 v225, v0 offset:196
	ds_read_u16 v233, v0 offset:328
	ds_read_u16 v234, v0 offset:460
	ds_read_u16 v235, v0 offset:592
	ds_read_u16 v236, v0 offset:724
	ds_read_u16 v237, v0 offset:856
	ds_read_u16 v243, v0 offset:988
	ds_read_u16 v244, v0 offset:96
	ds_read_u16 v245, v0 offset:228
	ds_read_u16 v246, v0 offset:360
	ds_read_u16 v247, v0 offset:492
	ds_read_u16 v248, v0 offset:624
	ds_read_u16 v249, v0 offset:756
	ds_read_u16 v250, v0 offset:888
	ds_read_u16 v251, v0 offset:1020
	ds_read_b128 v[160:163], v176 offset:8448
	ds_read_b128 v[164:167], v177 offset:8448
	s_waitcnt lgkmcnt(14)
	v_perm_b32 v131, v116, v113, s25
	v_perm_b32 v130, v62, v30, s25
	v_perm_b32 v129, v14, v12, s25
	v_perm_b32 v128, v1, v117, s25
	ds_read_b128 v[152:155], v174 offset:8448
	ds_read_b128 v[156:159], v175 offset:8448
	s_waitcnt lgkmcnt(3)
	v_mfma_f32_16x16x32_bf16 v[144:147], v[128:131], v[160:163], v[80:83]
	s_nop 2
	v_perm_b32 v83, v135, v134, s25
	v_perm_b32 v82, v133, v132, s25
	v_perm_b32 v81, v126, v124, s25
	v_perm_b32 v80, v121, v120, s25
	s_waitcnt lgkmcnt(0)
	v_mfma_f32_16x16x32_bf16 v[148:151], v[128:131], v[156:159], v[64:67]
	v_mov_b32_e32 v126, v125
	v_mfma_f32_16x16x32_bf16 v[64:67], v[80:83], v[152:155], v[40:43]
	s_nop 2
	v_perm_b32 v43, v243, v237, s25
	v_perm_b32 v42, v236, v235, s25
	v_perm_b32 v41, v234, v233, s25
	v_perm_b32 v40, v225, v179, s25
	v_mfma_f32_16x16x32_bf16 v[32:35], v[128:131], v[152:155], v[32:35]
	v_mfma_f32_16x16x32_bf16 v[140:143], v[128:131], v[164:167], v[96:99]
	v_mfma_f32_16x16x32_bf16 v[68:71], v[80:83], v[156:159], v[68:71]
	v_mfma_f32_16x16x32_bf16 v[136:139], v[80:83], v[160:163], v[84:87]
	v_mfma_f32_16x16x32_bf16 v[132:135], v[80:83], v[164:167], v[100:103]
	v_mfma_f32_16x16x32_bf16 v[80:83], v[40:43], v[152:155], v[48:51]
	v_mfma_f32_16x16x32_bf16 v[84:87], v[40:43], v[156:159], v[72:75]
	v_mfma_f32_16x16x32_bf16 v[88:91], v[40:43], v[160:163], v[88:91]
	v_mfma_f32_16x16x32_bf16 v[128:131], v[40:43], v[164:167], v[104:107]
	v_perm_b32 v43, v251, v250, s25
	v_perm_b32 v42, v249, v248, s25
	v_perm_b32 v41, v247, v246, s25
	v_perm_b32 v40, v245, v244, s25
	s_nop 1
	v_mfma_f32_16x16x32_bf16 v[96:99], v[40:43], v[152:155], v[52:55]
	v_mfma_f32_16x16x32_bf16 v[100:103], v[40:43], v[156:159], v[76:79]
	v_mfma_f32_16x16x32_bf16 v[104:107], v[40:43], v[160:163], v[92:95]
	v_mfma_f32_16x16x32_bf16 v[108:111], v[40:43], v[164:167], v[108:111]
	ds_read_u16 v40, v0 offset:4224
	ds_read_u16 v41, v0 offset:4356
	ds_read_u16 v42, v0 offset:4488
	ds_read_u16 v43, v0 offset:4620
	ds_read_u16 v48, v0 offset:4752
	ds_read_u16 v49, v0 offset:4884
	ds_read_u16 v50, v0 offset:5016
	ds_read_u16 v51, v0 offset:5148
	ds_read_u16 v72, v0 offset:4256
	ds_read_u16 v73, v0 offset:4388
	ds_read_u16 v74, v0 offset:4520
	ds_read_u16 v75, v0 offset:4652
	ds_read_u16 v76, v0 offset:4784
	ds_read_u16 v77, v0 offset:4916
	ds_read_u16 v78, v0 offset:5048
	ds_read_u16 v79, v0 offset:5180
	ds_read_u16 v92, v0 offset:4288
	ds_read_u16 v93, v0 offset:4420
	ds_read_u16 v94, v0 offset:4552
	ds_read_u16 v95, v0 offset:4684
	ds_read_u16 v112, v0 offset:4816
	ds_read_u16 v113, v0 offset:4948
	ds_read_u16 v116, v0 offset:5080
	ds_read_u16 v117, v0 offset:5212
	ds_read_u16 v1, v0 offset:4320
	ds_read_u16 v12, v0 offset:4452
	ds_read_u16 v14, v0 offset:4584
	ds_read_u16 v28, v0 offset:4716
	ds_read_u16 v30, v0 offset:4848
	ds_read_u16 v60, v0 offset:4980
	ds_read_u16 v62, v0 offset:5112
	ds_read_u16 v0, v0 offset:5244
	ds_read_b128 v[152:155], v174 offset:8512
	ds_read_b128 v[156:159], v175 offset:8512
	ds_read_b128 v[160:163], v176 offset:8512
	ds_read_b128 v[164:167], v177 offset:8512
	s_waitcnt lgkmcnt(14)
	v_perm_b32 v79, v79, v78, s25
	v_perm_b32 v78, v77, v76, s25
	v_perm_b32 v77, v75, v74, s25
	v_perm_b32 v76, v73, v72, s25
	v_perm_b32 v55, v51, v50, s25
	v_perm_b32 v54, v49, v48, s25
	s_waitcnt lgkmcnt(3)
	v_mfma_f32_16x16x32_bf16 v[64:67], v[76:79], v[152:155], v[64:67]
	v_perm_b32 v53, v43, v42, s25
	v_perm_b32 v52, v41, v40, s25
	s_waitcnt lgkmcnt(0)
	s_waitcnt lgkmcnt(2)
	v_mfma_f32_16x16x32_bf16 v[68:71], v[76:79], v[156:159], v[68:71]
	s_waitcnt lgkmcnt(1)
	v_mfma_f32_16x16x32_bf16 v[72:75], v[76:79], v[160:163], v[136:139]
	s_waitcnt lgkmcnt(0)
	v_mfma_f32_16x16x32_bf16 v[76:79], v[76:79], v[164:167], v[132:135]
	s_nop 2
	v_perm_b32 v135, v117, v116, s25
	v_perm_b32 v134, v113, v112, s25
	v_perm_b32 v133, v95, v94, s25
	v_perm_b32 v132, v93, v92, s25
	v_mov_b32_e32 v116, v190
	v_mfma_f32_16x16x32_bf16 v[32:35], v[52:55], v[152:155], v[32:35]
	v_mfma_f32_16x16x32_bf16 v[92:95], v[132:135], v[164:167], v[128:131]
	s_nop 2
	v_perm_b32 v131, v0, v62, s25
	v_perm_b32 v130, v60, v30, s25
	v_perm_b32 v129, v28, v14, s25
	v_perm_b32 v128, v12, v1, s25
	v_and_b32_e32 v12, 15, v116
	v_mfma_f32_16x16x32_bf16 v[40:43], v[52:55], v[156:159], v[148:151]
	v_or_b32_e32 v0, s58, v12
	v_mad_u64_u32 v[112:113], s[0:1], v0, s22, v[204:205]
	v_mfma_f32_16x16x32_bf16 v[48:51], v[52:55], v[160:163], v[144:147]
	v_or_b32_e32 v14, 32, v12
	v_add_u32_e32 v113, s20, v113
	v_mov_b32_e32 v30, v29
	v_mfma_f32_16x16x32_bf16 v[52:55], v[52:55], v[164:167], v[140:143]
	v_mov_b32_e32 v62, v61
	v_mfma_f32_16x16x32_bf16 v[108:111], v[128:131], v[164:167], v[108:111]
	v_or_b32_e32 v167, 16, v12
	v_or_b32_e32 v0, s58, v167
	v_mfma_f32_16x16x32_bf16 v[84:87], v[132:135], v[156:159], v[84:87]
	v_mfma_f32_16x16x32_bf16 v[96:99], v[128:131], v[152:155], v[96:99]
	v_mfma_f32_16x16x32_bf16 v[100:103], v[128:131], v[156:159], v[100:103]
	v_or_b32_e32 v156, 48, v12
	v_lshl_add_u32 v157, v12, 2, v191
	ds_read_b32 v165, v157 offset:18432
	v_mfma_f32_16x16x32_bf16 v[104:107], v[128:131], v[160:163], v[104:107]
	v_mad_u64_u32 v[130:131], s[0:1], v0, s22, v[204:205]
	v_or_b32_e32 v0, s58, v14
	v_mad_u64_u32 v[148:149], s[0:1], v0, s22, v[204:205]
	v_or_b32_e32 v0, s58, v156
	v_mfma_f32_16x16x32_bf16 v[80:83], v[132:135], v[152:155], v[80:83]
	v_ashrrev_i32_e32 v155, 4, v116
	v_mad_u64_u32 v[150:151], s[0:1], v0, s22, v[204:205]
	v_mov_b32_e32 v0, 0x900
	v_mad_u32_u24 v152, v12, s21, v0
	v_lshlrev_b32_e32 v0, 2, v155
	v_ashrrev_i32_e32 v1, 31, v0
	v_lshlrev_b64 v[28:29], 1, v[0:1]
	v_add_u32_e32 v131, s20, v131
	v_lshl_add_u64 v[60:61], v[112:113], 0, v[28:29]
	v_add_u32_e32 v149, s20, v149
	v_add_u32_e32 v151, s20, v151
	global_load_dwordx2 v[142:143], v[60:61], off offset:1536
	v_lshl_add_u64 v[60:61], v[130:131], 0, v[28:29]
	v_and_b32_e32 v1, -16, v116
	v_mfma_f32_16x16x32_bf16 v[88:91], v[132:135], v[160:163], v[88:91]
	global_load_dwordx2 v[134:135], v[60:61], off offset:1536
	v_lshl_add_u64 v[60:61], v[148:149], 0, v[28:29]
	v_lshl_add_u64 v[28:29], v[150:151], 0, v[28:29]
	v_add_u32_e32 v1, v191, v1
	global_load_dwordx2 v[128:129], v[60:61], off offset:1536
	global_load_dwordx2 v[120:121], v[28:29], off offset:1536
	ds_read_b128 v[136:139], v1 offset:18432
	ds_read_b128 v[144:147], v1 offset:18176
	v_lshlrev_b32_e32 v28, 3, v155
	v_sub_u32_e32 v162, v1, v28
	v_cmp_lt_i32_e32 vcc, v0, v12
	s_waitcnt lgkmcnt(1)
	v_sub_f32_e32 v29, v165, v137
	v_mul_f32_e32 v29, 0x3fb8aa3b, v29
	v_sub_f32_e32 v28, v165, v136
	v_exp_f32_e32 v60, v29
	v_sub_f32_e32 v29, v165, v138
	v_mul_f32_e32 v28, 0x3fb8aa3b, v28
	v_mul_f32_e32 v29, 0x3fb8aa3b, v29
	v_exp_f32_e32 v28, v28
	v_exp_f32_e32 v29, v29
	s_waitcnt lgkmcnt(0)
	v_mov_b32_e32 v116, v144
	v_mov_b32_e32 v117, v146
	v_or_b32_e32 v158, 2, v0
	v_pk_mul_f32 v[28:29], v[214:215], v[28:29]
	v_cmp_ge_i32_e64 s[0:1], v158, v12
	v_pk_mul_f32 v[28:29], v[116:117], v[28:29]
	v_or_b32_e32 v160, 1, v0
	v_cndmask_b32_e64 v116, v28, 0, vcc
	v_sub_f32_e32 v28, v165, v139
	v_mul_f32_e32 v28, 0x3fb8aa3b, v28
	v_exp_f32_e32 v61, v28
	v_cndmask_b32_e64 v117, 0, v29, s[0:1]
	v_mov_b32_e32 v146, v145
	v_or_b32_e32 v159, 3, v0
	v_pk_mul_f32 v[28:29], v[126:127], v[60:61]
	v_cmp_ge_i32_e64 s[0:1], v160, v12
	v_pk_mul_f32 v[28:29], v[146:147], v[28:29]
	v_and_b32_sdwa v60, v117, v228 dst_sel:DWORD dst_unused:UNUSED_PAD src0_sel:WORD_1 src1_sel:DWORD
	v_cndmask_b32_e64 v28, 0, v28, s[0:1]
	v_cmp_ge_i32_e64 s[0:1], v159, v12
	v_and_b32_sdwa v61, v116, v228 dst_sel:DWORD dst_unused:UNUSED_PAD src0_sel:WORD_1 src1_sel:DWORD
	v_add3_u32 v61, v116, v61, s96
	v_cndmask_b32_e64 v29, 0, v29, s[0:1]
	v_add3_u32 v60, v117, v60, s96
	v_and_b32_sdwa v116, v29, v228 dst_sel:DWORD dst_unused:UNUSED_PAD src0_sel:WORD_1 src1_sel:DWORD
	v_and_b32_sdwa v117, v28, v228 dst_sel:DWORD dst_unused:UNUSED_PAD src0_sel:WORD_1 src1_sel:DWORD
	v_add3_u32 v29, v29, v116, s96
	v_add3_u32 v28, v28, v117, s96
	v_and_b32_e32 v29, 0xffff0000, v29
	v_and_b32_e32 v28, 0xffff0000, v28
	v_mad_u32_u24 v174, v12, s21, v162
	v_or_b32_sdwa v29, v29, v60 dst_sel:DWORD dst_unused:UNUSED_PAD src0_sel:DWORD src1_sel:WORD_1
	v_or_b32_sdwa v28, v28, v61 dst_sel:DWORD dst_unused:UNUSED_PAD src0_sel:DWORD src1_sel:WORD_1
	ds_write_b64 v174, v[28:29] offset:8448
	ds_read_b128 v[124:127], v1 offset:18496
	ds_read_b128 v[138:141], v1 offset:18240
	v_add_u32_e32 v161, 18, v0
	v_add_u32_e32 v164, 17, v0
	v_add_u32_e32 v163, 34, v0
	s_waitcnt lgkmcnt(1)
	v_sub_f32_e32 v28, v165, v124
	v_mul_f32_e32 v28, 0x3fb8aa3b, v28
	v_exp_f32_e32 v60, v28
	v_sub_f32_e32 v28, v165, v125
	v_mul_f32_e32 v28, 0x3fb8aa3b, v28
	v_exp_f32_e32 v116, v28
	v_sub_f32_e32 v28, v165, v126
	v_mul_f32_e32 v28, 0x3fb8aa3b, v28
	v_exp_f32_e32 v61, v28
	v_sub_f32_e32 v28, v165, v127
	v_mul_f32_e32 v28, 0x3fb8aa3b, v28
	v_exp_f32_e32 v117, v28
	v_add_u32_e32 v28, 16, v0
	v_pk_mul_f32 v[60:61], v[212:213], v[60:61]
	s_waitcnt lgkmcnt(0)
	v_mov_b32_e32 v132, v138
	v_mov_b32_e32 v133, v140
	v_pk_mul_f32 v[60:61], v[132:133], v[60:61]
	v_cmp_ge_i32_e64 s[0:1], v28, v12
	v_ashrrev_i32_e32 v29, 31, v28
	v_mov_b32_e32 v140, v139
	v_cndmask_b32_e64 v132, 0, v60, s[0:1]
	v_cmp_ge_i32_e64 s[0:1], v161, v12
	v_lshlrev_b64 v[124:125], 1, v[28:29]
	v_add_u32_e32 v29, 19, v0
	v_cndmask_b32_e64 v133, 0, v61, s[0:1]
	v_pk_mul_f32 v[60:61], v[122:123], v[116:117]
	v_cmp_ge_i32_e64 s[0:1], v164, v12
	v_pk_mul_f32 v[60:61], v[140:141], v[60:61]
	s_nop 0
	v_cndmask_b32_e64 v60, 0, v60, s[0:1]
	v_cmp_ge_i32_e64 s[0:1], v29, v12
	s_nop 1
	v_cndmask_b32_e64 v61, 0, v61, s[0:1]
	v_lshl_add_u64 v[126:127], v[112:113], 0, v[124:125]
	global_load_dwordx2 v[144:145], v[126:127], off offset:1536
	v_lshl_add_u64 v[126:127], v[130:131], 0, v[124:125]
	v_cvt_pk_bf16_f32 v61, v133, v61
	v_cvt_pk_bf16_f32 v60, v132, v60
	global_load_dwordx2 v[136:137], v[126:127], off offset:1536
	v_lshl_add_u64 v[126:127], v[148:149], 0, v[124:125]
	v_lshl_add_u64 v[124:125], v[150:151], 0, v[124:125]
	ds_write_b64 v174, v[60:61] offset:8480
	global_load_dwordx2 v[126:127], v[126:127], off offset:1536
	v_add_u32_e32 v166, 33, v0
	global_load_dwordx2 v[124:125], v[124:125], off offset:1536
	ds_read_b128 v[138:141], v1 offset:18560
	ds_read_b128 v[212:215], v1 offset:18304
	v_mad_u32_u24 v153, v12, s21, v230
	v_mad_u32_u24 v154, v12, s21, v232
	s_waitcnt lgkmcnt(1)
	v_sub_f32_e32 v60, v165, v138
	v_mul_f32_e32 v60, 0x3fb8aa3b, v60
	v_exp_f32_e32 v138, v60
	v_sub_f32_e32 v60, v165, v139
	v_mul_f32_e32 v60, 0x3fb8aa3b, v60
	v_exp_f32_e32 v146, v60
	v_sub_f32_e32 v60, v165, v140
	v_mul_f32_e32 v60, 0x3fb8aa3b, v60
	v_exp_f32_e32 v139, v60
	v_sub_f32_e32 v60, v165, v141
	v_mul_f32_e32 v60, 0x3fb8aa3b, v60
	v_exp_f32_e32 v147, v60
	v_add_u32_e32 v60, 32, v0
	v_pk_mul_f32 v[138:139], v[210:211], v[138:139]
	s_waitcnt lgkmcnt(0)
	v_mov_b32_e32 v210, v212
	v_mov_b32_e32 v211, v214
	v_pk_mul_f32 v[138:139], v[210:211], v[138:139]
	v_cmp_ge_i32_e64 s[0:1], v60, v12
	v_ashrrev_i32_e32 v61, 31, v60
	v_pk_mul_f32 v[118:119], v[118:119], v[146:147]
	v_cndmask_b32_e64 v138, 0, v138, s[0:1]
	v_cmp_ge_i32_e64 s[0:1], v163, v12
	v_mov_b32_e32 v214, v213
	v_lshlrev_b64 v[116:117], 1, v[60:61]
	v_cndmask_b32_e64 v139, 0, v139, s[0:1]
	v_add_u32_e32 v61, 35, v0
	v_pk_mul_f32 v[118:119], v[214:215], v[118:119]
	v_cmp_ge_i32_e64 s[0:1], v166, v12
	s_nop 1
	v_cndmask_b32_e64 v118, 0, v118, s[0:1]
	v_cmp_ge_i32_e64 s[0:1], v61, v12
	s_nop 1
	v_cndmask_b32_e64 v119, 0, v119, s[0:1]
	v_lshl_add_u64 v[122:123], v[112:113], 0, v[116:117]
	global_load_dwordx2 v[140:141], v[122:123], off offset:1536
	v_lshl_add_u64 v[122:123], v[130:131], 0, v[116:117]
	v_cvt_pk_bf16_f32 v119, v139, v119
	v_cvt_pk_bf16_f32 v118, v138, v118
	global_load_dwordx2 v[132:133], v[122:123], off offset:1536
	v_lshl_add_u64 v[122:123], v[148:149], 0, v[116:117]
	v_lshl_add_u64 v[116:117], v[150:151], 0, v[116:117]
	ds_write_b64 v174, v[118:119] offset:8512
	global_load_dwordx2 v[122:123], v[122:123], off offset:1536
	v_add_u32_e32 v146, 48, v0
	global_load_dwordx2 v[116:117], v[116:117], off offset:1536
	ds_read_b128 v[210:213], v1 offset:18624
	ds_read_b128 v[244:247], v1 offset:18368
	v_ashrrev_i32_e32 v147, 31, v146
	v_cmp_ge_i32_e64 s[0:1], v146, v12
	s_waitcnt lgkmcnt(1)
	v_sub_f32_e32 v118, v165, v210
	v_mul_f32_e32 v118, 0x3fb8aa3b, v118
	v_exp_f32_e32 v210, v118
	v_sub_f32_e32 v118, v165, v211
	v_mul_f32_e32 v118, 0x3fb8aa3b, v118
	v_exp_f32_e32 v214, v118
	v_sub_f32_e32 v118, v165, v212
	v_mul_f32_e32 v118, 0x3fb8aa3b, v118
	v_exp_f32_e32 v211, v118
	v_sub_f32_e32 v118, v165, v213
	v_lshlrev_b64 v[212:213], 1, v[146:147]
	v_mul_f32_e32 v118, 0x3fb8aa3b, v118
	v_lshl_add_u64 v[112:113], v[112:113], 0, v[212:213]
	v_exp_f32_e32 v215, v118
	global_load_dwordx2 v[138:139], v[112:113], off offset:1536
	v_lshl_add_u64 v[112:113], v[130:131], 0, v[212:213]
	global_load_dwordx2 v[130:131], v[112:113], off offset:1536
	v_lshl_add_u64 v[112:113], v[148:149], 0, v[212:213]
	global_load_dwordx2 v[118:119], v[112:113], off offset:1536
	v_lshl_add_u64 v[112:113], v[150:151], 0, v[212:213]
	v_pk_mul_f32 v[148:149], v[208:209], v[210:211]
	s_waitcnt lgkmcnt(0)
	v_mov_b32_e32 v150, v244
	v_mov_b32_e32 v151, v246
	v_add_u32_e32 v165, 50, v0
	v_pk_mul_f32 v[148:149], v[150:151], v[148:149]
	v_pk_mul_f32 v[114:115], v[114:115], v[214:215]
	v_cndmask_b32_e64 v150, 0, v148, s[0:1]
	v_cmp_ge_i32_e64 s[0:1], v165, v12
	v_add_u32_e32 v148, 49, v0
	v_mov_b32_e32 v246, v245
	v_cndmask_b32_e64 v149, 0, v149, s[0:1]
	v_add_u32_e32 v147, 51, v0
	v_pk_mul_f32 v[114:115], v[246:247], v[114:115]
	v_cmp_ge_i32_e64 s[0:1], v148, v12
	s_nop 1
	v_cndmask_b32_e64 v114, 0, v114, s[0:1]
	v_cmp_ge_i32_e64 s[0:1], v147, v12
	s_nop 1
	v_cndmask_b32_e64 v115, 0, v115, s[0:1]
	v_cvt_pk_bf16_f32 v115, v149, v115
	v_cvt_pk_bf16_f32 v114, v150, v114
	ds_write_b64 v174, v[114:115] offset:8544
	ds_read_b32 v149, v157 offset:18496
	global_load_dwordx2 v[112:113], v[112:113], off offset:1536
	ds_read_b128 v[208:211], v1 offset:18432
	ds_read_b128 v[212:215], v1 offset:18176
	v_cmp_ge_i32_e64 s[0:1], v0, v167
	v_add_u32_e32 v174, v162, v152
	s_waitcnt lgkmcnt(1)
	v_sub_f32_e32 v115, v149, v209
	v_mul_f32_e32 v115, 0x3fb8aa3b, v115
	v_sub_f32_e32 v114, v149, v208
	v_exp_f32_e32 v150, v115
	v_sub_f32_e32 v115, v149, v210
	v_mul_f32_e32 v114, 0x3fb8aa3b, v114
	v_mul_f32_e32 v115, 0x3fb8aa3b, v115
	v_exp_f32_e32 v114, v114
	v_exp_f32_e32 v115, v115
	v_sub_f32_e32 v151, v149, v211
	v_mul_f32_e32 v151, 0x3fb8aa3b, v151
	v_exp_f32_e32 v151, v151
	v_pk_mul_f32 v[114:115], v[216:217], v[114:115]
	s_waitcnt lgkmcnt(0)
	v_mov_b32_e32 v208, v212
	v_mov_b32_e32 v209, v214
	v_pk_mul_f32 v[114:115], v[208:209], v[114:115]
	v_pk_mul_f32 v[62:63], v[62:63], v[150:151]
	v_cndmask_b32_e64 v114, 0, v114, s[0:1]
	v_cmp_ge_i32_e64 s[0:1], v158, v167
	v_mov_b32_e32 v214, v213
	v_pk_mul_f32 v[62:63], v[214:215], v[62:63]
	v_cndmask_b32_e64 v115, 0, v115, s[0:1]
	v_cmp_ge_i32_e64 s[0:1], v160, v167
	s_nop 1
	v_cndmask_b32_e64 v62, 0, v62, s[0:1]
	v_cmp_ge_i32_e64 s[0:1], v159, v167
	s_nop 1
	v_cndmask_b32_e64 v63, 0, v63, s[0:1]
	v_cvt_pk_bf16_f32 v63, v115, v63
	v_cvt_pk_bf16_f32 v62, v114, v62
	ds_write_b64 v174, v[62:63] offset:8448
	ds_read_b128 v[208:211], v1 offset:18496
	ds_read_b128 v[212:215], v1 offset:18240
	v_cmp_ge_i32_e64 s[0:1], v161, v167
	s_waitcnt lgkmcnt(1)
	v_sub_f32_e32 v63, v149, v209
	v_mul_f32_e32 v63, 0x3fb8aa3b, v63
	v_sub_f32_e32 v62, v149, v208
	v_exp_f32_e32 v114, v63
	v_sub_f32_e32 v63, v149, v210
	v_mul_f32_e32 v62, 0x3fb8aa3b, v62
	v_mul_f32_e32 v63, 0x3fb8aa3b, v63
	v_sub_f32_e32 v115, v149, v211
	v_exp_f32_e32 v62, v62
	v_exp_f32_e32 v63, v63
	v_mul_f32_e32 v115, 0x3fb8aa3b, v115
	v_exp_f32_e32 v115, v115
	s_waitcnt lgkmcnt(0)
	v_mov_b32_e32 v150, v212
	v_pk_mul_f32 v[62:63], v[218:219], v[62:63]
	v_mov_b32_e32 v151, v214
	v_pk_mul_f32 v[62:63], v[150:151], v[62:63]
	v_pk_mul_f32 v[58:59], v[58:59], v[114:115]
	v_mov_b32_e32 v214, v213
	v_cndmask_b32_e64 v63, 0, v63, s[0:1]
	v_pk_mul_f32 v[58:59], v[214:215], v[58:59]
	v_cmp_ge_i32_e64 s[0:1], v164, v167
	v_cndmask_b32_e64 v62, v62, 0, vcc
	s_nop 0
	v_cndmask_b32_e64 v58, 0, v58, s[0:1]
	v_cmp_ge_i32_e64 s[0:1], v29, v167
	s_nop 1
	v_cndmask_b32_e64 v59, 0, v59, s[0:1]
	v_cvt_pk_bf16_f32 v59, v63, v59
	v_cvt_pk_bf16_f32 v58, v62, v58
	ds_write_b64 v174, v[58:59] offset:8480
	ds_read_b128 v[208:211], v1 offset:18560
	ds_read_b128 v[212:215], v1 offset:18304
	v_cmp_ge_i32_e64 s[0:1], v60, v167
	s_waitcnt lgkmcnt(1)
	v_sub_f32_e32 v59, v149, v209
	v_mul_f32_e32 v59, 0x3fb8aa3b, v59
	v_sub_f32_e32 v58, v149, v208
	v_exp_f32_e32 v62, v59
	v_sub_f32_e32 v59, v149, v210
	v_mul_f32_e32 v58, 0x3fb8aa3b, v58
	v_mul_f32_e32 v59, 0x3fb8aa3b, v59
	v_exp_f32_e32 v58, v58
	v_exp_f32_e32 v59, v59
	v_sub_f32_e32 v63, v149, v211
	v_mul_f32_e32 v63, 0x3fb8aa3b, v63
	v_exp_f32_e32 v63, v63
	v_pk_mul_f32 v[56:57], v[56:57], v[58:59]
	s_waitcnt lgkmcnt(0)
	v_mov_b32_e32 v58, v212
	v_mov_b32_e32 v59, v214
	v_pk_mul_f32 v[56:57], v[58:59], v[56:57]
	v_pk_mul_f32 v[46:47], v[46:47], v[62:63]
	v_cndmask_b32_e64 v56, 0, v56, s[0:1]
	v_cmp_ge_i32_e64 s[0:1], v163, v167
	v_mov_b32_e32 v214, v213
	v_pk_mul_f32 v[46:47], v[214:215], v[46:47]
	v_cndmask_b32_e64 v57, 0, v57, s[0:1]
	v_cmp_ge_i32_e64 s[0:1], v166, v167
	s_nop 1
	v_cndmask_b32_e64 v46, 0, v46, s[0:1]
	v_cmp_ge_i32_e64 s[0:1], v61, v167
	s_nop 1
	v_cndmask_b32_e64 v47, 0, v47, s[0:1]
	v_cvt_pk_bf16_f32 v47, v57, v47
	v_cvt_pk_bf16_f32 v46, v56, v46
	ds_write_b64 v174, v[46:47] offset:8512
	ds_read_b128 v[56:59], v1 offset:18624
	ds_read_b128 v[208:211], v1 offset:18368
	v_cmp_ge_i32_e64 s[0:1], v146, v167
	v_add_u32_e32 v63, v162, v153
	s_waitcnt lgkmcnt(1)
	v_sub_f32_e32 v47, v149, v57
	v_mul_f32_e32 v47, 0x3fb8aa3b, v47
	v_sub_f32_e32 v46, v149, v56
	v_exp_f32_e32 v56, v47
	v_sub_f32_e32 v47, v149, v58
	v_mul_f32_e32 v46, 0x3fb8aa3b, v46
	v_mul_f32_e32 v47, 0x3fb8aa3b, v47
	v_exp_f32_e32 v46, v46
	v_exp_f32_e32 v47, v47
	v_sub_f32_e32 v57, v149, v59
	v_mul_f32_e32 v57, 0x3fb8aa3b, v57
	v_exp_f32_e32 v57, v57
	v_pk_mul_f32 v[44:45], v[44:45], v[46:47]
	s_waitcnt lgkmcnt(0)
	v_mov_b32_e32 v46, v208
	v_mov_b32_e32 v47, v210
	v_pk_mul_f32 v[44:45], v[46:47], v[44:45]
	v_pk_mul_f32 v[38:39], v[38:39], v[56:57]
	v_cndmask_b32_e64 v44, 0, v44, s[0:1]
	v_cmp_ge_i32_e64 s[0:1], v165, v167
	v_mov_b32_e32 v210, v209
	v_pk_mul_f32 v[38:39], v[210:211], v[38:39]
	v_cndmask_b32_e64 v45, 0, v45, s[0:1]
	v_cmp_ge_i32_e64 s[0:1], v148, v167
	s_nop 1
	v_cndmask_b32_e64 v38, 0, v38, s[0:1]
	v_cmp_ge_i32_e64 s[0:1], v147, v167
	s_nop 1
	v_cndmask_b32_e64 v39, 0, v39, s[0:1]
	v_cvt_pk_bf16_f32 v39, v45, v39
	v_cvt_pk_bf16_f32 v38, v44, v38
	ds_write_b64 v174, v[38:39] offset:8544
	ds_read_b32 v62, v157 offset:18560
	ds_read_b128 v[44:47], v1 offset:18432
	ds_read_b128 v[56:59], v1 offset:18176
	v_cmp_ge_i32_e64 s[0:1], v0, v14
	v_add_u32_e32 v167, v1, v152
	v_add_u32_e32 v174, v1, v153
	s_waitcnt lgkmcnt(1)
	v_sub_f32_e32 v39, v62, v45
	v_mul_f32_e32 v39, 0x3fb8aa3b, v39
	v_sub_f32_e32 v38, v62, v44
	v_exp_f32_e32 v44, v39
	v_sub_f32_e32 v39, v62, v46
	v_mul_f32_e32 v38, 0x3fb8aa3b, v38
	v_mul_f32_e32 v39, 0x3fb8aa3b, v39
	v_exp_f32_e32 v38, v38
	v_exp_f32_e32 v39, v39
	s_nop 0
	v_pk_mul_f32 v[36:37], v[36:37], v[38:39]
	s_waitcnt lgkmcnt(0)
	v_mov_b32_e32 v38, v56
	v_mov_b32_e32 v39, v58
	v_pk_mul_f32 v[36:37], v[38:39], v[36:37]
	v_sub_f32_e32 v38, v62, v47
	v_mul_f32_e32 v38, 0x3fb8aa3b, v38
	v_exp_f32_e32 v45, v38
	v_cndmask_b32_e64 v36, 0, v36, s[0:1]
	v_cmp_ge_i32_e64 s[0:1], v158, v14
	v_mov_b32_e32 v58, v57
	v_pk_mul_f32 v[30:31], v[30:31], v[44:45]
	v_cndmask_b32_e64 v37, 0, v37, s[0:1]
	v_pk_mul_f32 v[30:31], v[58:59], v[30:31]
	v_cmp_ge_i32_e64 s[0:1], v160, v14
	s_nop 1
	v_cndmask_b32_e64 v30, 0, v30, s[0:1]
	v_cmp_ge_i32_e64 s[0:1], v159, v14
	s_nop 1
	v_cndmask_b32_e64 v31, 0, v31, s[0:1]
	v_cvt_pk_bf16_f32 v31, v37, v31
	v_cvt_pk_bf16_f32 v30, v36, v30
	ds_write_b64 v63, v[30:31] offset:8448
	ds_read_b128 v[36:39], v1 offset:18496
	ds_read_b128 v[44:47], v1 offset:18240
	v_cmp_ge_i32_e64 s[0:1], v28, v14
	s_waitcnt lgkmcnt(1)
	v_sub_f32_e32 v31, v62, v37
	v_mul_f32_e32 v31, 0x3fb8aa3b, v31
	v_sub_f32_e32 v30, v62, v36
	v_exp_f32_e32 v36, v31
	v_sub_f32_e32 v31, v62, v38
	v_mul_f32_e32 v30, 0x3fb8aa3b, v30
	v_mul_f32_e32 v31, 0x3fb8aa3b, v31
	v_exp_f32_e32 v30, v30
	v_exp_f32_e32 v31, v31
	v_sub_f32_e32 v37, v62, v39
	v_mul_f32_e32 v37, 0x3fb8aa3b, v37
	v_exp_f32_e32 v37, v37
	v_pk_mul_f32 v[30:31], v[220:221], v[30:31]
	s_waitcnt lgkmcnt(0)
	v_mov_b32_e32 v38, v44
	v_mov_b32_e32 v39, v46
	v_pk_mul_f32 v[30:31], v[38:39], v[30:31]
	v_pk_mul_f32 v[26:27], v[26:27], v[36:37]
	v_cndmask_b32_e64 v30, 0, v30, s[0:1]
	v_cmp_ge_i32_e64 s[0:1], v161, v14
	v_mov_b32_e32 v46, v45
	v_pk_mul_f32 v[26:27], v[46:47], v[26:27]
	v_cndmask_b32_e64 v31, 0, v31, s[0:1]
	v_cmp_ge_i32_e64 s[0:1], v164, v14
	s_nop 1
	v_cndmask_b32_e64 v26, 0, v26, s[0:1]
	v_cmp_ge_i32_e64 s[0:1], v29, v14
	s_nop 1
	v_cndmask_b32_e64 v27, 0, v27, s[0:1]
	v_cvt_pk_bf16_f32 v27, v31, v27
	v_cvt_pk_bf16_f32 v26, v30, v26
	ds_write_b64 v63, v[26:27] offset:8480
	ds_read_b128 v[36:39], v1 offset:18560
	ds_read_b128 v[44:47], v1 offset:18304
	v_cmp_ge_i32_e64 s[0:1], v163, v14
	s_waitcnt lgkmcnt(1)
	v_sub_f32_e32 v27, v62, v37
	v_mul_f32_e32 v27, 0x3fb8aa3b, v27
	v_sub_f32_e32 v26, v62, v36
	v_exp_f32_e32 v30, v27
	v_sub_f32_e32 v27, v62, v38
	v_mul_f32_e32 v26, 0x3fb8aa3b, v26
	v_mul_f32_e32 v27, 0x3fb8aa3b, v27
	v_sub_f32_e32 v31, v62, v39
	v_exp_f32_e32 v26, v26
	v_exp_f32_e32 v27, v27
	v_mul_f32_e32 v31, 0x3fb8aa3b, v31
	v_exp_f32_e32 v31, v31
	v_pk_mul_f32 v[24:25], v[24:25], v[26:27]
	s_waitcnt lgkmcnt(0)
	v_mov_b32_e32 v26, v44
	v_mov_b32_e32 v27, v46
	v_pk_mul_f32 v[24:25], v[26:27], v[24:25]
	v_pk_mul_f32 v[22:23], v[22:23], v[30:31]
	v_mov_b32_e32 v46, v45
	v_cndmask_b32_e64 v25, 0, v25, s[0:1]
	v_pk_mul_f32 v[22:23], v[46:47], v[22:23]
	v_cmp_ge_i32_e64 s[0:1], v166, v14
	v_cndmask_b32_e64 v24, v24, 0, vcc
	s_nop 0
	v_cndmask_b32_e64 v22, 0, v22, s[0:1]
	v_cmp_ge_i32_e64 s[0:1], v61, v14
	s_nop 1
	v_cndmask_b32_e64 v23, 0, v23, s[0:1]
	v_cvt_pk_bf16_f32 v23, v25, v23
	v_cvt_pk_bf16_f32 v22, v24, v22
	ds_write_b64 v63, v[22:23] offset:8512
	ds_read_b128 v[22:25], v1 offset:18624
	ds_read_b128 v[36:39], v1 offset:18368
	v_cmp_ge_i32_e64 s[0:1], v146, v14
	s_waitcnt lgkmcnt(1)
	v_sub_f32_e32 v23, v62, v23
	v_mul_f32_e32 v23, 0x3fb8aa3b, v23
	v_sub_f32_e32 v22, v62, v22
	v_exp_f32_e32 v26, v23
	v_sub_f32_e32 v23, v62, v24
	v_mul_f32_e32 v22, 0x3fb8aa3b, v22
	v_mul_f32_e32 v23, 0x3fb8aa3b, v23
	v_exp_f32_e32 v22, v22
	v_exp_f32_e32 v23, v23
	v_sub_f32_e32 v24, v62, v25
	v_mul_f32_e32 v24, 0x3fb8aa3b, v24
	v_exp_f32_e32 v27, v24
	v_pk_mul_f32 v[20:21], v[20:21], v[22:23]
	s_waitcnt lgkmcnt(0)
	v_mov_b32_e32 v22, v36
	v_mov_b32_e32 v23, v38
	v_pk_mul_f32 v[20:21], v[22:23], v[20:21]
	v_pk_mul_f32 v[18:19], v[18:19], v[26:27]
	v_cndmask_b32_e64 v20, 0, v20, s[0:1]
	v_cmp_ge_i32_e64 s[0:1], v165, v14
	v_mov_b32_e32 v38, v37
	v_pk_mul_f32 v[18:19], v[38:39], v[18:19]
	v_cndmask_b32_e64 v21, 0, v21, s[0:1]
	v_cmp_ge_i32_e64 s[0:1], v148, v14
	s_nop 1
	v_cndmask_b32_e64 v18, 0, v18, s[0:1]
	v_cmp_ge_i32_e64 s[0:1], v147, v14
	s_nop 1
	v_cndmask_b32_e64 v14, 0, v19, s[0:1]
	v_cvt_pk_bf16_f32 v19, v21, v14
	v_cvt_pk_bf16_f32 v18, v20, v18
	ds_write_b64 v63, v[18:19] offset:8544
	ds_read_b32 v36, v157 offset:18624
	ds_read_b128 v[18:21], v1 offset:18432
	ds_read_b128 v[22:25], v1 offset:18176
	v_cmp_ge_i32_e64 s[0:1], v0, v156
	v_add_u32_e32 v37, v162, v154
	v_add_u32_e32 v154, v1, v154
	s_waitcnt lgkmcnt(1)
	v_sub_f32_e32 v14, v36, v18
	v_mul_f32_e32 v14, 0x3fb8aa3b, v14
	v_exp_f32_e32 v18, v14
	v_sub_f32_e32 v14, v36, v19
	v_mul_f32_e32 v14, 0x3fb8aa3b, v14
	v_exp_f32_e32 v26, v14
	v_sub_f32_e32 v14, v36, v20
	v_mul_f32_e32 v14, 0x3fb8aa3b, v14
	v_exp_f32_e32 v19, v14
	v_sub_f32_e32 v14, v36, v21
	v_mul_f32_e32 v14, 0x3fb8aa3b, v14
	v_exp_f32_e32 v27, v14
	v_pk_mul_f32 v[18:19], v[222:223], v[18:19]
	s_waitcnt lgkmcnt(0)
	v_mov_b32_e32 v30, v22
	v_mov_b32_e32 v31, v24
	v_pk_mul_f32 v[18:19], v[30:31], v[18:19]
	v_mov_b32_e32 v14, v13
	v_cndmask_b32_e64 v0, 0, v18, s[0:1]
	v_cmp_ge_i32_e64 s[0:1], v158, v156
	v_pk_mul_f32 v[14:15], v[14:15], v[26:27]
	v_mov_b32_e32 v24, v23
	v_cndmask_b32_e64 v18, 0, v19, s[0:1]
	v_pk_mul_f32 v[14:15], v[24:25], v[14:15]
	v_cmp_ge_i32_e64 s[0:1], v160, v156
	s_nop 1
	v_cndmask_b32_e64 v13, 0, v14, s[0:1]
	v_cmp_ge_i32_e64 s[0:1], v159, v156
	s_nop 1
	v_cndmask_b32_e64 v14, 0, v15, s[0:1]
	v_cvt_pk_bf16_f32 v15, v18, v14
	v_cvt_pk_bf16_f32 v14, v0, v13
	ds_write_b64 v37, v[14:15] offset:8448
	ds_read_b128 v[18:21], v1 offset:18496
	ds_read_b128 v[22:25], v1 offset:18240
	v_cmp_ge_i32_e64 s[0:1], v28, v156
	s_waitcnt lgkmcnt(1)
	v_sub_f32_e32 v0, v36, v18
	v_mul_f32_e32 v0, 0x3fb8aa3b, v0
	v_exp_f32_e32 v14, v0
	v_sub_f32_e32 v0, v36, v19
	v_mul_f32_e32 v0, 0x3fb8aa3b, v0
	v_exp_f32_e32 v18, v0
	v_sub_f32_e32 v0, v36, v20
	v_mul_f32_e32 v0, 0x3fb8aa3b, v0
	v_exp_f32_e32 v15, v0
	v_sub_f32_e32 v0, v36, v21
	v_mul_f32_e32 v0, 0x3fb8aa3b, v0
	v_exp_f32_e32 v19, v0
	v_pk_mul_f32 v[14:15], v[16:17], v[14:15]
	s_waitcnt lgkmcnt(0)
	v_mov_b32_e32 v16, v22
	v_mov_b32_e32 v17, v24
	v_pk_mul_f32 v[14:15], v[16:17], v[14:15]
	v_pk_mul_f32 v[10:11], v[10:11], v[18:19]
	v_cndmask_b32_e64 v0, 0, v14, s[0:1]
	v_cmp_ge_i32_e64 s[0:1], v161, v156
	v_mov_b32_e32 v24, v23
	v_pk_mul_f32 v[10:11], v[24:25], v[10:11]
	v_cndmask_b32_e64 v13, 0, v15, s[0:1]
	v_cmp_ge_i32_e64 s[0:1], v164, v156
	s_nop 1
	v_cndmask_b32_e64 v10, 0, v10, s[0:1]
	v_cmp_ge_i32_e64 s[0:1], v29, v156
	s_nop 1
	v_cndmask_b32_e64 v11, 0, v11, s[0:1]
	v_cvt_pk_bf16_f32 v11, v13, v11
	v_cvt_pk_bf16_f32 v10, v0, v10
	ds_write_b64 v37, v[10:11] offset:8480
	ds_read_b128 v[14:17], v1 offset:18560
	ds_read_b128 v[18:21], v1 offset:18304
	v_cmp_ge_i32_e64 s[0:1], v60, v156
	s_waitcnt lgkmcnt(1)
	v_sub_f32_e32 v0, v36, v14
	v_mul_f32_e32 v0, 0x3fb8aa3b, v0
	v_exp_f32_e32 v10, v0
	v_sub_f32_e32 v0, v36, v15
	v_mul_f32_e32 v0, 0x3fb8aa3b, v0
	v_exp_f32_e32 v14, v0
	v_sub_f32_e32 v0, v36, v16
	v_mul_f32_e32 v0, 0x3fb8aa3b, v0
	v_exp_f32_e32 v11, v0
	v_sub_f32_e32 v0, v36, v17
	v_mul_f32_e32 v0, 0x3fb8aa3b, v0
	v_exp_f32_e32 v15, v0
	v_pk_mul_f32 v[8:9], v[8:9], v[10:11]
	s_waitcnt lgkmcnt(0)
	v_mov_b32_e32 v10, v18
	v_mov_b32_e32 v11, v20
	v_pk_mul_f32 v[8:9], v[10:11], v[8:9]
	v_pk_mul_f32 v[6:7], v[6:7], v[14:15]
	v_cndmask_b32_e64 v0, 0, v8, s[0:1]
	v_cmp_ge_i32_e64 s[0:1], v163, v156
	v_mov_b32_e32 v20, v19
	v_pk_mul_f32 v[6:7], v[20:21], v[6:7]
	v_cndmask_b32_e64 v8, 0, v9, s[0:1]
	v_cmp_ge_i32_e64 s[0:1], v166, v156
	s_nop 1
	v_cndmask_b32_e64 v6, 0, v6, s[0:1]
	v_cmp_ge_i32_e64 s[0:1], v61, v156
	s_nop 1
	v_cndmask_b32_e64 v7, 0, v7, s[0:1]
	v_cvt_pk_bf16_f32 v7, v8, v7
	v_cvt_pk_bf16_f32 v6, v0, v6
	ds_write_b64 v37, v[6:7] offset:8512
	ds_read_b128 v[6:9], v1 offset:18624
	ds_read_b128 v[14:17], v1 offset:18368
	v_mad_u32_u24 v166, v12, s21, v1
	s_waitcnt lgkmcnt(1)
	v_sub_f32_e32 v0, v36, v6
	v_mul_f32_e32 v0, 0x3fb8aa3b, v0
	v_exp_f32_e32 v6, v0
	v_sub_f32_e32 v0, v36, v7
	v_mul_f32_e32 v0, 0x3fb8aa3b, v0
	v_exp_f32_e32 v10, v0
	v_sub_f32_e32 v0, v36, v8
	v_mul_f32_e32 v0, 0x3fb8aa3b, v0
	v_exp_f32_e32 v7, v0
	v_sub_f32_e32 v0, v36, v9
	v_mul_f32_e32 v0, 0x3fb8aa3b, v0
	v_exp_f32_e32 v11, v0
	v_pk_mul_f32 v[4:5], v[4:5], v[6:7]
	s_waitcnt lgkmcnt(0)
	v_mov_b32_e32 v6, v14
	v_mov_b32_e32 v7, v16
	v_pk_mul_f32 v[4:5], v[6:7], v[4:5]
	v_pk_mul_f32 v[2:3], v[2:3], v[10:11]
	v_cndmask_b32_e64 v0, v4, 0, vcc
	v_cmp_ge_i32_e32 vcc, v165, v156
	v_mov_b32_e32 v16, v15
	v_pk_mul_f32 v[2:3], v[16:17], v[2:3]
	v_cndmask_b32_e32 v4, 0, v5, vcc
	v_cmp_ge_i32_e32 vcc, v148, v156
	s_nop 1
	v_cndmask_b32_e32 v2, 0, v2, vcc
	v_cmp_ge_i32_e32 vcc, v147, v156
	s_nop 1
	v_cndmask_b32_e32 v3, 0, v3, vcc
	v_cvt_pk_bf16_f32 v3, v4, v3
	v_cvt_pk_bf16_f32 v2, v0, v2
	ds_write_b64 v37, v[2:3] offset:8544
	v_lshlrev_b32_e32 v0, 1, v12
	v_mul_lo_u32 v2, v155, s23
	v_add3_u32 v114, v191, v0, v2
	s_waitcnt lgkmcnt(0)
	ds_read_u16 v0, v114 offset:132
	ds_read_u16 v4, v114 offset:264
	ds_read_u16 v5, v114 offset:396
	ds_read_u16 v2, v114 offset:528
	ds_read_u16 v6, v114 offset:660
	ds_read_u16 v3, v114 offset:792
	ds_read_u16 v7, v114 offset:924
	ds_read_u16 v8, v114
	ds_read_u16 v9, v114 offset:32
	ds_read_u16 v10, v114 offset:164
	ds_read_u16 v11, v114 offset:296
	ds_read_u16 v20, v114 offset:428
	ds_read_u16 v21, v114 offset:560
	ds_read_u16 v22, v114 offset:692
	ds_read_u16 v23, v114 offset:824
	ds_read_u16 v24, v114 offset:956
	ds_read_u16 v36, v114 offset:64
	ds_read_u16 v37, v114 offset:196
	ds_read_u16 v38, v114 offset:328
	ds_read_u16 v39, v114 offset:460
	ds_read_u16 v115, v114 offset:592
	ds_read_u16 v155, v114 offset:724
	ds_read_u16 v156, v114 offset:856
	ds_read_u16 v157, v114 offset:988
	ds_read_u16 v158, v114 offset:96
	ds_read_u16 v159, v114 offset:228
	ds_read_u16 v160, v114 offset:360
	ds_read_u16 v161, v114 offset:492
	ds_read_u16 v162, v114 offset:624
	ds_read_u16 v163, v114 offset:756
	ds_read_u16 v164, v114 offset:888
	ds_read_u16 v165, v114 offset:1020
	ds_read_b128 v[16:19], v166 offset:8448
	ds_read_b128 v[150:153], v154 offset:8448
	ds_read_b128 v[56:59], v167 offset:8448
	ds_read_b128 v[146:149], v174 offset:8448
	s_waitcnt lgkmcnt(14)
	v_perm_b32 v3, v7, v3, s25
	v_perm_b32 v2, v6, v2, s25
	v_perm_b32 v1, v5, v4, s25
	v_perm_b32 v0, v0, v8, s25
	s_waitcnt lgkmcnt(3)
	s_nop 0
	v_mfma_f32_16x16x32_bf16 v[60:63], v[0:3], v[16:19], v[32:35]
	s_waitcnt lgkmcnt(1)
	v_mfma_f32_16x16x32_bf16 v[44:47], v[0:3], v[56:59], v[40:43]
	s_waitcnt lgkmcnt(0)
	v_mfma_f32_16x16x32_bf16 v[28:31], v[0:3], v[146:149], v[48:51]
	v_mfma_f32_16x16x32_bf16 v[12:15], v[0:3], v[150:153], v[52:55]
	v_perm_b32 v3, v24, v23, s25
	v_perm_b32 v2, v22, v21, s25
	v_perm_b32 v1, v20, v11, s25
	v_perm_b32 v0, v10, v9, s25
	s_nop 1
	v_mfma_f32_16x16x32_bf16 v[48:51], v[0:3], v[16:19], v[64:67]
	s_nop 2
	v_perm_b32 v67, v165, v164, s25
	v_perm_b32 v66, v163, v162, s25
	v_mfma_f32_16x16x32_bf16 v[40:43], v[0:3], v[56:59], v[68:71]
	v_perm_b32 v65, v161, v160, s25
	v_perm_b32 v64, v159, v158, s25
	v_mfma_f32_16x16x32_bf16 v[24:27], v[0:3], v[146:149], v[72:75]
	v_mfma_f32_16x16x32_bf16 v[8:11], v[0:3], v[150:153], v[76:79]
	v_perm_b32 v3, v157, v156, s25
	v_perm_b32 v2, v155, v115, s25
	v_perm_b32 v1, v39, v38, s25
	v_perm_b32 v0, v37, v36, s25
	v_mfma_f32_16x16x32_bf16 v[52:55], v[64:67], v[146:149], v[104:107]
	s_nop 0
	v_mfma_f32_16x16x32_bf16 v[36:39], v[0:3], v[16:19], v[80:83]
	v_mfma_f32_16x16x32_bf16 v[32:35], v[0:3], v[56:59], v[84:87]
	v_mfma_f32_16x16x32_bf16 v[20:23], v[0:3], v[146:149], v[88:91]
	v_mfma_f32_16x16x32_bf16 v[4:7], v[0:3], v[150:153], v[92:95]
	v_mfma_f32_16x16x32_bf16 v[0:3], v[64:67], v[16:19], v[96:99]
	v_mfma_f32_16x16x32_bf16 v[16:19], v[64:67], v[56:59], v[100:103]
	v_mfma_f32_16x16x32_bf16 v[56:59], v[64:67], v[150:153], v[108:111]
	s_nop 1
	ds_read_u16 v100, v114 offset:4224
	ds_read_u16 v104, v114 offset:4356
	ds_read_u16 v101, v114 offset:4488
	ds_read_u16 v105, v114 offset:4620
	ds_read_u16 v102, v114 offset:4752
	ds_read_u16 v106, v114 offset:4884
	ds_read_u16 v103, v114 offset:5016
	ds_read_u16 v107, v114 offset:5148
	ds_read_u16 v64, v114 offset:4256
	ds_read_u16 v65, v114 offset:4388
	ds_read_u16 v66, v114 offset:4520
	ds_read_u16 v67, v114 offset:4652
	ds_read_u16 v108, v114 offset:4784
	ds_read_u16 v109, v114 offset:4916
	ds_read_u16 v110, v114 offset:5048
	ds_read_u16 v111, v114 offset:5180
	ds_read_u16 v92, v114 offset:4288
	ds_read_u16 v93, v114 offset:4420
	ds_read_u16 v94, v114 offset:4552
	ds_read_u16 v95, v114 offset:4684
	ds_read_u16 v96, v114 offset:4816
	ds_read_u16 v97, v114 offset:4948
	ds_read_u16 v98, v114 offset:5080
	ds_read_u16 v99, v114 offset:5212
	ds_read_u16 v84, v114 offset:4320
	ds_read_u16 v85, v114 offset:4452
	ds_read_u16 v86, v114 offset:4584
	ds_read_u16 v87, v114 offset:4716
	ds_read_u16 v88, v114 offset:4848
	ds_read_u16 v89, v114 offset:4980
	ds_read_u16 v90, v114 offset:5112
	ds_read_u16 v91, v114 offset:5244
	ds_read_b128 v[68:71], v166 offset:8512
	ds_read_b128 v[72:75], v167 offset:8512
	ds_read_b128 v[76:79], v174 offset:8512
	ds_read_b128 v[80:83], v154 offset:8512
	s_waitcnt lgkmcnt(14)
	v_perm_b32 v103, v107, v103, s25
	v_perm_b32 v102, v106, v102, s25
	v_perm_b32 v101, v105, v101, s25
	v_perm_b32 v100, v104, v100, s25
	s_waitcnt lgkmcnt(4)
	v_perm_b32 v91, v91, v90, s25
	v_perm_b32 v90, v89, v88, s25
	s_waitcnt lgkmcnt(3)
	v_mfma_f32_16x16x32_bf16 v[104:107], v[100:103], v[68:71], v[60:63]
	v_perm_b32 v89, v87, v86, s25
	s_nop 1
	v_perm_b32 v63, v111, v110, s25
	v_perm_b32 v62, v109, v108, s25
	v_perm_b32 v61, v67, v66, s25
	v_perm_b32 v60, v65, v64, s25
	v_perm_b32 v88, v85, v84, s25
	s_waitcnt lgkmcnt(2)
	v_mfma_f32_16x16x32_bf16 v[44:47], v[100:103], v[72:75], v[44:47]
	s_waitcnt lgkmcnt(0)
	v_mfma_f32_16x16x32_bf16 v[64:67], v[60:63], v[68:71], v[48:51]
	s_nop 2
	v_perm_b32 v51, v99, v98, s25
	v_perm_b32 v50, v97, v96, s25
	v_perm_b32 v49, v95, v94, s25
	v_perm_b32 v48, v93, v92, s25
	v_mfma_f32_16x16x32_bf16 v[40:43], v[60:63], v[72:75], v[40:43]
	s_waitcnt lgkmcnt(1)
	v_mfma_f32_16x16x32_bf16 v[24:27], v[60:63], v[76:79], v[24:27]
	s_waitcnt lgkmcnt(0)
	v_mfma_f32_16x16x32_bf16 v[8:11], v[60:63], v[80:83], v[8:11]
	v_mfma_f32_16x16x32_bf16 v[60:63], v[48:51], v[68:71], v[36:39]
	v_mfma_f32_16x16x32_bf16 v[36:39], v[48:51], v[72:75], v[32:35]
	v_mfma_f32_16x16x32_bf16 v[20:23], v[48:51], v[76:79], v[20:23]
	s_nop 5
	v_mov_b32_e32 v84, v60
	v_mov_b32_e32 v85, v62
	v_mov_b32_e32 v62, v61
	v_mfma_f32_16x16x32_bf16 v[4:7], v[48:51], v[80:83], v[4:7]
	v_mfma_f32_16x16x32_bf16 v[48:51], v[88:91], v[68:71], v[0:3]
	s_waitcnt vmcnt(15)
	v_and_b32_e32 v68, 0xffff0000, v142
	v_and_b32_e32 v69, 0xffff0000, v143
	v_mfma_f32_16x16x32_bf16 v[0:3], v[88:91], v[80:83], v[56:59]
	s_nop 2
	v_mul_f32_e32 v59, 0xbfb8aa3b, v68
	v_exp_f32_e32 v59, v59
	v_mfma_f32_16x16x32_bf16 v[32:35], v[88:91], v[72:75], v[16:19]
	v_mov_b32_e32 v74, v190
	v_lshlrev_b32_e32 v57, 16, v143
	v_lshlrev_b32_e32 v56, 16, v142
	v_add_f32_e32 v59, 1.0, v59
	v_mfma_f32_16x16x32_bf16 v[16:19], v[88:91], v[76:79], v[52:55]
	v_mul_f32_e32 v58, 0xbfb8aa3b, v56
	v_rcp_f32_e32 v70, v59
	v_mul_f32_e32 v59, 0xbfb8aa3b, v57
	v_ashrrev_i32_e32 v53, 2, v74
	v_and_b32_e32 v52, 15, v74
	v_lshlrev_b32_e32 v53, 1, v53
	v_exp_f32_e32 v58, v58
	v_exp_f32_e32 v59, v59
	v_and_b32_e32 v53, -8, v53
	v_mul_u32_u24_e32 v52, 0x84, v52
	v_mfma_f32_16x16x32_bf16 v[28:31], v[100:103], v[76:79], v[28:31]
	v_xor_b32_e32 v54, 16, v224
	v_add_u32_e32 v55, 64, v168
	v_add3_u32 v77, v191, v53, v52
	v_cmp_lt_i32_e32 vcc, v54, v55
	ds_read2_b32 v[52:53], v77 offset1:1
	v_add_f32_e32 v58, 1.0, v58
	v_cndmask_b32_e32 v54, v224, v54, vcc
	v_add_f32_e32 v59, 1.0, v59
	v_lshlrev_b32_e32 v76, 2, v54
	v_xor_b32_e32 v54, 32, v224
	v_rcp_f32_e32 v58, v58
	v_rcp_f32_e32 v59, v59
	v_cmp_lt_i32_e32 vcc, v54, v55
	s_waitcnt lgkmcnt(0)
	v_lshlrev_b32_e32 v55, 16, v53
	v_mov_b32_e32 v72, v104
	v_cndmask_b32_e32 v54, v224, v54, vcc
	v_lshlrev_b32_e32 v75, 2, v54
	v_lshlrev_b32_e32 v54, 16, v52
	v_mov_b32_e32 v73, v106
	v_pk_fma_f32 v[54:55], v[188:189], v[54:55], v[72:73]
	v_pk_mul_f32 v[56:57], v[58:59], v[56:57]
	s_waitcnt vmcnt(11)
	v_and_b32_e32 v78, 0xffff0000, v144
	v_pk_mul_f32 v[54:55], v[56:57], v[54:55]
	v_mul_f32_e32 v56, 0xbfb8aa3b, v69
	v_exp_f32_e32 v56, v56
	v_mfma_f32_16x16x32_bf16 v[12:15], v[100:103], v[80:83], v[12:15]
	v_mul_f32_e32 v73, 0xbfb8aa3b, v78
	v_mov_b32_e32 v82, v64
	v_add_f32_e32 v56, 1.0, v56
	v_rcp_f32_e32 v71, v56
	v_exp_f32_e32 v73, v73
	v_and_b32_e32 v79, 0xffff0000, v145
	v_and_b32_e32 v53, 0xffff0000, v53
	v_pk_mul_f32 v[56:57], v[70:71], v[68:69]
	v_lshlrev_b32_e32 v71, 16, v145
	v_mul_f32_e32 v64, 0xbfb8aa3b, v71
	v_exp_f32_e32 v64, v64
	v_add_f32_e32 v73, 1.0, v73
	v_and_b32_e32 v52, 0xffff0000, v52
	v_mov_b32_e32 v106, v105
	v_add_f32_e32 v64, 1.0, v64
	v_lshlrev_b32_e32 v70, 16, v144
	v_rcp_f32_e32 v80, v73
	v_rcp_f32_e32 v73, v64
	v_mul_f32_e32 v64, 0xbfb8aa3b, v79
	v_pk_fma_f32 v[52:53], v[188:189], v[52:53], v[106:107]
	v_mul_f32_e32 v72, 0xbfb8aa3b, v70
	v_exp_f32_e32 v64, v64
	v_pk_mul_f32 v[58:59], v[56:57], v[52:53]
	v_exp_f32_e32 v72, v72
	v_pk_mul_f32 v[52:53], v[58:59], v[58:59]
	v_add_f32_e32 v64, 1.0, v64
	v_pk_fma_f32 v[68:69], v[54:55], v[54:55], v[52:53]
	ds_read2_b32 v[52:53], v77 offset0:8 offset1:9
	v_add_f32_e32 v72, 1.0, v72
	v_rcp_f32_e32 v81, v64
	v_rcp_f32_e32 v72, v72
	v_mov_b32_e32 v83, v66
	s_waitcnt lgkmcnt(0)
	v_lshlrev_b32_e32 v56, 16, v52
	v_lshlrev_b32_e32 v57, 16, v53
	v_and_b32_e32 v53, 0xffff0000, v53
	v_and_b32_e32 v52, 0xffff0000, v52
	v_mov_b32_e32 v66, v65
	v_pk_fma_f32 v[52:53], v[188:189], v[52:53], v[66:67]
	v_pk_mul_f32 v[64:65], v[80:81], v[78:79]
	v_pk_fma_f32 v[56:57], v[188:189], v[56:57], v[82:83]
	v_pk_mul_f32 v[70:71], v[72:73], v[70:71]
	v_pk_mul_f32 v[52:53], v[64:65], v[52:53]
	v_pk_mul_f32 v[56:57], v[70:71], v[56:57]
	v_pk_mul_f32 v[64:65], v[52:53], v[52:53]
	s_waitcnt vmcnt(7)
	v_and_b32_e32 v80, 0xffff0000, v140
	v_pk_fma_f32 v[66:67], v[56:57], v[56:57], v[64:65]
	ds_read2_b32 v[64:65], v77 offset0:16 offset1:17
	v_mul_f32_e32 v79, 0xbfb8aa3b, v80
	v_exp_f32_e32 v79, v79
	v_and_b32_e32 v81, 0xffff0000, v141
	v_mov_b32_e32 v86, v48
	s_waitcnt lgkmcnt(0)
	v_lshlrev_b32_e32 v71, 16, v65
	v_and_b32_e32 v73, 0xffff0000, v65
	v_lshlrev_b32_e32 v65, 16, v141
	v_mul_f32_e32 v60, 0xbfb8aa3b, v65
	v_exp_f32_e32 v60, v60
	v_and_b32_e32 v72, 0xffff0000, v64
	v_add_f32_e32 v79, 1.0, v79
	v_lshlrev_b32_e32 v70, 16, v64
	v_add_f32_e32 v60, 1.0, v60
	v_lshlrev_b32_e32 v64, 16, v140
	v_rcp_f32_e32 v82, v79
	v_rcp_f32_e32 v79, v60
	v_pk_fma_f32 v[60:61], v[188:189], v[72:73], v[62:63]
	v_mul_f32_e32 v62, 0xbfb8aa3b, v81
	v_mul_f32_e32 v78, 0xbfb8aa3b, v64
	v_exp_f32_e32 v62, v62
	v_exp_f32_e32 v78, v78
	v_pk_fma_f32 v[70:71], v[188:189], v[70:71], v[84:85]
	v_mov_b32_e32 v87, v50
	v_add_f32_e32 v62, 1.0, v62
	v_add_f32_e32 v78, 1.0, v78
	v_rcp_f32_e32 v83, v62
	v_rcp_f32_e32 v78, v78
	v_mov_b32_e32 v50, v49
	v_add_f32_e32 v66, v66, v67
	v_pk_mul_f32 v[62:63], v[82:83], v[80:81]
	v_pk_mul_f32 v[64:65], v[78:79], v[64:65]
	v_pk_mul_f32 v[60:61], v[62:63], v[60:61]
	v_pk_mul_f32 v[64:65], v[64:65], v[70:71]
	v_pk_mul_f32 v[62:63], v[60:61], v[60:61]
	s_waitcnt vmcnt(3)
	v_and_b32_e32 v82, 0xffff0000, v138
	v_pk_fma_f32 v[70:71], v[64:65], v[64:65], v[62:63]
	ds_read2_b32 v[62:63], v77 offset0:24 offset1:25
	v_mul_f32_e32 v81, 0xbfb8aa3b, v82
	v_exp_f32_e32 v81, v81
	v_and_b32_e32 v83, 0xffff0000, v139
	v_add_f32_e32 v67, v68, v69
	s_waitcnt lgkmcnt(0)
	v_lshlrev_b32_e32 v73, 16, v63
	v_and_b32_e32 v79, 0xffff0000, v63
	v_lshlrev_b32_e32 v63, 16, v139
	v_mul_f32_e32 v48, 0xbfb8aa3b, v63
	v_exp_f32_e32 v48, v48
	v_and_b32_e32 v78, 0xffff0000, v62
	v_add_f32_e32 v81, 1.0, v81
	v_lshlrev_b32_e32 v72, 16, v62
	v_add_f32_e32 v48, 1.0, v48
	v_lshlrev_b32_e32 v62, 16, v138
	v_rcp_f32_e32 v84, v81
	v_rcp_f32_e32 v81, v48
	v_pk_fma_f32 v[48:49], v[188:189], v[78:79], v[50:51]
	v_mul_f32_e32 v50, 0xbfb8aa3b, v83
	v_mul_f32_e32 v80, 0xbfb8aa3b, v62
	v_exp_f32_e32 v50, v50
	v_exp_f32_e32 v80, v80
	v_pk_fma_f32 v[72:73], v[188:189], v[72:73], v[86:87]
	v_add_f32_e32 v66, v67, v66
	v_add_f32_e32 v50, 1.0, v50
	v_add_f32_e32 v80, 1.0, v80
	v_rcp_f32_e32 v85, v50
	v_rcp_f32_e32 v80, v80
	v_add_f32_e32 v67, v70, v71
	v_add_f32_e32 v66, v66, v67
	v_pk_mul_f32 v[50:51], v[84:85], v[82:83]
	v_pk_mul_f32 v[62:63], v[80:81], v[62:63]
	v_pk_mul_f32 v[50:51], v[50:51], v[48:49]
	v_pk_mul_f32 v[62:63], v[62:63], v[72:73]
	v_pk_mul_f32 v[48:49], v[50:51], v[50:51]
	v_and_b32_e32 v72, 0xffff0000, v134
	v_pk_fma_f32 v[48:49], v[62:63], v[62:63], v[48:49]
	v_mul_f32_e32 v71, 0xbfb8aa3b, v72
	v_add_f32_e32 v48, v48, v49
	v_add_f32_e32 v48, v66, v48
	ds_bpermute_b32 v49, v76, v48
	v_mov_b32_e32 v82, v44
	v_exp_f32_e32 v71, v71
	v_and_b32_e32 v73, 0xffff0000, v135
	v_mov_b32_e32 v83, v46
	s_waitcnt lgkmcnt(0)
	v_add_f32_e32 v78, v48, v49
	v_add_u32_e32 v48, 0x840, v77
	ds_read2_b32 v[48:49], v48 offset1:1
	v_add_f32_e32 v71, 1.0, v71
	v_mov_b32_e32 v46, v45
	v_rcp_f32_e32 v80, v71
	v_mov_b32_e32 v84, v40
	s_waitcnt lgkmcnt(0)
	v_lshlrev_b32_e32 v67, 16, v49
	v_and_b32_e32 v69, 0xffff0000, v49
	v_lshlrev_b32_e32 v49, 16, v135
	v_mul_f32_e32 v44, 0xbfb8aa3b, v49
	v_exp_f32_e32 v44, v44
	v_and_b32_e32 v68, 0xffff0000, v48
	v_lshlrev_b32_e32 v66, 16, v48
	v_lshlrev_b32_e32 v48, 16, v134
	v_add_f32_e32 v44, 1.0, v44
	v_rcp_f32_e32 v71, v44
	v_pk_fma_f32 v[44:45], v[188:189], v[68:69], v[46:47]
	v_mul_f32_e32 v46, 0xbfb8aa3b, v73
	v_mul_f32_e32 v70, 0xbfb8aa3b, v48
	v_exp_f32_e32 v46, v46
	v_exp_f32_e32 v70, v70
	v_pk_fma_f32 v[66:67], v[188:189], v[66:67], v[82:83]
	v_mov_b32_e32 v85, v42
	v_add_f32_e32 v46, 1.0, v46
	v_add_f32_e32 v70, 1.0, v70
	v_rcp_f32_e32 v81, v46
	v_rcp_f32_e32 v70, v70
	v_mov_b32_e32 v42, v41
	v_mov_b32_e32 v86, v36
	v_pk_mul_f32 v[46:47], v[80:81], v[72:73]
	v_pk_mul_f32 v[48:49], v[70:71], v[48:49]
	v_pk_mul_f32 v[46:47], v[46:47], v[44:45]
	v_pk_mul_f32 v[48:49], v[48:49], v[66:67]
	v_pk_mul_f32 v[44:45], v[46:47], v[46:47]
	v_and_b32_e32 v80, 0xffff0000, v136
	v_pk_fma_f32 v[66:67], v[48:49], v[48:49], v[44:45]
	v_add_u32_e32 v44, 0x860, v77
	ds_read2_b32 v[44:45], v44 offset1:1
	v_mul_f32_e32 v73, 0xbfb8aa3b, v80
	v_exp_f32_e32 v73, v73
	v_and_b32_e32 v81, 0xffff0000, v137
	v_mov_b32_e32 v87, v38
	s_waitcnt lgkmcnt(0)
	v_lshlrev_b32_e32 v69, 16, v45
	v_and_b32_e32 v71, 0xffff0000, v45
	v_lshlrev_b32_e32 v45, 16, v137
	v_mul_f32_e32 v40, 0xbfb8aa3b, v45
	v_exp_f32_e32 v40, v40
	v_and_b32_e32 v70, 0xffff0000, v44
	v_add_f32_e32 v73, 1.0, v73
	v_lshlrev_b32_e32 v68, 16, v44
	v_add_f32_e32 v40, 1.0, v40
	v_lshlrev_b32_e32 v44, 16, v136
	v_rcp_f32_e32 v82, v73
	v_rcp_f32_e32 v73, v40
	v_pk_fma_f32 v[40:41], v[188:189], v[70:71], v[42:43]
	v_mul_f32_e32 v42, 0xbfb8aa3b, v81
	v_mul_f32_e32 v72, 0xbfb8aa3b, v44
	v_exp_f32_e32 v42, v42
	v_exp_f32_e32 v72, v72
	v_pk_fma_f32 v[68:69], v[188:189], v[68:69], v[84:85]
	v_mov_b32_e32 v38, v37
	v_add_f32_e32 v42, 1.0, v42
	v_add_f32_e32 v72, 1.0, v72
	v_rcp_f32_e32 v83, v42
	v_rcp_f32_e32 v72, v72
	v_mov_b32_e32 v88, v32
	v_mov_b32_e32 v89, v34
	v_pk_mul_f32 v[42:43], v[82:83], v[80:81]
	v_pk_mul_f32 v[44:45], v[72:73], v[44:45]
	v_pk_mul_f32 v[40:41], v[42:43], v[40:41]
	v_pk_mul_f32 v[44:45], v[44:45], v[68:69]
	v_pk_mul_f32 v[42:43], v[40:41], v[40:41]
	v_and_b32_e32 v82, 0xffff0000, v132
	v_pk_fma_f32 v[68:69], v[44:45], v[44:45], v[42:43]
	v_add_u32_e32 v42, 0x880, v77
	ds_read2_b32 v[42:43], v42 offset1:1
	v_mul_f32_e32 v81, 0xbfb8aa3b, v82
	v_exp_f32_e32 v81, v81
	v_and_b32_e32 v83, 0xffff0000, v133
	v_mov_b32_e32 v34, v33
	s_waitcnt lgkmcnt(0)
	v_lshlrev_b32_e32 v71, 16, v43
	v_and_b32_e32 v73, 0xffff0000, v43
	v_lshlrev_b32_e32 v43, 16, v133
	v_mul_f32_e32 v36, 0xbfb8aa3b, v43
	v_exp_f32_e32 v36, v36
	v_and_b32_e32 v72, 0xffff0000, v42
	v_add_f32_e32 v81, 1.0, v81
	v_lshlrev_b32_e32 v70, 16, v42
	v_add_f32_e32 v36, 1.0, v36
	v_lshlrev_b32_e32 v42, 16, v132
	v_rcp_f32_e32 v84, v81
	v_rcp_f32_e32 v81, v36
	v_pk_fma_f32 v[36:37], v[188:189], v[72:73], v[38:39]
	v_mul_f32_e32 v38, 0xbfb8aa3b, v83
	v_mul_f32_e32 v80, 0xbfb8aa3b, v42
	v_exp_f32_e32 v38, v38
	v_exp_f32_e32 v80, v80
	v_pk_fma_f32 v[70:71], v[188:189], v[70:71], v[86:87]
	v_add_f32_e32 v68, v68, v69
	v_add_f32_e32 v38, 1.0, v38
	v_add_f32_e32 v80, 1.0, v80
	v_rcp_f32_e32 v85, v38
	v_rcp_f32_e32 v80, v80
	v_add_f32_e32 v66, v66, v67
	v_add_f32_e32 v66, v66, v68
	v_pk_mul_f32 v[38:39], v[84:85], v[82:83]
	v_pk_mul_f32 v[42:43], v[80:81], v[42:43]
	v_pk_mul_f32 v[36:37], v[38:39], v[36:37]
	v_pk_mul_f32 v[42:43], v[42:43], v[70:71]
	v_pk_mul_f32 v[38:39], v[36:37], v[36:37]
	s_waitcnt vmcnt(2)
	v_and_b32_e32 v84, 0xffff0000, v130
	v_pk_fma_f32 v[70:71], v[42:43], v[42:43], v[38:39]
	v_add_u32_e32 v38, 0x8a0, v77
	ds_read2_b32 v[38:39], v38 offset1:1
	v_mul_f32_e32 v83, 0xbfb8aa3b, v84
	v_exp_f32_e32 v83, v83
	v_and_b32_e32 v85, 0xffff0000, v131
	v_add_f32_e32 v67, v70, v71
	s_waitcnt lgkmcnt(0)
	v_lshlrev_b32_e32 v73, 16, v39
	v_and_b32_e32 v81, 0xffff0000, v39
	v_lshlrev_b32_e32 v39, 16, v131
	v_mul_f32_e32 v32, 0xbfb8aa3b, v39
	v_exp_f32_e32 v32, v32
	v_and_b32_e32 v80, 0xffff0000, v38
	v_add_f32_e32 v83, 1.0, v83
	v_lshlrev_b32_e32 v72, 16, v38
	v_add_f32_e32 v32, 1.0, v32
	v_lshlrev_b32_e32 v38, 16, v130
	v_rcp_f32_e32 v86, v83
	v_rcp_f32_e32 v83, v32
	v_pk_fma_f32 v[32:33], v[188:189], v[80:81], v[34:35]
	v_mul_f32_e32 v34, 0xbfb8aa3b, v85
	v_mul_f32_e32 v82, 0xbfb8aa3b, v38
	v_exp_f32_e32 v34, v34
	v_exp_f32_e32 v82, v82
	v_pk_fma_f32 v[72:73], v[188:189], v[72:73], v[88:89]
	v_add_f32_e32 v66, v66, v67
	v_add_f32_e32 v34, 1.0, v34
	v_add_f32_e32 v82, 1.0, v82
	v_rcp_f32_e32 v87, v34
	v_rcp_f32_e32 v82, v82
	v_mov_b32_e32 v88, v20
	v_mov_b32_e32 v89, v22
	v_pk_mul_f32 v[34:35], v[86:87], v[84:85]
	v_pk_mul_f32 v[38:39], v[82:83], v[38:39]
	v_pk_mul_f32 v[34:35], v[34:35], v[32:33]
	v_pk_mul_f32 v[38:39], v[38:39], v[72:73]
	v_pk_mul_f32 v[32:33], v[34:35], v[34:35]
	v_and_b32_e32 v72, 0xffff0000, v128
	v_pk_fma_f32 v[32:33], v[38:39], v[38:39], v[32:33]
	v_mul_f32_e32 v71, 0xbfb8aa3b, v72
	v_add_f32_e32 v32, v32, v33
	v_add_f32_e32 v32, v66, v32
	ds_bpermute_b32 v33, v76, v32
	v_mov_b32_e32 v84, v28
	v_exp_f32_e32 v71, v71
	v_and_b32_e32 v73, 0xffff0000, v129
	v_mov_b32_e32 v85, v30
	s_waitcnt lgkmcnt(0)
	v_add_f32_e32 v80, v32, v33
	v_add_u32_e32 v32, 0x1080, v77
	ds_read2_b32 v[32:33], v32 offset1:1
	v_add_f32_e32 v71, 1.0, v71
	v_mov_b32_e32 v30, v29
	v_rcp_f32_e32 v82, v71
	v_mov_b32_e32 v86, v24
	s_waitcnt lgkmcnt(0)
	v_lshlrev_b32_e32 v67, 16, v33
	v_and_b32_e32 v69, 0xffff0000, v33
	v_lshlrev_b32_e32 v33, 16, v129
	v_mul_f32_e32 v28, 0xbfb8aa3b, v33
	v_exp_f32_e32 v28, v28
	v_and_b32_e32 v68, 0xffff0000, v32
	v_lshlrev_b32_e32 v66, 16, v32
	v_lshlrev_b32_e32 v32, 16, v128
	v_add_f32_e32 v28, 1.0, v28
	v_rcp_f32_e32 v71, v28
	v_pk_fma_f32 v[28:29], v[188:189], v[68:69], v[30:31]
	v_mul_f32_e32 v30, 0xbfb8aa3b, v73
	v_mul_f32_e32 v70, 0xbfb8aa3b, v32
	v_exp_f32_e32 v30, v30
	v_exp_f32_e32 v70, v70
	v_pk_fma_f32 v[66:67], v[188:189], v[66:67], v[84:85]
	v_mov_b32_e32 v87, v26
	v_add_f32_e32 v30, 1.0, v30
	v_add_f32_e32 v70, 1.0, v70
	v_rcp_f32_e32 v83, v30
	v_rcp_f32_e32 v70, v70
	v_mov_b32_e32 v26, v25
	v_mov_b32_e32 v22, v21
	v_pk_mul_f32 v[30:31], v[82:83], v[72:73]
	v_pk_mul_f32 v[32:33], v[70:71], v[32:33]
	v_pk_mul_f32 v[30:31], v[30:31], v[28:29]
	v_pk_mul_f32 v[32:33], v[32:33], v[66:67]
	v_pk_mul_f32 v[28:29], v[30:31], v[30:31]
	v_and_b32_e32 v82, 0xffff0000, v126
	v_pk_fma_f32 v[66:67], v[32:33], v[32:33], v[28:29]
	v_add_u32_e32 v28, 0x10a0, v77
	ds_read2_b32 v[28:29], v28 offset1:1
	v_mul_f32_e32 v73, 0xbfb8aa3b, v82
	v_exp_f32_e32 v73, v73
	v_and_b32_e32 v83, 0xffff0000, v127
	v_mov_b32_e32 v90, v16
	s_waitcnt lgkmcnt(0)
	v_lshlrev_b32_e32 v69, 16, v29
	v_and_b32_e32 v71, 0xffff0000, v29
	v_lshlrev_b32_e32 v29, 16, v127
	v_mul_f32_e32 v24, 0xbfb8aa3b, v29
	v_exp_f32_e32 v24, v24
	v_and_b32_e32 v70, 0xffff0000, v28
	v_add_f32_e32 v73, 1.0, v73
	v_lshlrev_b32_e32 v68, 16, v28
	v_add_f32_e32 v24, 1.0, v24
	v_lshlrev_b32_e32 v28, 16, v126
	v_rcp_f32_e32 v84, v73
	v_rcp_f32_e32 v73, v24
	v_pk_fma_f32 v[24:25], v[188:189], v[70:71], v[26:27]
	v_mul_f32_e32 v26, 0xbfb8aa3b, v83
	v_mul_f32_e32 v72, 0xbfb8aa3b, v28
	v_exp_f32_e32 v26, v26
	v_exp_f32_e32 v72, v72
	v_pk_fma_f32 v[68:69], v[188:189], v[68:69], v[86:87]
	v_mov_b32_e32 v91, v18
	v_add_f32_e32 v26, 1.0, v26
	v_add_f32_e32 v72, 1.0, v72
	v_rcp_f32_e32 v85, v26
	v_rcp_f32_e32 v72, v72
	v_mov_b32_e32 v18, v17
	v_add_f32_e32 v66, v66, v67
	v_pk_mul_f32 v[26:27], v[84:85], v[82:83]
	v_pk_mul_f32 v[28:29], v[72:73], v[28:29]
	v_pk_mul_f32 v[24:25], v[26:27], v[24:25]
	v_pk_mul_f32 v[28:29], v[28:29], v[68:69]
	v_pk_mul_f32 v[26:27], v[24:25], v[24:25]
	v_and_b32_e32 v84, 0xffff0000, v122
	v_pk_fma_f32 v[68:69], v[28:29], v[28:29], v[26:27]
	v_add_u32_e32 v26, 0x10c0, v77
	ds_read2_b32 v[26:27], v26 offset1:1
	v_mul_f32_e32 v83, 0xbfb8aa3b, v84
	v_exp_f32_e32 v83, v83
	v_and_b32_e32 v85, 0xffff0000, v123
	v_add_f32_e32 v68, v68, v69
	s_waitcnt lgkmcnt(0)
	v_lshlrev_b32_e32 v71, 16, v27
	v_and_b32_e32 v73, 0xffff0000, v27
	v_lshlrev_b32_e32 v27, 16, v123
	v_mul_f32_e32 v20, 0xbfb8aa3b, v27
	v_exp_f32_e32 v20, v20
	v_and_b32_e32 v72, 0xffff0000, v26
	v_add_f32_e32 v83, 1.0, v83
	v_lshlrev_b32_e32 v70, 16, v26
	v_add_f32_e32 v20, 1.0, v20
	v_lshlrev_b32_e32 v26, 16, v122
	v_rcp_f32_e32 v86, v83
	v_rcp_f32_e32 v83, v20
	v_pk_fma_f32 v[20:21], v[188:189], v[72:73], v[22:23]
	v_mul_f32_e32 v22, 0xbfb8aa3b, v85
	v_mul_f32_e32 v82, 0xbfb8aa3b, v26
	v_exp_f32_e32 v22, v22
	v_exp_f32_e32 v82, v82
	v_pk_fma_f32 v[70:71], v[188:189], v[70:71], v[88:89]
	v_add_f32_e32 v66, v66, v68
	v_add_f32_e32 v22, 1.0, v22
	v_add_f32_e32 v82, 1.0, v82
	v_rcp_f32_e32 v87, v22
	v_rcp_f32_e32 v82, v82
	v_mov_b32_e32 v92, v0
	v_mov_b32_e32 v93, v2
	v_pk_mul_f32 v[22:23], v[86:87], v[84:85]
	v_pk_mul_f32 v[26:27], v[82:83], v[26:27]
	v_pk_mul_f32 v[20:21], v[22:23], v[20:21]
	v_pk_mul_f32 v[26:27], v[26:27], v[70:71]
	v_pk_mul_f32 v[22:23], v[20:21], v[20:21]
	s_waitcnt vmcnt(1)
	v_and_b32_e32 v86, 0xffff0000, v118
	v_pk_fma_f32 v[70:71], v[26:27], v[26:27], v[22:23]
	v_add_u32_e32 v22, 0x10e0, v77
	ds_read2_b32 v[22:23], v22 offset1:1
	v_mul_f32_e32 v85, 0xbfb8aa3b, v86
	v_exp_f32_e32 v85, v85
	v_and_b32_e32 v87, 0xffff0000, v119
	v_add_f32_e32 v67, v70, v71
	s_waitcnt lgkmcnt(0)
	v_lshlrev_b32_e32 v73, 16, v23
	v_and_b32_e32 v83, 0xffff0000, v23
	v_lshlrev_b32_e32 v23, 16, v119
	v_mul_f32_e32 v16, 0xbfb8aa3b, v23
	v_exp_f32_e32 v16, v16
	v_and_b32_e32 v82, 0xffff0000, v22
	v_add_f32_e32 v85, 1.0, v85
	v_lshlrev_b32_e32 v72, 16, v22
	v_add_f32_e32 v16, 1.0, v16
	v_lshlrev_b32_e32 v22, 16, v118
	v_rcp_f32_e32 v88, v85
	v_rcp_f32_e32 v85, v16
	v_pk_fma_f32 v[16:17], v[188:189], v[82:83], v[18:19]
	v_mul_f32_e32 v18, 0xbfb8aa3b, v87
	v_mul_f32_e32 v84, 0xbfb8aa3b, v22
	v_exp_f32_e32 v18, v18
	v_exp_f32_e32 v84, v84
	v_pk_fma_f32 v[72:73], v[188:189], v[72:73], v[90:91]
	v_add_f32_e32 v66, v66, v67
	v_add_f32_e32 v18, 1.0, v18
	v_add_f32_e32 v84, 1.0, v84
	v_rcp_f32_e32 v89, v18
	v_rcp_f32_e32 v84, v84
	v_mov_b32_e32 v90, v4
	v_mov_b32_e32 v91, v6
	v_pk_mul_f32 v[18:19], v[88:89], v[86:87]
	v_pk_mul_f32 v[22:23], v[84:85], v[22:23]
	v_pk_mul_f32 v[18:19], v[18:19], v[16:17]
	v_pk_mul_f32 v[22:23], v[22:23], v[72:73]
	v_pk_mul_f32 v[16:17], v[18:19], v[18:19]
	v_and_b32_e32 v72, 0xffff0000, v120
	v_pk_fma_f32 v[16:17], v[22:23], v[22:23], v[16:17]
	v_mul_f32_e32 v71, 0xbfb8aa3b, v72
	v_add_f32_e32 v16, v16, v17
	v_add_f32_e32 v16, v66, v16
	ds_bpermute_b32 v17, v76, v16
	v_mov_b32_e32 v86, v12
	v_exp_f32_e32 v71, v71
	v_and_b32_e32 v73, 0xffff0000, v121
	v_mov_b32_e32 v87, v14
	s_waitcnt lgkmcnt(0)
	v_add_f32_e32 v82, v16, v17
	v_add_u32_e32 v16, 0x18c0, v77
	ds_read2_b32 v[16:17], v16 offset1:1
	v_add_f32_e32 v71, 1.0, v71
	v_mov_b32_e32 v14, v13
	v_rcp_f32_e32 v84, v71
	v_mov_b32_e32 v88, v8
	s_waitcnt lgkmcnt(0)
	v_lshlrev_b32_e32 v67, 16, v17
	v_and_b32_e32 v69, 0xffff0000, v17
	v_lshlrev_b32_e32 v17, 16, v121
	v_mul_f32_e32 v12, 0xbfb8aa3b, v17
	v_exp_f32_e32 v12, v12
	v_and_b32_e32 v68, 0xffff0000, v16
	v_lshlrev_b32_e32 v66, 16, v16
	v_lshlrev_b32_e32 v16, 16, v120
	v_add_f32_e32 v12, 1.0, v12
	v_rcp_f32_e32 v71, v12
	v_pk_fma_f32 v[12:13], v[188:189], v[68:69], v[14:15]
	v_mul_f32_e32 v14, 0xbfb8aa3b, v73
	v_mul_f32_e32 v70, 0xbfb8aa3b, v16
	v_exp_f32_e32 v14, v14
	v_exp_f32_e32 v70, v70
	v_pk_fma_f32 v[66:67], v[188:189], v[66:67], v[86:87]
	v_mov_b32_e32 v89, v10
	v_add_f32_e32 v14, 1.0, v14
	v_add_f32_e32 v70, 1.0, v70
	v_rcp_f32_e32 v85, v14
	v_rcp_f32_e32 v70, v70
	v_mov_b32_e32 v10, v9
	v_mov_b32_e32 v6, v5
	v_pk_mul_f32 v[14:15], v[84:85], v[72:73]
	v_pk_mul_f32 v[16:17], v[70:71], v[16:17]
	v_pk_mul_f32 v[14:15], v[14:15], v[12:13]
	v_pk_mul_f32 v[16:17], v[16:17], v[66:67]
	v_pk_mul_f32 v[12:13], v[14:15], v[14:15]
	v_and_b32_e32 v84, 0xffff0000, v124
	v_pk_fma_f32 v[68:69], v[16:17], v[16:17], v[12:13]
	v_add_u32_e32 v12, 0x18e0, v77
	ds_read2_b32 v[12:13], v12 offset1:1
	v_mul_f32_e32 v73, 0xbfb8aa3b, v84
	v_exp_f32_e32 v73, v73
	v_and_b32_e32 v85, 0xffff0000, v125
	v_mov_b32_e32 v2, v1
	s_waitcnt lgkmcnt(0)
	v_lshlrev_b32_e32 v67, 16, v13
	v_and_b32_e32 v71, 0xffff0000, v13
	v_lshlrev_b32_e32 v13, 16, v125
	v_mul_f32_e32 v8, 0xbfb8aa3b, v13
	v_exp_f32_e32 v8, v8
	v_and_b32_e32 v70, 0xffff0000, v12
	v_add_f32_e32 v73, 1.0, v73
	v_lshlrev_b32_e32 v66, 16, v12
	v_add_f32_e32 v8, 1.0, v8
	v_lshlrev_b32_e32 v12, 16, v124
	v_rcp_f32_e32 v86, v73
	v_rcp_f32_e32 v73, v8
	v_pk_fma_f32 v[8:9], v[188:189], v[70:71], v[10:11]
	v_mul_f32_e32 v10, 0xbfb8aa3b, v85
	v_mul_f32_e32 v72, 0xbfb8aa3b, v12
	v_exp_f32_e32 v10, v10
	v_exp_f32_e32 v72, v72
	v_pk_fma_f32 v[66:67], v[188:189], v[66:67], v[88:89]
	ds_bpermute_b32 v79, v75, v78
	v_add_f32_e32 v10, 1.0, v10
	v_add_f32_e32 v72, 1.0, v72
	v_rcp_f32_e32 v87, v10
	v_rcp_f32_e32 v72, v72
	ds_bpermute_b32 v81, v75, v80
	ds_bpermute_b32 v83, v75, v82
	v_pk_mul_f32 v[10:11], v[86:87], v[84:85]
	v_pk_mul_f32 v[12:13], v[72:73], v[12:13]
	v_pk_mul_f32 v[8:9], v[10:11], v[8:9]
	v_pk_mul_f32 v[12:13], v[12:13], v[66:67]
	v_pk_mul_f32 v[10:11], v[8:9], v[8:9]
	v_and_b32_e32 v86, 0xffff0000, v116
	v_pk_fma_f32 v[70:71], v[12:13], v[12:13], v[10:11]
	v_add_u32_e32 v10, 0x1900, v77
	ds_read2_b32 v[10:11], v10 offset1:1
	v_mul_f32_e32 v85, 0xbfb8aa3b, v86
	v_exp_f32_e32 v85, v85
	v_and_b32_e32 v87, 0xffff0000, v117
	v_cmp_gt_u32_e32 vcc, 16, v74
	s_waitcnt lgkmcnt(0)
	v_lshlrev_b32_e32 v67, 16, v11
	v_and_b32_e32 v73, 0xffff0000, v11
	v_lshlrev_b32_e32 v11, 16, v117
	v_mul_f32_e32 v4, 0xbfb8aa3b, v11
	v_exp_f32_e32 v4, v4
	v_and_b32_e32 v72, 0xffff0000, v10
	v_add_f32_e32 v85, 1.0, v85
	v_lshlrev_b32_e32 v66, 16, v10
	v_add_f32_e32 v4, 1.0, v4
	v_lshlrev_b32_e32 v10, 16, v116
	v_rcp_f32_e32 v88, v85
	v_rcp_f32_e32 v85, v4
	v_pk_fma_f32 v[4:5], v[188:189], v[72:73], v[6:7]
	v_mul_f32_e32 v6, 0xbfb8aa3b, v87
	v_mul_f32_e32 v84, 0xbfb8aa3b, v10
	v_exp_f32_e32 v6, v6
	v_exp_f32_e32 v84, v84
	v_pk_fma_f32 v[66:67], v[188:189], v[66:67], v[90:91]
	v_add_f32_e32 v6, 1.0, v6
	v_add_f32_e32 v84, 1.0, v84
	v_rcp_f32_e32 v89, v6
	v_rcp_f32_e32 v84, v84
	v_pk_mul_f32 v[6:7], v[88:89], v[86:87]
	v_pk_mul_f32 v[10:11], v[84:85], v[10:11]
	v_pk_mul_f32 v[4:5], v[6:7], v[4:5]
	v_pk_mul_f32 v[10:11], v[10:11], v[66:67]
	v_pk_mul_f32 v[6:7], v[4:5], v[4:5]
	s_waitcnt vmcnt(0)
	v_and_b32_e32 v89, 0xffff0000, v113
	v_pk_fma_f32 v[72:73], v[10:11], v[10:11], v[6:7]
	v_add_u32_e32 v6, 0x1920, v77
	ds_read2_b32 v[6:7], v6 offset1:1
	v_and_b32_e32 v88, 0xffff0000, v112
	s_waitcnt lgkmcnt(0)
	v_lshlrev_b32_e32 v66, 16, v6
	v_lshlrev_b32_e32 v67, 16, v7
	v_and_b32_e32 v85, 0xffff0000, v7
	v_and_b32_e32 v84, 0xffff0000, v6
	v_lshlrev_b32_e32 v7, 16, v113
	v_lshlrev_b32_e32 v6, 16, v112
	v_mul_f32_e32 v77, 0xbfb8aa3b, v6
	v_mul_f32_e32 v0, 0xbfb8aa3b, v7
	v_exp_f32_e32 v77, v77
	v_exp_f32_e32 v0, v0
	v_pk_fma_f32 v[66:67], v[188:189], v[66:67], v[92:93]
	v_add_f32_e32 v77, 1.0, v77
	v_add_f32_e32 v0, 1.0, v0
	v_rcp_f32_e32 v86, v77
	v_mul_f32_e32 v77, 0xbfb8aa3b, v88
	v_rcp_f32_e32 v87, v0
	v_pk_fma_f32 v[0:1], v[188:189], v[84:85], v[2:3]
	v_mul_f32_e32 v2, 0xbfb8aa3b, v89
	v_exp_f32_e32 v77, v77
	v_exp_f32_e32 v2, v2
	v_pk_mul_f32 v[6:7], v[86:87], v[6:7]
	v_add_f32_e32 v77, 1.0, v77
	v_add_f32_e32 v2, 1.0, v2
	v_rcp_f32_e32 v90, v77
	v_rcp_f32_e32 v91, v2
	v_pk_mul_f32 v[6:7], v[6:7], v[66:67]
	v_pk_mul_f32 v[2:3], v[90:91], v[88:89]
	s_nop 0
	v_pk_mul_f32 v[66:67], v[2:3], v[0:1]
	v_add_f32_e32 v2, v70, v71
	v_pk_mul_f32 v[0:1], v[66:67], v[66:67]
	v_add_f32_e32 v3, v68, v69
	v_pk_fma_f32 v[0:1], v[6:7], v[6:7], v[0:1]
	v_add_f32_e32 v2, v3, v2
	v_add_f32_e32 v3, v72, v73
	v_add_f32_e32 v2, v2, v3
	v_add_f32_e32 v0, v0, v1
	v_add_f32_e32 v0, v2, v0
	ds_bpermute_b32 v1, v76, v0
	s_waitcnt lgkmcnt(0)
	v_add_f32_e32 v0, v0, v1
	ds_bpermute_b32 v1, v75, v0
	s_and_saveexec_b64 s[0:1], vcc
	s_cbranch_execz .LBB0_549
	v_add_f32_e32 v2, v80, v81
	v_add_f32_e32 v3, v78, v79
	v_lshl_add_u32 v68, v74, 2, v242
	s_waitcnt lgkmcnt(0)
	v_add_f32_e32 v0, v0, v1
	v_add_f32_e32 v1, v82, v83
	ds_write2_b32 v68, v3, v2 offset1:16
	ds_write2_b32 v68, v1, v0 offset0:32 offset1:48
	s_branch .LBB0_549

.LBB0_602:
	s_ashr_i32 s24, s48, 8
	s_bfe_u32 s49, s48, 0x70001
	s_ashr_i32 s25, s24, 31
	s_lshl_b64 s[0:1], s[24:25], 13
	s_lshl_b32 s25, s49, 6
	s_or_b32 s0, s0, s25
	v_or_b32_e32 v2, s0, v72
	v_mov_b64_e32 v[0:1], s[20:21]
	s_movk_i32 s25, 0x600
	v_mad_u64_u32 v[2:3], s[26:27], v2, s25, v[0:1]
	v_mad_i32_i24 v3, s1, v229, v3
	v_lshl_add_u64 v[4:5], v[2:3], 0, v[88:89]
	v_lshl_add_u64 v[2:3], v[2:3], 0, v[90:91]
	v_lshl_add_u64 v[4:5], v[4:5], 0, v[168:169]
	v_lshl_add_u64 v[2:3], v[2:3], 0, v[168:169]
	global_load_dwordx4 v[60:63], v[4:5], off
	global_load_dwordx4 v[48:51], v[2:3], off offset:1024
	v_or_b32_e32 v2, s0, v74
	v_mad_u64_u32 v[2:3], s[26:27], v2, s25, v[0:1]
	v_mad_i32_i24 v3, s1, v229, v3
	v_lshl_add_u64 v[4:5], v[2:3], 0, v[88:89]
	v_lshl_add_u64 v[2:3], v[2:3], 0, v[90:91]
	v_lshl_add_u64 v[4:5], v[4:5], 0, v[168:169]
	v_lshl_add_u64 v[2:3], v[2:3], 0, v[168:169]
	global_load_dwordx4 v[56:59], v[4:5], off
	global_load_dwordx4 v[52:55], v[2:3], off offset:1024
	v_or_b32_e32 v2, s0, v76
	v_mad_u64_u32 v[2:3], s[26:27], v2, s25, v[0:1]
	v_mad_i32_i24 v3, s1, v229, v3
	v_lshl_add_u64 v[4:5], v[2:3], 0, v[88:89]
	v_lshl_add_u64 v[2:3], v[2:3], 0, v[90:91]
	v_lshl_add_u64 v[4:5], v[4:5], 0, v[168:169]
	v_lshl_add_u64 v[2:3], v[2:3], 0, v[168:169]
	global_load_dwordx4 v[44:47], v[4:5], off
	global_load_dwordx4 v[40:43], v[2:3], off offset:1024
	v_or_b32_e32 v2, s0, v78
	v_mad_u64_u32 v[2:3], s[26:27], v2, s25, v[0:1]
	v_mad_i32_i24 v3, s1, v229, v3
	v_lshl_add_u64 v[4:5], v[2:3], 0, v[88:89]
	v_lshl_add_u64 v[2:3], v[2:3], 0, v[90:91]
	v_lshl_add_u64 v[4:5], v[4:5], 0, v[168:169]
	v_lshl_add_u64 v[2:3], v[2:3], 0, v[168:169]
	global_load_dwordx4 v[36:39], v[4:5], off
	global_load_dwordx4 v[32:35], v[2:3], off offset:1024
	v_or_b32_e32 v2, s0, v80
	v_mad_u64_u32 v[2:3], s[26:27], v2, s25, v[0:1]
	v_mad_i32_i24 v3, s1, v229, v3
	v_lshl_add_u64 v[4:5], v[2:3], 0, v[88:89]
	v_lshl_add_u64 v[2:3], v[2:3], 0, v[90:91]
	v_lshl_add_u64 v[4:5], v[4:5], 0, v[168:169]
	v_lshl_add_u64 v[2:3], v[2:3], 0, v[168:169]
	global_load_dwordx4 v[28:31], v[4:5], off
	global_load_dwordx4 v[24:27], v[2:3], off offset:1024
	v_or_b32_e32 v2, s0, v82
	v_mad_u64_u32 v[2:3], s[26:27], v2, s25, v[0:1]
	v_mad_i32_i24 v3, s1, v229, v3
	v_lshl_add_u64 v[4:5], v[2:3], 0, v[88:89]
	v_lshl_add_u64 v[2:3], v[2:3], 0, v[90:91]
	v_lshl_add_u64 v[4:5], v[4:5], 0, v[168:169]
	v_lshl_add_u64 v[2:3], v[2:3], 0, v[168:169]
	global_load_dwordx4 v[20:23], v[4:5], off
	global_load_dwordx4 v[16:19], v[2:3], off offset:1024
	v_or_b32_e32 v2, s0, v84
	v_mad_u64_u32 v[2:3], s[26:27], v2, s25, v[0:1]
	v_mad_i32_i24 v3, s1, v229, v3
	v_lshl_add_u64 v[4:5], v[2:3], 0, v[88:89]
	v_lshl_add_u64 v[2:3], v[2:3], 0, v[90:91]
	v_lshl_add_u64 v[4:5], v[4:5], 0, v[168:169]
	v_lshl_add_u64 v[2:3], v[2:3], 0, v[168:169]
	global_load_dwordx4 v[12:15], v[4:5], off
	global_load_dwordx4 v[8:11], v[2:3], off offset:1024
	v_or_b32_e32 v2, s0, v86
	v_or_b32_e32 v81, s0, v66
	v_mov_b64_e32 v[98:99], s[2:3]
	s_movk_i32 s0, 0x1220
	v_mad_u64_u32 v[0:1], s[26:27], v2, s25, v[0:1]
	s_and_b32 s25, s48, 1
	v_mad_u64_u32 v[98:99], s[26:27], v81, s0, v[98:99]
	v_mov_b32_e32 v81, 0x1220
	v_mad_i32_i24 v99, s1, v81, v99
	s_lshl_b32 s34, s25, 4
	v_lshl_add_u64 v[98:99], v[98:99], 0, s[34:35]
	v_lshl_add_u64 v[98:99], v[64:65], 1, v[98:99]
	s_mov_b32 s0, 0xe401000
	v_mad_i32_i24 v1, s1, v229, v1
	v_add_co_u32_e64 v98, s[0:1], s0, v98
	v_lshl_add_u64 v[2:3], v[0:1], 0, v[88:89]
	v_lshl_add_u64 v[0:1], v[0:1], 0, v[90:91]
	v_addc_co_u32_e64 v99, s[0:1], 0, v99, s[0:1]
	v_lshl_add_u64 v[2:3], v[2:3], 0, v[168:169]
	v_lshl_add_u64 v[0:1], v[0:1], 0, v[168:169]
	s_mov_b64 s[0:1], 0
	global_load_dwordx4 v[4:7], v[2:3], off
	s_nop 0
	global_load_dwordx4 v[0:3], v[0:1], off offset:1024
	s_nop 0
	global_load_ushort v81, v[98:99], off
	s_add_u32 s0, s4, s0
	v_lshl_add_u32 v98, s25, 3, v67
	s_addc_u32 s1, s5, s1
	v_ashrrev_i32_e32 v99, 31, v98
	v_lshl_add_u64 v[100:101], v[98:99], 2, s[0:1]
	global_load_dword v83, v[100:101], off
	v_lshl_add_u64 v[162:163], v[98:99], 2, s[6:7]
	global_load_dword v160, v[162:163], off
	s_mov_b32 s0, 0x41a00000
	s_waitcnt vmcnt(0)
	v_lshlrev_b32_e32 v81, 16, v81
	v_add_f32_e32 v83, v83, v81
	v_cmp_nlt_f32_e64 s[0:1], s0, v83
	s_and_saveexec_b64 s[26:27], s[0:1]
	s_cbranch_execz .LBB0_604
	v_mul_f32_e32 v81, 0x3fb8aa3b, v83
	v_rndne_f32_e32 v85, v81
	s_mov_b32 s0, 0x3fb8aa3b
	v_sub_f32_e32 v87, v81, v85
	v_fma_f32 v81, v83, s0, -v81
	v_fmac_f32_e32 v81, 0x32a5705f, v83
	v_add_f32_e32 v81, v87, v81
	v_cvt_i32_f32_e32 v85, v85
	v_exp_f32_e32 v81, v81
	v_cmp_ngt_f32_e64 s[0:1], s37, v83
	v_ldexp_f32 v81, v81, v85
	s_nop 0
	v_cndmask_b32_e64 v81, 0, v81, s[0:1]
	v_cmp_nlt_f32_e64 s[0:1], s30, v83
	s_nop 1
	v_cndmask_b32_e64 v81, v231, v81, s[0:1]
	v_add_f32_e32 v83, 1.0, v81
	v_add_f32_e32 v85, -1.0, v83
	v_sub_f32_e32 v87, v85, v83
	v_add_f32_e32 v87, 1.0, v87
	v_sub_f32_e32 v85, v81, v85
	v_add_f32_e32 v85, v85, v87
	v_frexp_mant_f32_e32 v87, v83
	v_cvt_f64_f32_e32 v[100:101], v83
	s_mov_b32 s0, 0x3f2aaaab
	v_frexp_exp_i32_f64_e32 v93, v[100:101]
	v_cmp_gt_f32_e64 s[0:1], s0, v87
	s_nop 1
	v_subbrev_co_u32_e64 v87, s[0:1], 0, v93, s[0:1]
	v_sub_u32_e32 v93, 0, v87
	v_ldexp_f32 v83, v83, v93
	v_ldexp_f32 v85, v85, v93
	v_add_f32_e32 v93, -1.0, v83
	v_add_f32_e32 v97, 1.0, v83
	v_add_f32_e32 v95, 1.0, v93
	v_add_f32_e32 v100, -1.0, v97
	v_sub_f32_e32 v95, v83, v95
	v_sub_f32_e32 v83, v83, v100
	v_add_f32_e32 v83, v85, v83
	v_add_f32_e32 v95, v85, v95
	v_add_f32_e32 v85, v97, v83
	v_sub_f32_e32 v97, v97, v85
	v_add_f32_e32 v83, v83, v97
	v_rcp_f32_e32 v97, v85
	v_add_f32_e32 v101, v93, v95
	v_sub_f32_e32 v93, v93, v101
	v_add_f32_e32 v93, v95, v93
	v_mul_f32_e32 v95, v101, v97
	v_mul_f32_e32 v102, v85, v95
	v_fma_f32 v104, v95, v85, -v102
	v_fmac_f32_e32 v104, v95, v83
	v_add_f32_e32 v100, v102, v104
	v_sub_f32_e32 v103, v101, v100
	v_pk_add_f32 v[106:107], v[100:101], v[102:103] neg_lo:[0,1] neg_hi:[0,1]
	v_mov_b32_e32 v105, v100
	v_pk_add_f32 v[100:101], v[106:107], v[104:105] neg_lo:[0,1] neg_hi:[0,1]
	s_mov_b32 s0, 0x3f317218
	v_add_f32_e32 v93, v93, v101
	v_add_f32_e32 v93, v100, v93
	v_add_f32_e32 v101, v103, v93
	v_mul_f32_e32 v108, v97, v101
	v_mul_f32_e32 v102, v85, v108
	v_fma_f32 v104, v108, v85, -v102
	v_fmac_f32_e32 v104, v108, v83
	v_add_f32_e32 v100, v102, v104
	v_sub_f32_e32 v83, v103, v101
	v_sub_f32_e32 v103, v101, v100
	v_pk_add_f32 v[106:107], v[100:101], v[102:103] neg_lo:[0,1] neg_hi:[0,1]
	v_mov_b32_e32 v105, v100
	v_add_f32_e32 v83, v93, v83
	v_pk_add_f32 v[100:101], v[106:107], v[104:105] neg_lo:[0,1] neg_hi:[0,1]
	v_add_f32_e32 v85, v95, v108
	v_add_f32_e32 v83, v83, v101
	v_add_f32_e32 v83, v100, v83
	v_add_f32_e32 v83, v103, v83
	v_sub_f32_e32 v93, v85, v95
	v_mul_f32_e32 v83, v97, v83
	v_sub_f32_e32 v93, v108, v93
	v_add_f32_e32 v83, v93, v83
	v_add_f32_e32 v93, v85, v83
	v_cvt_f32_i32_e32 v100, v87
	v_mul_f32_e32 v95, v93, v93
	v_mov_b32_e32 v97, 0x3ecc95a3
	v_fmamk_f32 v97, v95, 0x3e9b6dac, v97
	v_fmaak_f32 v179, v95, v97, 0x3f2aaada
	v_mul_f32_e32 v101, v93, v95
	v_pk_mul_f32 v[104:105], v[100:101], v[178:179]
	v_ldexp_f32 v103, v93, 1
	v_fma_f32 v102, v100, s0, -v104
	v_fmac_f32_e32 v102, 0xb102e308, v100
	v_sub_f32_e32 v85, v93, v85
	v_pk_add_f32 v[100:101], v[104:105], v[102:103]
	v_sub_f32_e32 v83, v83, v85
	v_sub_f32_e32 v85, v101, v103
	v_ldexp_f32 v83, v83, 1
	v_sub_f32_e32 v85, v105, v85
	v_add_f32_e32 v107, v83, v85
	v_mov_b32_e32 v106, v104
	v_pk_add_f32 v[104:105], v[100:101], v[104:105] neg_lo:[0,1] neg_hi:[0,1]
	v_pk_add_f32 v[108:109], v[100:101], v[106:107]
	v_mov_b32_e32 v103, v100
	v_mov_b32_e32 v105, v109
	v_pk_add_f32 v[110:111], v[102:103], v[104:105] neg_lo:[0,1] neg_hi:[0,1]
	v_pk_add_f32 v[102:103], v[102:103], v[104:105]
	v_mov_b32_e32 v106, v107
	v_pk_add_f32 v[104:105], v[102:103], v[100:101] op_sel:[1,0] op_sel_hi:[0,1] neg_lo:[0,1] neg_hi:[0,1]
	v_pk_add_f32 v[112:113], v[108:109], v[104:105] op_sel_hi:[1,0] neg_lo:[0,1] neg_hi:[0,1]
	v_mov_b32_e32 v108, v109
	v_mov_b32_e32 v109, v103
	v_pk_mov_b32 v[104:105], v[100:101], v[104:105] op_sel:[1,0]
	v_mov_b32_e32 v107, v100
	v_pk_add_f32 v[104:105], v[108:109], v[104:105] neg_lo:[0,1] neg_hi:[0,1]
	v_mov_b32_e32 v112, v110
	v_pk_add_f32 v[100:101], v[106:107], v[104:105] neg_lo:[0,1] neg_hi:[0,1]
	v_mov_b32_e32 v111, v103
	v_pk_add_f32 v[104:105], v[112:113], v[100:101]
	s_mov_b32 s0, 0x7f800000
	v_pk_add_f32 v[106:107], v[104:105], v[104:105] op_sel:[0,1] op_sel_hi:[1,0]
	v_cmp_neq_f32_e64 s[0:1], s0, v81
	v_pk_add_f32 v[102:103], v[102:103], v[106:107] op_sel:[1,0] op_sel_hi:[0,1]
	v_mov_b32_e32 v105, v102
	v_pk_add_f32 v[108:109], v[104:105], v[110:111] neg_lo:[0,1] neg_hi:[0,1]
	v_mov_b32_e32 v101, v106
	v_sub_f32_e32 v83, v104, v108
	v_pk_add_f32 v[100:101], v[100:101], v[108:109] neg_lo:[0,1] neg_hi:[0,1]
	v_sub_f32_e32 v83, v110, v83
	v_add_f32_e32 v83, v100, v83
	v_add_f32_e32 v83, v83, v101
	v_add_f32_e32 v83, v102, v83
	v_cndmask_b32_e64 v83, v231, v83, s[0:1]
	s_mov_b32 s0, 0x33800000
	v_cmp_lt_f32_e64 s[0:1], |v81|, s0
	s_nop 1
	v_cndmask_b32_e64 v83, v83, v81, s[0:1]
.LBB0_604:
	s_or_b64 exec, exec, s[26:27]
	s_mov_b64 s[0:1], 0
	s_add_u32 s0, s6, s0
	s_addc_u32 s1, s7, s1
	v_mov_b32_e32 v85, v160
	s_mov_b32 s0, 0x3fb8aa3b
	v_and_b32_e32 v87, 64, v224
	v_add_u32_e32 v93, -1, v224
	v_add_u32_e32 v95, -2, v224
	v_add_u32_e32 v97, -4, v224
	v_add_u32_e32 v104, -8, v224
	v_add_u32_e32 v106, -16, v224
	v_subrev_u32_e32 v107, 32, v224
	s_cmp_eq_u32 s25, 0
	v_add_u32_e32 v81, 0x4400, v75
	v_add_u32_e32 v110, 0x2100, v77
	v_add_u32_e32 v111, 0x2108, v77
	v_lshlrev_b32_e32 v99, 16, v61
	v_lshlrev_b32_e32 v98, 16, v60
	v_and_b32_e32 v61, 0xffff0000, v61
	v_and_b32_e32 v60, 0xffff0000, v60
	v_lshlrev_b32_e32 v101, 16, v63
	v_lshlrev_b32_e32 v100, 16, v62
	v_and_b32_e32 v63, 0xffff0000, v63
	v_and_b32_e32 v62, 0xffff0000, v62
	v_lshlrev_b32_e32 v109, 16, v45
	v_lshlrev_b32_e32 v108, 16, v44
	v_and_b32_e32 v45, 0xffff0000, v45
	v_and_b32_e32 v44, 0xffff0000, v44
	s_waitcnt vmcnt(0)
	v_mul_f32_e32 v102, 0x3fb8aa3b, v85
	v_fma_f32 v103, v85, s0, -v102
	v_rndne_f32_e32 v105, v102
	v_fmac_f32_e32 v103, 0x32a5705f, v85
	v_sub_f32_e32 v102, v102, v105
	v_add_f32_e32 v102, v102, v103
	v_cvt_i32_f32_e32 v105, v105
	v_exp_f32_e32 v102, v102
	v_cmp_lt_i32_e64 s[0:1], v93, v87
	v_lshlrev_b32_e32 v103, 16, v57
	v_ldexp_f32 v102, v102, v105
	v_cndmask_b32_e64 v93, v93, v224, s[0:1]
	v_cmp_ngt_f32_e64 s[0:1], s37, v85
	v_lshlrev_b32_e32 v93, 2, v93
	v_and_b32_e32 v105, 0xffff0000, v57
	v_cndmask_b32_e64 v102, 0, v102, s[0:1]
	v_cmp_nlt_f32_e64 s[0:1], s30, v85
	s_nop 1
	v_cndmask_b32_e64 v85, v231, v102, s[0:1]
	v_mul_f32_e64 v102, v83, -v85
	ds_bpermute_b32 v93, v93, v102
	v_cmp_lt_i32_e64 s[0:1], v95, v87
	s_waitcnt lgkmcnt(0)
	v_fma_f32 v93, v83, -v85, v93
	v_cndmask_b32_e64 v95, v95, v224, s[0:1]
	v_lshlrev_b32_e32 v95, 2, v95
	v_cndmask_b32_e32 v93, v93, v102, vcc
	ds_bpermute_b32 v95, v95, v93
	v_cmp_lt_i32_e64 s[0:1], v97, v87
	v_lshlrev_b32_e32 v102, 16, v56
	s_waitcnt lgkmcnt(0)
	v_add_f32_e32 v95, v93, v95
	v_cndmask_b32_e64 v97, v97, v224, s[0:1]
	v_lshlrev_b32_e32 v97, 2, v97
	v_cndmask_b32_e64 v93, v95, v93, s[38:39]
	ds_bpermute_b32 v95, v97, v93
	v_cmp_lt_i32_e64 s[0:1], v104, v87
	s_waitcnt lgkmcnt(0)
	v_add_f32_e32 v95, v93, v95
	v_cndmask_b32_e64 v97, v104, v224, s[0:1]
	v_lshlrev_b32_e32 v97, 2, v97
	v_cndmask_b32_e64 v93, v95, v93, s[40:41]
	ds_bpermute_b32 v95, v97, v93
	v_cmp_lt_i32_e64 s[0:1], v106, v87
	v_and_b32_e32 v104, 0xffff0000, v56
	s_waitcnt lgkmcnt(0)
	v_add_f32_e32 v95, v93, v95
	v_cndmask_b32_e64 v57, v106, v224, s[0:1]
	v_lshlrev_b32_e32 v57, 2, v57
	v_cndmask_b32_e64 v93, v95, v93, s[42:43]
	ds_bpermute_b32 v57, v57, v93
	v_cmp_lt_i32_e64 s[0:1], v107, v87
	v_add_u32_e32 v95, 0x2520, v77
	v_lshlrev_b32_e32 v106, 16, v58
	v_cndmask_b32_e64 v56, v107, v224, s[0:1]
	s_waitcnt lgkmcnt(0)
	v_add_f32_e32 v57, v93, v57
	v_lshlrev_b32_e32 v56, 2, v56
	v_cndmask_b32_e64 v57, v57, v93, s[44:45]
	ds_bpermute_b32 v56, v56, v57
	s_cselect_b64 s[0:1], -1, 0
	v_lshlrev_b32_e32 v107, 16, v59
	v_and_b32_e32 v59, 0xffff0000, v59
	v_and_b32_e32 v58, 0xffff0000, v58
	s_waitcnt lgkmcnt(0)
	v_add_f32_e32 v56, v57, v56
	v_cndmask_b32_e64 v57, v56, v57, s[46:47]
	ds_bpermute_b32 v56, v230, v57
	v_add_u32_e32 v87, 0x420, v77
	v_add_u32_e32 v93, 0x428, v77
	s_waitcnt lgkmcnt(0)
	v_sub_f32_e32 v97, v56, v57
	v_fma_f32 v85, v83, -v85, v97
	v_cndmask_b32_e64 v57, v85, v57, s[0:1]
	v_sub_f32_e32 v57, v56, v57
	v_mul_f32_e32 v57, 0x3fb8aa3b, v57
	v_exp_f32_e32 v57, v57
	v_add_u32_e32 v85, 0x2528, v77
	s_mov_b32 s0, 0x5040100
	v_mul_f32_e32 v57, v83, v57
	ds_write_b32 v73, v57 offset:17664
	s_waitcnt lgkmcnt(0)
	ds_write2_b32 v110, v48, v49 offset1:1
	ds_read2_b32 v[48:49], v81 offset0:64 offset1:72
	ds_write2_b32 v111, v50, v51 offset1:1
	ds_write2_b32 v95, v52, v53 offset1:1
	ds_write2_b32 v85, v54, v55 offset1:1
	ds_read2_b32 v[50:51], v81 offset0:80 offset1:88
	s_waitcnt lgkmcnt(4)
	v_pk_mul_f32 v[52:53], v[48:49], v[98:99] op_sel_hi:[0,1]
	v_pk_mul_f32 v[54:55], v[48:49], v[60:61] op_sel_hi:[0,1]
	v_pk_mul_f32 v[60:61], v[48:49], v[100:101] op_sel_hi:[0,1]
	v_pk_mul_f32 v[62:63], v[48:49], v[62:63] op_sel_hi:[0,1]
	v_mov_b32_e32 v48, v49
	s_waitcnt lgkmcnt(0)
	v_pk_mul_f32 v[98:99], v[50:51], v[108:109] op_sel_hi:[0,1]
	v_and_b32_sdwa v108, v60, v228 dst_sel:DWORD dst_unused:UNUSED_PAD src0_sel:WORD_1 src1_sel:DWORD
	v_and_b32_sdwa v109, v63, v228 dst_sel:DWORD dst_unused:UNUSED_PAD src0_sel:WORD_1 src1_sel:DWORD
	v_and_b32_sdwa v110, v62, v228 dst_sel:DWORD dst_unused:UNUSED_PAD src0_sel:WORD_1 src1_sel:DWORD
	v_pk_mul_f32 v[100:101], v[48:49], v[102:103] op_sel_hi:[0,1]
	v_pk_mul_f32 v[102:103], v[48:49], v[104:105] op_sel_hi:[0,1]
	v_and_b32_sdwa v97, v61, v228 dst_sel:DWORD dst_unused:UNUSED_PAD src0_sel:WORD_1 src1_sel:DWORD
	v_pk_mul_f32 v[104:105], v[48:49], v[106:107] op_sel_hi:[0,1]
	v_pk_mul_f32 v[48:49], v[48:49], v[58:59] op_sel_hi:[0,1]
	v_add3_u32 v57, v60, v108, s96
	v_add3_u32 v59, v63, v109, s96
	v_add3_u32 v60, v62, v110, s96
	v_add3_u32 v58, v61, v97, s96
	v_and_b32_e32 v59, 0xffff0000, v59
	v_and_b32_e32 v60, 0xffff0000, v60
	v_cvt_pk_bf16_f32 v53, v53, v55
	v_cvt_pk_bf16_f32 v52, v52, v54
	v_or_b32_sdwa v54, v59, v58 dst_sel:DWORD dst_unused:UNUSED_PAD src0_sel:DWORD src1_sel:WORD_1
	v_or_b32_sdwa v55, v60, v57 dst_sel:DWORD dst_unused:UNUSED_PAD src0_sel:DWORD src1_sel:WORD_1
	ds_write2_b32 v77, v52, v53 offset1:1
	ds_write2_b32 v77, v55, v54 offset0:2 offset1:3
	v_cvt_pk_bf16_f32 v52, v101, v103
	v_cvt_pk_bf16_f32 v53, v100, v102
	v_pk_mul_f32 v[44:45], v[50:51], v[44:45] op_sel_hi:[0,1]
	v_cvt_pk_bf16_f32 v49, v105, v49
	v_cvt_pk_bf16_f32 v48, v104, v48
	ds_write2_b32 v87, v53, v52 offset1:1
	ds_write2_b32 v93, v48, v49 offset1:1
	v_cvt_pk_bf16_f32 v45, v99, v45
	v_cvt_pk_bf16_f32 v44, v98, v44
	v_add_u32_e32 v48, 0x840, v77
	ds_write2_b32 v48, v44, v45 offset1:1
	v_lshlrev_b32_e32 v45, 16, v47
	v_lshlrev_b32_e32 v44, 16, v46
	v_pk_mul_f32 v[44:45], v[50:51], v[44:45] op_sel_hi:[0,1]
	v_and_b32_e32 v47, 0xffff0000, v47
	v_and_b32_e32 v46, 0xffff0000, v46
	v_pk_mul_f32 v[46:47], v[50:51], v[46:47] op_sel_hi:[0,1]
	s_nop 0
	v_cvt_pk_bf16_f32 v45, v45, v47
	v_cvt_pk_bf16_f32 v44, v44, v46
	v_add_u32_e32 v46, 0x848, v77
	ds_write2_b32 v46, v44, v45 offset1:1
	v_add_u32_e32 v44, 0x2940, v77
	ds_write2_b32 v44, v40, v41 offset1:1
	v_add_u32_e32 v40, 0x2948, v77
	ds_write2_b32 v40, v42, v43 offset1:1
	v_lshlrev_b32_e32 v41, 16, v37
	v_lshlrev_b32_e32 v40, 16, v36
	v_mov_b32_e32 v42, v51
	v_pk_mul_f32 v[40:41], v[42:43], v[40:41] op_sel_hi:[0,1]
	v_and_b32_e32 v37, 0xffff0000, v37
	v_and_b32_e32 v36, 0xffff0000, v36
	v_pk_mul_f32 v[36:37], v[42:43], v[36:37] op_sel_hi:[0,1]
	v_and_b32_sdwa v43, v41, v228 dst_sel:DWORD dst_unused:UNUSED_PAD src0_sel:WORD_1 src1_sel:DWORD
	s_nop 0
	v_add3_u32 v41, v41, v43, s96
	v_and_b32_sdwa v43, v37, v228 dst_sel:DWORD dst_unused:UNUSED_PAD src0_sel:WORD_1 src1_sel:DWORD
	s_nop 0
	v_add3_u32 v37, v37, v43, s96
	v_and_b32_e32 v37, 0xffff0000, v37
	v_or_b32_sdwa v37, v37, v41 dst_sel:DWORD dst_unused:UNUSED_PAD src0_sel:DWORD src1_sel:WORD_1
	v_cvt_pk_bf16_f32 v36, v40, v36
	v_add_u32_e32 v40, 0xc60, v77
	ds_write2_b32 v40, v36, v37 offset1:1
	v_lshlrev_b32_e32 v37, 16, v39
	v_lshlrev_b32_e32 v36, 16, v38
	v_pk_mul_f32 v[36:37], v[42:43], v[36:37] op_sel_hi:[0,1]
	v_and_b32_e32 v39, 0xffff0000, v39
	v_and_b32_e32 v38, 0xffff0000, v38
	v_pk_mul_f32 v[38:39], v[42:43], v[38:39] op_sel_hi:[0,1]
	s_nop 0
	v_cvt_pk_bf16_f32 v37, v37, v39
	v_cvt_pk_bf16_f32 v36, v36, v38
	v_add_u32_e32 v38, 0xc68, v77
	ds_write2_b32 v38, v36, v37 offset1:1
	v_add_u32_e32 v36, 0x2d60, v77
	ds_write2_b32 v36, v32, v33 offset1:1
	ds_read2_b32 v[32:33], v81 offset0:96 offset1:104
	v_add_u32_e32 v36, 0x2d68, v77
	ds_write2_b32 v36, v34, v35 offset1:1
	v_lshlrev_b32_e32 v35, 16, v29
	v_lshlrev_b32_e32 v34, 16, v28
	s_waitcnt lgkmcnt(1)
	v_pk_mul_f32 v[34:35], v[32:33], v[34:35] op_sel_hi:[0,1]
	v_and_b32_e32 v29, 0xffff0000, v29
	v_and_b32_e32 v28, 0xffff0000, v28
	v_pk_mul_f32 v[28:29], v[32:33], v[28:29] op_sel_hi:[0,1]
	s_nop 0
	v_cvt_pk_bf16_f32 v29, v35, v29
	v_cvt_pk_bf16_f32 v28, v34, v28
	v_add_u32_e32 v34, 0x1080, v77
	ds_write2_b32 v34, v28, v29 offset1:1
	v_lshlrev_b32_e32 v29, 16, v31
	v_lshlrev_b32_e32 v28, 16, v30
	v_pk_mul_f32 v[28:29], v[32:33], v[28:29] op_sel_hi:[0,1]
	v_and_b32_e32 v31, 0xffff0000, v31
	v_and_b32_e32 v30, 0xffff0000, v30
	v_pk_mul_f32 v[30:31], v[32:33], v[30:31] op_sel_hi:[0,1]
	s_nop 0
	v_cvt_pk_bf16_f32 v29, v29, v31
	v_cvt_pk_bf16_f32 v28, v28, v30
	v_add_u32_e32 v30, 0x1088, v77
	ds_write2_b32 v30, v28, v29 offset1:1
	v_add_u32_e32 v28, 0x3180, v77
	ds_write2_b32 v28, v24, v25 offset1:1
	v_add_u32_e32 v24, 0x3188, v77
	ds_write2_b32 v24, v26, v27 offset1:1
	v_lshlrev_b32_e32 v25, 16, v21
	v_lshlrev_b32_e32 v24, 16, v20
	v_mov_b32_e32 v26, v33
	v_pk_mul_f32 v[24:25], v[26:27], v[24:25] op_sel_hi:[0,1]
	v_and_b32_e32 v21, 0xffff0000, v21
	v_and_b32_e32 v20, 0xffff0000, v20
	v_pk_mul_f32 v[20:21], v[26:27], v[20:21] op_sel_hi:[0,1]
	v_and_b32_sdwa v27, v25, v228 dst_sel:DWORD dst_unused:UNUSED_PAD src0_sel:WORD_1 src1_sel:DWORD
	s_nop 0
	v_add3_u32 v25, v25, v27, s96
	v_and_b32_sdwa v27, v21, v228 dst_sel:DWORD dst_unused:UNUSED_PAD src0_sel:WORD_1 src1_sel:DWORD
	s_nop 0
	v_add3_u32 v21, v21, v27, s96
	v_and_b32_e32 v21, 0xffff0000, v21
	v_or_b32_sdwa v21, v21, v25 dst_sel:DWORD dst_unused:UNUSED_PAD src0_sel:DWORD src1_sel:WORD_1
	v_cvt_pk_bf16_f32 v20, v24, v20
	v_add_u32_e32 v24, 0x14a0, v77
	ds_write2_b32 v24, v20, v21 offset1:1
	v_lshlrev_b32_e32 v21, 16, v23
	v_lshlrev_b32_e32 v20, 16, v22
	v_pk_mul_f32 v[20:21], v[26:27], v[20:21] op_sel_hi:[0,1]
	v_and_b32_e32 v23, 0xffff0000, v23
	v_and_b32_e32 v22, 0xffff0000, v22
	v_pk_mul_f32 v[22:23], v[26:27], v[22:23] op_sel_hi:[0,1]
	s_nop 0
	v_cvt_pk_bf16_f32 v21, v21, v23
	v_cvt_pk_bf16_f32 v20, v20, v22
	v_add_u32_e32 v22, 0x14a8, v77
	ds_write2_b32 v22, v20, v21 offset1:1
	v_add_u32_e32 v20, 0x35a0, v77
	ds_write2_b32 v20, v16, v17 offset1:1
	ds_read2_b32 v[16:17], v81 offset0:112 offset1:120
	v_add_u32_e32 v20, 0x35a8, v77
	ds_write2_b32 v20, v18, v19 offset1:1
	v_lshlrev_b32_e32 v19, 16, v13
	v_lshlrev_b32_e32 v18, 16, v12
	s_waitcnt lgkmcnt(1)
	v_pk_mul_f32 v[18:19], v[16:17], v[18:19] op_sel_hi:[0,1]
	v_and_b32_e32 v13, 0xffff0000, v13
	v_and_b32_e32 v12, 0xffff0000, v12
	v_pk_mul_f32 v[12:13], v[16:17], v[12:13] op_sel_hi:[0,1]
	s_nop 0
	v_cvt_pk_bf16_f32 v13, v19, v13
	v_cvt_pk_bf16_f32 v12, v18, v12
	v_add_u32_e32 v18, 0x18c0, v77
	ds_write2_b32 v18, v12, v13 offset1:1
	v_lshlrev_b32_e32 v13, 16, v15
	v_lshlrev_b32_e32 v12, 16, v14
	v_pk_mul_f32 v[12:13], v[16:17], v[12:13] op_sel_hi:[0,1]
	v_and_b32_e32 v15, 0xffff0000, v15
	v_and_b32_e32 v14, 0xffff0000, v14
	v_pk_mul_f32 v[14:15], v[16:17], v[14:15] op_sel_hi:[0,1]
	s_nop 0
	v_cvt_pk_bf16_f32 v13, v13, v15
	v_cvt_pk_bf16_f32 v12, v12, v14
	v_add_u32_e32 v14, 0x18c8, v77
	ds_write2_b32 v14, v12, v13 offset1:1
	v_add_u32_e32 v12, 0x39c0, v77
	ds_write2_b32 v12, v8, v9 offset1:1
	v_add_u32_e32 v8, 0x39c8, v77
	ds_write2_b32 v8, v10, v11 offset1:1
	v_lshlrev_b32_e32 v9, 16, v5
	v_lshlrev_b32_e32 v8, 16, v4
	v_mov_b32_e32 v10, v17
	v_pk_mul_f32 v[8:9], v[10:11], v[8:9] op_sel_hi:[0,1]
	v_and_b32_e32 v5, 0xffff0000, v5
	v_and_b32_e32 v4, 0xffff0000, v4
	v_pk_mul_f32 v[4:5], v[10:11], v[4:5] op_sel_hi:[0,1]
	v_and_b32_sdwa v11, v9, v228 dst_sel:DWORD dst_unused:UNUSED_PAD src0_sel:WORD_1 src1_sel:DWORD
	s_nop 0
	v_add3_u32 v9, v9, v11, s96
	v_and_b32_sdwa v11, v5, v228 dst_sel:DWORD dst_unused:UNUSED_PAD src0_sel:WORD_1 src1_sel:DWORD
	s_nop 0
	v_add3_u32 v5, v5, v11, s96
	v_and_b32_e32 v5, 0xffff0000, v5
	v_or_b32_sdwa v5, v5, v9 dst_sel:DWORD dst_unused:UNUSED_PAD src0_sel:DWORD src1_sel:WORD_1
	v_cvt_pk_bf16_f32 v4, v8, v4
	v_add_u32_e32 v8, 0x1ce0, v77
	ds_write2_b32 v8, v4, v5 offset1:1
	v_lshlrev_b32_e32 v5, 16, v7
	v_lshlrev_b32_e32 v4, 16, v6
	v_pk_mul_f32 v[4:5], v[10:11], v[4:5] op_sel_hi:[0,1]
	v_and_b32_e32 v7, 0xffff0000, v7
	v_and_b32_e32 v6, 0xffff0000, v6
	v_pk_mul_f32 v[6:7], v[10:11], v[6:7] op_sel_hi:[0,1]
	s_nop 0
	v_cvt_pk_bf16_f32 v5, v5, v7
	v_cvt_pk_bf16_f32 v4, v4, v6
	v_add_u32_e32 v6, 0x1ce8, v77
	ds_write2_b32 v6, v4, v5 offset1:1
	v_add_u32_e32 v4, 0x3de0, v77
	ds_write2_b32 v4, v0, v1 offset1:1
	v_add_u32_e32 v0, 0x3de8, v77
	ds_write2_b32 v0, v2, v3 offset1:1
	s_waitcnt lgkmcnt(0)
	ds_read_u16 v0, v79 offset:8448
	ds_read_u16 v4, v79 offset:8580
	ds_read_u16 v32, v79 offset:8480
	ds_read_u16 v36, v79 offset:8612
	ds_read_u16 v48, v79 offset:8512
	ds_read_u16 v52, v79 offset:8644
	ds_read_u16 v57, v79 offset:8676
	ds_read_u16 v62, v79 offset:8544
	ds_read_u16 v1, v79 offset:8712
	ds_read_u16 v5, v79 offset:8844
	ds_read_u16 v33, v79 offset:8744
	ds_read_u16 v37, v79 offset:8876
	ds_read_u16 v49, v79 offset:8776
	ds_read_u16 v53, v79 offset:8908
	ds_read_u16 v63, v79 offset:8940
	ds_read_u16 v81, v79 offset:8808
	ds_read_u16 v2, v79 offset:8976
	ds_read_u16 v6, v79 offset:9108
	ds_read_u16 v34, v79 offset:9008
	ds_read_u16 v38, v79 offset:9140
	ds_read_u16 v50, v79 offset:9040
	ds_read_u16 v54, v79 offset:9172
	ds_read_u16 v83, v79 offset:9204
	ds_read_u16 v85, v79 offset:9072
	ds_read_u16 v3, v79 offset:9240
	ds_read_u16 v7, v79 offset:9372
	ds_read_u16 v35, v79 offset:9272
	ds_read_u16 v39, v79 offset:9404
	ds_read_u16 v51, v79 offset:9304
	ds_read_u16 v55, v79 offset:9436
	ds_read_u16 v87, v79 offset:9468
	ds_read_u16 v93, v79 offset:9336
	ds_read_u16 v8, v79 offset:132
	ds_read_u16 v9, v79
	ds_read_u16 v12, v79 offset:32
	ds_read_u16 v16, v79 offset:164
	ds_read_u16 v20, v79 offset:64
	ds_read_u16 v24, v79 offset:196
	ds_read_u16 v28, v79 offset:228
	ds_read_u16 v40, v79 offset:96
	ds_read_u16 v10, v79 offset:264
	ds_read_u16 v11, v79 offset:396
	ds_read_u16 v13, v79 offset:296
	ds_read_u16 v17, v79 offset:428
	ds_read_u16 v21, v79 offset:328
	ds_read_u16 v25, v79 offset:460
	ds_read_u16 v29, v79 offset:492
	ds_read_u16 v41, v79 offset:360
	ds_read_u16 v14, v79 offset:528
	ds_read_u16 v15, v79 offset:660
	ds_read_u16 v18, v79 offset:560
	ds_read_u16 v19, v79 offset:692
	ds_read_u16 v22, v79 offset:592
	ds_read_u16 v26, v79 offset:724
	ds_read_u16 v30, v79 offset:756
	ds_read_u16 v42, v79 offset:624
	ds_read_u16 v23, v79 offset:792
	ds_read_u16 v27, v79 offset:924
	ds_read_u16 v31, v79 offset:824
	ds_read_u16 v43, v79 offset:956
	ds_read_u16 v44, v79 offset:856
	ds_read_u16 v45, v79 offset:988
	ds_read_u16 v46, v79 offset:1020
	ds_read_u16 v47, v79 offset:888
	s_waitcnt lgkmcnt(14)
	v_perm_b32 v3, v7, v3, s0
	v_perm_b32 v2, v6, v2, s0
	v_perm_b32 v1, v5, v1, s0
	v_perm_b32 v0, v4, v0, s0
	v_perm_b32 v35, v39, v35, s0
	v_perm_b32 v34, v38, v34, s0
	v_perm_b32 v33, v37, v33, s0
	v_perm_b32 v32, v36, v32, s0
	v_perm_b32 v51, v55, v51, s0
	v_perm_b32 v50, v54, v50, s0
	v_perm_b32 v49, v53, v49, s0
	v_perm_b32 v48, v52, v48, s0
	v_perm_b32 v105, v87, v93, s0
	v_perm_b32 v104, v83, v85, s0
	v_perm_b32 v103, v63, v81, s0
	v_perm_b32 v102, v57, v62, s0
	s_waitcnt lgkmcnt(6)
	v_perm_b32 v7, v27, v23, s0
	v_perm_b32 v6, v15, v14, s0
	v_perm_b32 v5, v11, v10, s0
	v_perm_b32 v4, v8, v9, s0
	s_waitcnt lgkmcnt(4)
	v_perm_b32 v15, v43, v31, s0
	v_perm_b32 v14, v19, v18, s0
	v_perm_b32 v13, v17, v13, s0
	v_perm_b32 v12, v16, v12, s0
	s_waitcnt lgkmcnt(2)
	v_perm_b32 v23, v45, v44, s0
	v_perm_b32 v22, v26, v22, s0
	v_perm_b32 v21, v25, v21, s0
	v_perm_b32 v20, v24, v20, s0
	s_waitcnt lgkmcnt(0)
	v_perm_b32 v31, v46, v47, s0
	v_perm_b32 v30, v30, v42, s0
	v_perm_b32 v29, v29, v41, s0
	v_perm_b32 v28, v28, v40, s0
	v_mfma_f32_16x16x32_bf16 v[8:11], v[0:3], v[4:7], 0
	v_mfma_f32_16x16x32_bf16 v[16:19], v[0:3], v[12:15], 0
	v_mfma_f32_16x16x32_bf16 v[24:27], v[0:3], v[20:23], 0
	v_mfma_f32_16x16x32_bf16 v[0:3], v[0:3], v[28:31], 0
	v_mfma_f32_16x16x32_bf16 v[36:39], v[32:35], v[4:7], 0
	v_mfma_f32_16x16x32_bf16 v[40:43], v[32:35], v[12:15], 0
	v_mfma_f32_16x16x32_bf16 v[44:47], v[32:35], v[20:23], 0
	v_mfma_f32_16x16x32_bf16 v[32:35], v[32:35], v[28:31], 0
	v_mfma_f32_16x16x32_bf16 v[52:55], v[48:51], v[4:7], 0
	v_mfma_f32_16x16x32_bf16 v[58:61], v[48:51], v[12:15], 0
	v_mfma_f32_16x16x32_bf16 v[98:101], v[48:51], v[20:23], 0
	v_mfma_f32_16x16x32_bf16 v[48:51], v[48:51], v[28:31], 0
	v_mfma_f32_16x16x32_bf16 v[4:7], v[102:105], v[4:7], 0
	v_mfma_f32_16x16x32_bf16 v[12:15], v[102:105], v[12:15], 0
	v_mfma_f32_16x16x32_bf16 v[20:23], v[102:105], v[20:23], 0
	v_mfma_f32_16x16x32_bf16 v[28:31], v[102:105], v[28:31], 0
	ds_read_u16 v57, v79 offset:12672
	ds_read_u16 v62, v79 offset:12804
	ds_read_u16 v63, v79 offset:12704
	ds_read_u16 v81, v79 offset:12836
	ds_read_u16 v83, v79 offset:12736
	ds_read_u16 v85, v79 offset:12868
	ds_read_u16 v87, v79 offset:12900
	ds_read_u16 v93, v79 offset:12768
	ds_read_u16 v95, v79 offset:12936
	ds_read_u16 v97, v79 offset:13068
	ds_read_u16 v122, v79 offset:12968
	ds_read_u16 v123, v79 offset:13100
	ds_read_u16 v124, v79 offset:13000
	ds_read_u16 v125, v79 offset:13132
	ds_read_u16 v126, v79 offset:13164
	ds_read_u16 v127, v79 offset:13032
	ds_read_u16 v102, v79 offset:13200
	ds_read_u16 v103, v79 offset:13332
	ds_read_u16 v128, v79 offset:13232
	ds_read_u16 v129, v79 offset:13364
	ds_read_u16 v130, v79 offset:13264
	ds_read_u16 v131, v79 offset:13396
	ds_read_u16 v132, v79 offset:13428
	ds_read_u16 v133, v79 offset:13296
	ds_read_u16 v104, v79 offset:13464
	ds_read_u16 v105, v79 offset:13596
	ds_read_u16 v134, v79 offset:13496
	ds_read_u16 v135, v79 offset:13628
	ds_read_u16 v136, v79 offset:13528
	ds_read_u16 v137, v79 offset:13660
	ds_read_u16 v138, v79 offset:13692
	ds_read_u16 v139, v79 offset:13560
	ds_read_u16 v106, v79 offset:4224
	ds_read_u16 v110, v79 offset:4356
	ds_read_u16 v114, v79 offset:4256
	ds_read_u16 v115, v79 offset:4388
	ds_read_u16 v118, v79 offset:4288
	ds_read_u16 v119, v79 offset:4420
	ds_read_u16 v140, v79 offset:4452
	ds_read_u16 v141, v79 offset:4320
	ds_read_u16 v107, v79 offset:4488
	ds_read_u16 v111, v79 offset:4620
	ds_read_u16 v116, v79 offset:4520
	ds_read_u16 v117, v79 offset:4652
	ds_read_u16 v120, v79 offset:4552
	ds_read_u16 v121, v79 offset:4684
	ds_read_u16 v142, v79 offset:4716
	ds_read_u16 v143, v79 offset:4584
	ds_read_u16 v108, v79 offset:4752
	ds_read_u16 v112, v79 offset:4884
	ds_read_u16 v144, v79 offset:4784
	ds_read_u16 v145, v79 offset:4916
	ds_read_u16 v146, v79 offset:4816
	ds_read_u16 v147, v79 offset:4948
	ds_read_u16 v148, v79 offset:4980
	ds_read_u16 v149, v79 offset:4848
	ds_read_u16 v109, v79 offset:5016
	ds_read_u16 v113, v79 offset:5148
	ds_read_u16 v150, v79 offset:5048
	ds_read_u16 v151, v79 offset:5180
	ds_read_u16 v152, v79 offset:5080
	ds_read_u16 v153, v79 offset:5212
	ds_read_u16 v154, v79 offset:5244
	ds_read_u16 v155, v79 offset:5112
	s_waitcnt lgkmcnt(14)
	v_perm_b32 v105, v105, v104, s0
	v_perm_b32 v104, v103, v102, s0
	v_perm_b32 v103, v97, v95, s0
	v_perm_b32 v102, v62, v57, s0
	s_waitcnt lgkmcnt(6)
	v_perm_b32 v109, v113, v109, s0
	v_perm_b32 v108, v112, v108, s0
	v_perm_b32 v107, v111, v107, s0
	v_perm_b32 v106, v110, v106, s0
	s_waitcnt lgkmcnt(4)
	v_perm_b32 v113, v151, v150, s0
	v_perm_b32 v112, v145, v144, s0
	v_perm_b32 v111, v117, v116, s0
	v_perm_b32 v110, v115, v114, s0
	s_waitcnt lgkmcnt(2)
	v_perm_b32 v117, v153, v152, s0
	v_perm_b32 v116, v147, v146, s0
	v_perm_b32 v115, v121, v120, s0
	v_perm_b32 v114, v119, v118, s0
	s_waitcnt lgkmcnt(0)
	v_perm_b32 v121, v154, v155, s0
	v_perm_b32 v120, v148, v149, s0
	v_perm_b32 v119, v142, v143, s0
	v_perm_b32 v118, v140, v141, s0
	v_mfma_f32_16x16x32_bf16 v[8:11], v[102:105], v[106:109], v[8:11]
	v_mov_b32_e32 v95, v169
	v_mov_b32_e32 v97, v169
	v_mfma_f32_16x16x32_bf16 v[16:19], v[102:105], v[110:113], v[16:19]
	v_mfma_f32_16x16x32_bf16 v[24:27], v[102:105], v[114:117], v[24:27]
	v_mfma_f32_16x16x32_bf16 v[102:105], v[102:105], v[118:121], v[0:3]
	s_nop 2
	v_perm_b32 v3, v135, v134, s0
	v_perm_b32 v2, v129, v128, s0
	v_perm_b32 v1, v123, v122, s0
	v_perm_b32 v0, v81, v63, s0
	s_nop 1
	v_mfma_f32_16x16x32_bf16 v[36:39], v[0:3], v[106:109], v[36:39]
	v_mfma_f32_16x16x32_bf16 v[40:43], v[0:3], v[110:113], v[40:43]
	v_mfma_f32_16x16x32_bf16 v[44:47], v[0:3], v[114:117], v[44:47]
	v_mfma_f32_16x16x32_bf16 v[32:35], v[0:3], v[118:121], v[32:35]
	v_perm_b32 v3, v137, v136, s0
	v_perm_b32 v2, v131, v130, s0
	v_perm_b32 v1, v125, v124, s0
	v_perm_b32 v0, v85, v83, s0
	s_nop 1
	v_mfma_f32_16x16x32_bf16 v[52:55], v[0:3], v[106:109], v[52:55]
	v_mfma_f32_16x16x32_bf16 v[58:61], v[0:3], v[110:113], v[58:61]
	v_mfma_f32_16x16x32_bf16 v[98:101], v[0:3], v[114:117], v[98:101]
	v_mfma_f32_16x16x32_bf16 v[48:51], v[0:3], v[118:121], v[48:51]
	v_perm_b32 v3, v138, v139, s0
	v_perm_b32 v2, v132, v133, s0
	v_perm_b32 v1, v126, v127, s0
	v_perm_b32 v0, v87, v93, s0
	s_lshl_b32 s0, s24, 7
	s_or_b32 s0, s0, s49
	v_mfma_f32_16x16x32_bf16 v[106:109], v[0:3], v[106:109], v[4:7]
	s_ashr_i32 s1, s0, 31
	s_nop 1
	v_lshl_add_u64 v[4:5], s[0:1], 4, v[68:69]
	v_or_b32_e32 v4, s25, v4
	v_mfma_f32_16x16x32_bf16 v[12:15], v[0:3], v[110:113], v[12:15]
	v_lshlrev_b64 v[6:7], 13, v[4:5]
	v_lshl_add_u64 v[6:7], v[70:71], 0, v[6:7]
	v_mov_b32_e32 v93, v169
	v_mfma_f32_16x16x32_bf16 v[20:23], v[0:3], v[114:117], v[20:23]
	s_mov_b64 s[0:1], 0x60
	v_mfma_f32_16x16x32_bf16 v[0:3], v[0:3], v[118:121], v[28:31]
	s_nop 2
	v_cvt_pk_bf16_f32 v8, v8, v9
	v_cvt_pk_bf16_f32 v9, v10, v11
	v_lshl_add_u64 v[10:11], v[6:7], 0, v[92:93]
	global_store_dwordx2 v[10:11], v[8:9], off
	v_cvt_pk_bf16_f32 v8, v16, v17
	v_cvt_pk_bf16_f32 v9, v18, v19
	global_store_dwordx2 v[10:11], v[8:9], off offset:2048
	v_cvt_pk_bf16_f32 v8, v24, v25
	v_cvt_pk_bf16_f32 v9, v26, v27
	v_lshl_add_u64 v[16:17], v[6:7], 0, v[94:95]
	global_store_dwordx2 v[16:17], v[8:9], off
	v_cvt_pk_bf16_f32 v8, v102, v103
	v_cvt_pk_bf16_f32 v9, v104, v105
	v_lshl_add_u64 v[16:17], v[6:7], 0, v[96:97]
	global_store_dwordx2 v[16:17], v[8:9], off
	v_cvt_pk_bf16_f32 v16, v36, v37
	v_cvt_pk_bf16_f32 v17, v38, v39
	global_store_dwordx2 v[10:11], v[16:17], off offset:32
	v_cvt_pk_bf16_f32 v16, v40, v41
	v_cvt_pk_bf16_f32 v17, v42, v43
	global_store_dwordx2 v[10:11], v[16:17], off offset:2080
	v_cvt_pk_bf16_f32 v16, v44, v45
	v_lshl_add_u64 v[8:9], v[6:7], 0, 32
	v_cvt_pk_bf16_f32 v17, v46, v47
	v_lshl_add_u64 v[18:19], v[8:9], 0, v[94:95]
	global_store_dwordx2 v[18:19], v[16:17], off
	v_cvt_pk_bf16_f32 v16, v32, v33
	v_cvt_pk_bf16_f32 v17, v34, v35
	v_lshl_add_u64 v[8:9], v[8:9], 0, v[96:97]
	global_store_dwordx2 v[8:9], v[16:17], off
	v_cvt_pk_bf16_f32 v16, v52, v53
	v_cvt_pk_bf16_f32 v17, v54, v55
	global_store_dwordx2 v[10:11], v[16:17], off offset:64
	v_cvt_pk_bf16_f32 v16, v58, v59
	v_cvt_pk_bf16_f32 v17, v60, v61
	global_store_dwordx2 v[10:11], v[16:17], off offset:2112
	v_cvt_pk_bf16_f32 v16, v98, v99
	v_lshl_add_u64 v[8:9], v[6:7], 0, 64
	v_cvt_pk_bf16_f32 v17, v100, v101
	v_lshl_add_u64 v[18:19], v[8:9], 0, v[94:95]
	global_store_dwordx2 v[18:19], v[16:17], off
	v_cvt_pk_bf16_f32 v16, v48, v49
	v_cvt_pk_bf16_f32 v17, v50, v51
	v_lshl_add_u64 v[8:9], v[8:9], 0, v[96:97]
	global_store_dwordx2 v[8:9], v[16:17], off
	v_cvt_pk_bf16_f32 v8, v106, v107
	v_cvt_pk_bf16_f32 v9, v108, v109
	global_store_dwordx2 v[10:11], v[8:9], off offset:96
	v_cvt_pk_bf16_f32 v8, v12, v13
	v_cvt_pk_bf16_f32 v9, v14, v15
	global_store_dwordx2 v[10:11], v[8:9], off offset:2144
	v_cvt_pk_bf16_f32 v8, v20, v21
	v_lshl_add_u64 v[6:7], v[6:7], 0, s[0:1]
	v_cvt_pk_bf16_f32 v9, v22, v23
	v_lshl_add_u64 v[10:11], v[6:7], 0, v[94:95]
	global_store_dwordx2 v[10:11], v[8:9], off
	v_cvt_pk_bf16_f32 v0, v0, v1
	v_cvt_pk_bf16_f32 v1, v2, v3
	v_lshl_add_u64 v[2:3], v[6:7], 0, v[96:97]
	global_store_dwordx2 v[2:3], v[0:1], off
	s_and_saveexec_b64 s[0:1], vcc
	s_cbranch_execz .LBB0_601
	v_mul_f32_e32 v0, 0x3fb8aa3b, v56
	v_exp_f32_e32 v2, v0
	v_lshl_add_u64 v[0:1], v[4:5], 2, s[22:23]
	global_store_dword v[0:1], v2, off
	s_branch .LBB0_601

.LBB0_713:
	v_mov_b32_e32 v105, v179
	s_and_b64 vcc, exec, s[74:75]
	v_lshlrev_b32_e32 v104, 4, v105
	v_and_b32_e32 v104, 0x70, v104
	v_add_u32_e32 v104, s40, v104
	v_add_u32_e32 v104, 0x2848, v104
	s_cbranch_vccnz .LBB0_720
	v_ashrrev_i32_e32 v107, 3, v105
	s_movk_i32 vcc_lo, 0x88
	v_mad_u64_u32 v[236:237], s[38:39], v107, vcc_lo, v[104:105]
	v_add_u32_e32 v107, 64, v105
	v_ashrrev_i32_e32 v107, 3, v107
	s_waitcnt vmcnt(0)
	ds_write2_b32 v236, v60, v61 offset1:1
	ds_write2_b32 v236, v62, v63 offset0:2 offset1:3
	v_mad_u64_u32 v[236:237], s[38:39], v107, vcc_lo, v[104:105]
	v_add_u32_e32 v107, 0x80, v105
	v_ashrrev_i32_e32 v107, 3, v107
	ds_write2_b32 v236, v56, v57 offset1:1
	ds_write2_b32 v236, v58, v59 offset0:2 offset1:3
	v_mad_u64_u32 v[236:237], s[38:39], v107, vcc_lo, v[104:105]
	v_add_u32_e32 v107, 0xc0, v105
	v_ashrrev_i32_e32 v107, 3, v107
	ds_write2_b32 v236, v48, v49 offset1:1
	ds_write2_b32 v236, v50, v51 offset0:2 offset1:3
	v_mad_u64_u32 v[236:237], s[38:39], v107, vcc_lo, v[104:105]
	ds_write2_b32 v236, v40, v41 offset1:1
	ds_write2_b32 v236, v42, v43 offset0:2 offset1:3
	s_and_b64 vcc, exec, s[76:77]
	s_cbranch_vccz .LBB0_721

.LBB0_721:
	v_add_u32_e32 v107, 0x100, v105
	v_ashrrev_i32_e32 v107, 3, v107
	s_movk_i32 vcc_lo, 0x88
	v_mad_u64_u32 v[236:237], s[38:39], v107, vcc_lo, v[104:105]
	v_add_u32_e32 v107, 0x140, v105
	v_ashrrev_i32_e32 v107, 3, v107
	s_waitcnt vmcnt(0)
	ds_write2_b32 v236, v36, v37 offset1:1
	ds_write2_b32 v236, v38, v39 offset0:2 offset1:3
	v_mad_u64_u32 v[236:237], s[38:39], v107, vcc_lo, v[104:105]
	v_add_u32_e32 v107, 0x180, v105
	v_ashrrev_i32_e32 v107, 3, v107
	ds_write2_b32 v236, v28, v29 offset1:1
	ds_write2_b32 v236, v30, v31 offset0:2 offset1:3
	v_mad_u64_u32 v[236:237], s[38:39], v107, vcc_lo, v[104:105]
	v_add_u32_e32 v107, 0x1c0, v105
	v_ashrrev_i32_e32 v107, 3, v107
	ds_write2_b32 v236, v20, v21 offset1:1
	ds_write2_b32 v236, v22, v23 offset0:2 offset1:3
	v_mad_u64_u32 v[236:237], s[38:39], v107, vcc_lo, v[104:105]
	ds_write2_b32 v236, v12, v13 offset1:1
	ds_write2_b32 v236, v14, v15 offset0:2 offset1:3
	s_and_b64 vcc, exec, s[22:23]
	s_cbranch_vccnz .LBB0_716

.LBB0_814:
	v_pk_mul_f32 v[102:103], v[102:103], v[104:105] op_sel_hi:[1,0]
	v_pk_mul_f32 v[100:101], v[100:101], v[104:105] op_sel_hi:[1,0]
	v_pk_mul_f32 v[98:99], v[98:99], v[104:105] op_sel_hi:[1,0]
	v_pk_mul_f32 v[96:97], v[96:97], v[104:105] op_sel_hi:[1,0]
	v_pk_mul_f32 v[94:95], v[94:95], v[104:105] op_sel_hi:[1,0]
	v_pk_mul_f32 v[92:93], v[92:93], v[104:105] op_sel_hi:[1,0]
	v_pk_mul_f32 v[90:91], v[90:91], v[104:105] op_sel_hi:[1,0]
	v_pk_mul_f32 v[88:89], v[88:89], v[104:105] op_sel_hi:[1,0]
	v_lshrrev_b32_e32 v225, 2, v105
	v_and_b32_e32 v243, 3, v105
	v_mul_u32_u24_e32 v225, 0x88, v225
	s_and_b64 vcc, exec, s[74:75]
	v_lshl_add_u32 v204, v243, 3, v225
	v_add_u32_e32 v204, s40, v204
	v_add_u32_e32 v204, 0x2848, v204
	s_cbranch_vccnz .LBB0_816
	v_cvt_pk_bf16_f32 v104, v84, v85
	v_cvt_pk_bf16_f32 v105, v86, v87
	v_cvt_pk_bf16_f32 v106, v80, v81
	v_cvt_pk_bf16_f32 v107, v82, v83
	ds_read_b64_tr_b16 v[244:245], v204
	ds_read_b64_tr_b16 v[246:247], v204 offset:2176
	ds_read_b64_tr_b16 v[248:249], v204 offset:32
	ds_read_b64_tr_b16 v[250:251], v204 offset:2208
	ds_read_b64_tr_b16 v[234:235], v204 offset:64
	ds_read_b64_tr_b16 v[236:237], v204 offset:2240
	s_waitcnt lgkmcnt(4)
	v_mfma_f32_16x16x32_bf16 v[100:103], v[244:247], v[104:107], v[100:103]
	ds_read_b64_tr_b16 v[244:245], v204 offset:96
	ds_read_b64_tr_b16 v[246:247], v204 offset:2272
	s_waitcnt lgkmcnt(4)
	v_mfma_f32_16x16x32_bf16 v[96:99], v[248:251], v[104:107], v[96:99]
	s_waitcnt lgkmcnt(2)
	v_mfma_f32_16x16x32_bf16 v[92:95], v[234:237], v[104:107], v[92:95]
	s_waitcnt lgkmcnt(0)
	v_mfma_f32_16x16x32_bf16 v[88:91], v[244:247], v[104:107], v[88:91]
.LBB0_816:
	s_and_b64 vcc, exec, s[76:77]
	s_cbranch_vccnz .LBB0_818
	v_cvt_pk_bf16_f32 v104, v76, v77
	v_cvt_pk_bf16_f32 v105, v78, v79
	v_cvt_pk_bf16_f32 v106, v64, v65
	v_cvt_pk_bf16_f32 v107, v66, v67
	ds_read_b64_tr_b16 v[244:245], v204 offset:4352
	ds_read_b64_tr_b16 v[246:247], v204 offset:6528
	ds_read_b64_tr_b16 v[248:249], v204 offset:4384
	ds_read_b64_tr_b16 v[250:251], v204 offset:6560
	ds_read_b64_tr_b16 v[234:235], v204 offset:4416
	ds_read_b64_tr_b16 v[236:237], v204 offset:6592
	s_waitcnt lgkmcnt(4)
	v_mfma_f32_16x16x32_bf16 v[100:103], v[244:247], v[104:107], v[100:103]
	ds_read_b64_tr_b16 v[244:245], v204 offset:4448
	ds_read_b64_tr_b16 v[246:247], v204 offset:6624
	s_waitcnt lgkmcnt(4)
	v_mfma_f32_16x16x32_bf16 v[96:99], v[248:251], v[104:107], v[96:99]
	s_waitcnt lgkmcnt(2)
	v_mfma_f32_16x16x32_bf16 v[92:95], v[234:237], v[104:107], v[92:95]
	s_waitcnt lgkmcnt(0)
	v_mfma_f32_16x16x32_bf16 v[88:91], v[244:247], v[104:107], v[88:91]
